# epilogue scale-load hoist plus non-temporal hints on read-once streams (x in P3, H1 in P9, H2 and output in P12, ACT in the quantise pass, gate reads in the branch epilogue)
# speedup vs baseline: 1.0027x; 1.0007x over previous
.LBB0_326:
	s_or_b64 exec, exec, s[0:1]
	s_mul_hi_i32 s43, s38, 0x2b00
	s_mul_i32 s42, s38, 0x2b00
	v_lshl_add_u64 v[94:95], s[42:43], 1, v[90:91]
	v_add_co_u32_e32 v2, vcc, 0x1000, v94
	global_load_dwordx4 v[86:89], v[94:95], off nt
	global_load_dwordx4 v[82:85], v[94:95], off offset:1024 nt
	global_load_dwordx4 v[78:81], v[94:95], off offset:2048 nt
	global_load_dwordx4 v[74:77], v[94:95], off offset:3072 nt
	v_addc_co_u32_e32 v3, vcc, 0, v95, vcc
	global_load_dwordx4 v[70:73], v[2:3], off nt
	global_load_dwordx4 v[66:69], v[2:3], off offset:1024 nt
	global_load_dwordx4 v[62:65], v[2:3], off offset:2048 nt
	global_load_dwordx4 v[58:61], v[2:3], off offset:3072 nt
	v_add_co_u32_e32 v2, vcc, 0x2000, v94
	v_mov_b32_e32 v4, 0
	s_nop 0
	v_addc_co_u32_e32 v3, vcc, 0, v95, vcc
	global_load_dwordx4 v[54:57], v[2:3], off nt
	global_load_dwordx4 v[50:53], v[2:3], off offset:1024 nt
	global_load_dwordx4 v[46:49], v[2:3], off offset:2048 nt
	global_load_dwordx4 v[42:45], v[2:3], off offset:3072 nt
	v_add_co_u32_e32 v2, vcc, 0x3000, v94
	v_mov_b32_e32 v5, 0
	s_nop 0
	v_addc_co_u32_e32 v3, vcc, 0, v95, vcc
	global_load_dwordx4 v[38:41], v[2:3], off nt
	global_load_dwordx4 v[34:37], v[2:3], off offset:1024 nt
	global_load_dwordx4 v[30:33], v[2:3], off offset:2048 nt
	global_load_dwordx4 v[26:29], v[2:3], off offset:3072 nt
	v_add_co_u32_e32 v2, vcc, 0x4000, v94
	s_nop 1
	v_addc_co_u32_e32 v3, vcc, 0, v95, vcc
	global_load_dwordx4 v[22:25], v[2:3], off nt
	global_load_dwordx4 v[18:21], v[2:3], off offset:1024 nt
	global_load_dwordx4 v[14:17], v[2:3], off offset:2048 nt
	global_load_dwordx4 v[10:13], v[2:3], off offset:3072 nt
	v_add_co_u32_e32 v2, vcc, 0x5000, v94
	s_nop 1
	v_addc_co_u32_e32 v3, vcc, 0, v95, vcc
	global_load_dwordx4 v[6:9], v[2:3], off nt
	v_mov_b32_e32 v2, 0
	v_mov_b32_e32 v3, 0
	s_and_saveexec_b64 s[0:1], s[6:7]
	s_cbranch_execz .LBB0_328
	v_add_co_u32_e32 v2, vcc, 0x5000, v94
	s_nop 1
	v_addc_co_u32_e32 v3, vcc, 0, v95, vcc
	global_load_dwordx4 v[2:5], v[2:3], off offset:1024 nt

.LBB0_481:
	s_or_b64 exec, exec, s[0:1]
	s_ashr_i32 s39, s38, 31
	s_lshl_b64 s[0:1], s[38:39], 13
	v_lshl_add_u64 v[8:9], v[68:69], 0, s[0:1]
	global_load_dwordx2 v[10:11], v[8:9], off
	global_load_dwordx2 v[12:13], v[8:9], off offset:512
	global_load_dwordx2 v[14:15], v[8:9], off offset:1024
	global_load_dwordx2 v[16:17], v[8:9], off offset:1536
	global_load_dwordx2 v[18:19], v[8:9], off offset:2048
	global_load_dwordx2 v[20:21], v[8:9], off offset:2560
	global_load_dwordx2 v[22:23], v[8:9], off offset:3072
	global_load_dwordx2 v[24:25], v[8:9], off offset:3584
	s_lshl_b64 s[8:9], s[38:39], 14
	v_add_co_u32_e32 v8, vcc, 0x1000, v8
	v_lshl_add_u64 v[6:7], v[70:71], 0, s[8:9]
	s_nop 0
	v_addc_co_u32_e32 v9, vcc, 0, v9, vcc
	global_load_dwordx4 v[2:5], v[6:7], off nt
	global_load_dwordx2 v[26:27], v[8:9], off
	global_load_dwordx2 v[28:29], v[8:9], off offset:512
	global_load_dwordx2 v[30:31], v[8:9], off offset:1024
	global_load_dwordx2 v[32:33], v[8:9], off offset:1536
	global_load_dwordx2 v[34:35], v[8:9], off offset:2048
	global_load_dwordx2 v[36:37], v[8:9], off offset:2560
	global_load_dwordx2 v[38:39], v[8:9], off offset:3072
	s_nop 0
	global_load_dwordx2 v[8:9], v[8:9], off offset:3584
	s_nop 0
	global_load_dwordx4 v[62:65], v[6:7], off offset:1024 nt
	global_load_dwordx4 v[54:57], v[6:7], off offset:2048 nt
	global_load_dwordx4 v[50:53], v[6:7], off offset:3072 nt
	s_waitcnt vmcnt(19)
	v_and_b32_e32 v89, 0xffff0000, v10
	v_and_b32_e32 v91, 0xffff0000, v11
	s_waitcnt vmcnt(18)
	v_and_b32_e32 v95, 0xffff0000, v12
	v_and_b32_e32 v97, 0xffff0000, v13
	v_lshlrev_b32_e32 v88, 16, v10
	v_lshlrev_b32_e32 v90, 16, v11
	v_lshlrev_b32_e32 v94, 16, v12
	v_lshlrev_b32_e32 v96, 16, v13
	s_waitcnt vmcnt(17)
	v_and_b32_e32 v99, 0xffff0000, v14
	v_and_b32_e32 v101, 0xffff0000, v15
	v_mul_f32_e32 v10, v89, v89
	v_mul_f32_e32 v11, v91, v91
	v_mul_f32_e32 v12, v95, v95
	v_mul_f32_e32 v13, v97, v97
	v_lshlrev_b32_e32 v98, 16, v14
	v_lshlrev_b32_e32 v100, 16, v15
	s_waitcnt vmcnt(16)
	v_and_b32_e32 v103, 0xffff0000, v16
	v_and_b32_e32 v105, 0xffff0000, v17
	v_mul_f32_e32 v14, v99, v99
	v_mul_f32_e32 v15, v101, v101
	v_fmac_f32_e32 v10, v88, v88
	v_fmac_f32_e32 v11, v90, v90
	v_fmac_f32_e32 v12, v94, v94
	v_fmac_f32_e32 v13, v96, v96
	v_lshlrev_b32_e32 v102, 16, v16
	v_lshlrev_b32_e32 v104, 16, v17
	s_waitcnt vmcnt(15)
	v_and_b32_e32 v107, 0xffff0000, v18
	v_and_b32_e32 v109, 0xffff0000, v19
	v_mul_f32_e32 v16, v103, v103
	v_mul_f32_e32 v17, v105, v105
	v_fmac_f32_e32 v14, v98, v98
	v_fmac_f32_e32 v15, v100, v100
	v_add_f32_e32 v10, v10, v11
	v_add_f32_e32 v11, v12, v13
	v_lshlrev_b32_e32 v106, 16, v18
	v_lshlrev_b32_e32 v108, 16, v19
	s_waitcnt vmcnt(14)
	v_and_b32_e32 v111, 0xffff0000, v20
	v_and_b32_e32 v113, 0xffff0000, v21
	v_mul_f32_e32 v18, v107, v107
	v_mul_f32_e32 v19, v109, v109
	v_fmac_f32_e32 v16, v102, v102
	v_fmac_f32_e32 v17, v104, v104
	v_add_f32_e32 v12, v14, v15
	v_add_f32_e32 v10, v10, v11
	v_lshlrev_b32_e32 v110, 16, v20
	v_lshlrev_b32_e32 v112, 16, v21
	s_waitcnt vmcnt(13)
	v_and_b32_e32 v115, 0xffff0000, v22
	v_and_b32_e32 v117, 0xffff0000, v23
	v_mul_f32_e32 v20, v111, v111
	v_mul_f32_e32 v21, v113, v113
	v_fmac_f32_e32 v18, v106, v106
	v_fmac_f32_e32 v19, v108, v108
	v_add_f32_e32 v13, v16, v17
	v_add_f32_e32 v10, v10, v12
	v_lshlrev_b32_e32 v114, 16, v22
	v_lshlrev_b32_e32 v116, 16, v23
	v_mul_f32_e32 v22, v115, v115
	v_fmac_f32_e32 v20, v110, v110
	v_fmac_f32_e32 v21, v112, v112
	v_add_f32_e32 v14, v18, v19
	v_add_f32_e32 v10, v10, v13
	v_mul_f32_e32 v11, v117, v117
	v_fmac_f32_e32 v22, v114, v114
	v_add_f32_e32 v15, v20, v21
	v_add_f32_e32 v10, v10, v14
	v_fmac_f32_e32 v11, v116, v116
	v_add_f32_e32 v10, v10, v15
	v_add_f32_e32 v11, v22, v11
	s_waitcnt vmcnt(12)
	v_and_b32_e32 v119, 0xffff0000, v24
	v_and_b32_e32 v121, 0xffff0000, v25
	v_add_f32_e32 v10, v10, v11
	v_lshlrev_b32_e32 v118, 16, v24
	v_lshlrev_b32_e32 v120, 16, v25
	v_mul_f32_e32 v11, v119, v119
	v_mul_f32_e32 v12, v121, v121
	v_fmac_f32_e32 v11, v118, v118
	v_fmac_f32_e32 v12, v120, v120
	v_add_f32_e32 v11, v11, v12
	s_waitcnt vmcnt(10)
	v_and_b32_e32 v123, 0xffff0000, v26
	v_and_b32_e32 v125, 0xffff0000, v27
	v_add_f32_e32 v10, v10, v11
	v_lshlrev_b32_e32 v122, 16, v26
	v_lshlrev_b32_e32 v124, 16, v27
	v_mul_f32_e32 v11, v123, v123
	v_mul_f32_e32 v12, v125, v125
	v_fmac_f32_e32 v11, v122, v122
	v_fmac_f32_e32 v12, v124, v124
	v_add_f32_e32 v11, v11, v12
	s_waitcnt vmcnt(9)
	v_and_b32_e32 v127, 0xffff0000, v28
	v_and_b32_e32 v129, 0xffff0000, v29
	v_add_f32_e32 v10, v10, v11
	v_lshlrev_b32_e32 v126, 16, v28
	v_lshlrev_b32_e32 v128, 16, v29
	v_mul_f32_e32 v11, v127, v127
	v_mul_f32_e32 v12, v129, v129
	v_fmac_f32_e32 v11, v126, v126
	v_fmac_f32_e32 v12, v128, v128
	v_add_f32_e32 v11, v11, v12
	s_waitcnt vmcnt(8)
	v_and_b32_e32 v131, 0xffff0000, v30
	v_and_b32_e32 v133, 0xffff0000, v31
	v_add_f32_e32 v10, v10, v11
	v_lshlrev_b32_e32 v130, 16, v30
	v_lshlrev_b32_e32 v132, 16, v31
	v_mul_f32_e32 v11, v131, v131
	v_mul_f32_e32 v12, v133, v133
	v_fmac_f32_e32 v11, v130, v130
	v_fmac_f32_e32 v12, v132, v132
	v_add_f32_e32 v11, v11, v12
	s_waitcnt vmcnt(7)
	v_and_b32_e32 v135, 0xffff0000, v32
	v_and_b32_e32 v137, 0xffff0000, v33
	v_add_f32_e32 v10, v10, v11
	v_lshlrev_b32_e32 v134, 16, v32
	v_lshlrev_b32_e32 v136, 16, v33
	v_mul_f32_e32 v11, v135, v135
	v_mul_f32_e32 v12, v137, v137
	v_fmac_f32_e32 v11, v134, v134
	v_fmac_f32_e32 v12, v136, v136
	v_add_f32_e32 v11, v11, v12
	s_waitcnt vmcnt(6)
	v_and_b32_e32 v139, 0xffff0000, v34
	v_and_b32_e32 v141, 0xffff0000, v35
	v_add_f32_e32 v10, v10, v11
	v_lshlrev_b32_e32 v138, 16, v34
	v_lshlrev_b32_e32 v140, 16, v35
	v_mul_f32_e32 v11, v139, v139
	v_mul_f32_e32 v12, v141, v141
	v_fmac_f32_e32 v11, v138, v138
	v_fmac_f32_e32 v12, v140, v140
	v_add_f32_e32 v11, v11, v12
	s_waitcnt vmcnt(5)
	v_and_b32_e32 v143, 0xffff0000, v36
	v_and_b32_e32 v145, 0xffff0000, v37
	v_add_f32_e32 v10, v10, v11
	v_lshlrev_b32_e32 v142, 16, v36
	v_lshlrev_b32_e32 v144, 16, v37
	v_mul_f32_e32 v11, v143, v143
	v_mul_f32_e32 v12, v145, v145
	v_fmac_f32_e32 v11, v142, v142
	v_fmac_f32_e32 v12, v144, v144
	v_add_f32_e32 v11, v11, v12
	s_waitcnt vmcnt(4)
	v_and_b32_e32 v148, 0xffff0000, v38
	v_and_b32_e32 v150, 0xffff0000, v39
	v_add_f32_e32 v10, v10, v11
	v_lshlrev_b32_e32 v147, 16, v38
	v_lshlrev_b32_e32 v149, 16, v39
	v_mul_f32_e32 v11, v148, v148
	v_mul_f32_e32 v12, v150, v150
	s_waitcnt vmcnt(3)
	v_and_b32_e32 v152, 0xffff0000, v8
	v_and_b32_e32 v154, 0xffff0000, v9
	v_fmac_f32_e32 v11, v147, v147
	v_fmac_f32_e32 v12, v149, v149
	v_lshlrev_b32_e32 v151, 16, v8
	v_lshlrev_b32_e32 v153, 16, v9
	v_mul_f32_e32 v8, v152, v152
	v_mul_f32_e32 v9, v154, v154
	v_add_f32_e32 v11, v11, v12
	v_fmac_f32_e32 v8, v151, v151
	v_fmac_f32_e32 v9, v153, v153
	v_add_f32_e32 v10, v10, v11
	v_add_f32_e32 v8, v8, v9
	v_add_f32_e32 v8, v10, v8
	ds_bpermute_b32 v9, v1, v8
	s_waitcnt lgkmcnt(0)
	v_add_f32_e32 v8, v8, v9
	ds_bpermute_b32 v9, v76, v8
	s_waitcnt lgkmcnt(0)
	v_add_f32_e32 v10, v8, v9
	ds_bpermute_b32 v11, v77, v10
	v_add_co_u32_e32 v8, vcc, s47, v6
	s_waitcnt lgkmcnt(0)
	v_add_f32_e32 v10, v10, v11
	ds_bpermute_b32 v11, v78, v10
	v_addc_co_u32_e32 v9, vcc, 0, v7, vcc
	v_add_co_u32_e32 v58, vcc, s48, v6
	s_waitcnt lgkmcnt(0)
	v_add_f32_e32 v10, v10, v11
	ds_bpermute_b32 v11, v79, v10
	v_addc_co_u32_e32 v59, vcc, 0, v7, vcc
	v_add_co_u32_e32 v6, vcc, s49, v6
	s_waitcnt lgkmcnt(0)
	v_add_f32_e32 v10, v10, v11
	ds_bpermute_b32 v11, v80, v10
	global_load_dwordx4 v[46:49], v[8:9], off offset:1024 nt
	global_load_dwordx4 v[38:41], v[8:9], off offset:2048 nt
	global_load_dwordx4 v[34:37], v[58:59], off nt
	global_load_dwordx4 v[30:33], v[58:59], off offset:1024 nt
	global_load_dwordx4 v[26:29], v[58:59], off offset:2048 nt
	global_load_dwordx4 v[22:25], v[58:59], off offset:3072 nt
	v_addc_co_u32_e32 v7, vcc, 0, v7, vcc
	global_load_dwordx4 v[42:45], v[8:9], off offset:3072 nt
	global_load_dwordx4 v[18:21], v[6:7], off nt
	s_waitcnt lgkmcnt(0)
	v_add_f32_e32 v8, v10, v11
	v_fmamk_f32 v8, v8, 0x39800000, v66
	v_mul_f32_e32 v9, 0x4f800000, v8
	v_cmp_gt_f32_e32 vcc, s50, v8
	s_nop 1
	v_cndmask_b32_e32 v84, v8, v9, vcc
	global_load_dwordx4 v[14:17], v[6:7], off offset:1024 nt
	global_load_dwordx4 v[10:13], v[6:7], off offset:2048 nt
	s_nop 0
	global_load_dwordx4 v[58:61], v[58:59], off offset:-4096 nt
	s_nop 0
	global_load_dwordx4 v[6:9], v[6:7], off offset:3072 nt
	v_sqrt_f32_e32 v85, v84
	s_nop 0
	v_add_u32_e32 v86, -1, v85
	v_fma_f32 v87, -v86, v85, v84
	v_cmp_ge_f32_e64 s[8:9], 0, v87
	v_add_u32_e32 v87, 1, v85
	s_nop 0
	v_cndmask_b32_e64 v86, v85, v86, s[8:9]
	v_fma_f32 v85, -v87, v85, v84
	v_cmp_lt_f32_e64 s[8:9], 0, v85
	s_nop 1
	v_cndmask_b32_e64 v85, v86, v87, s[8:9]
	v_mul_f32_e32 v86, 0x37800000, v85
	v_cndmask_b32_e32 v85, v85, v86, vcc
	v_cmp_class_f32_e32 vcc, v84, v82
	s_nop 1
	v_cndmask_b32_e32 v92, v85, v84, vcc
	v_div_scale_f32 v84, s[8:9], v92, v92, 0.5
	v_rcp_f32_e32 v93, v84
	s_nop 0
	v_fma_f32 v85, -v84, v93, 1.0
	v_fmac_f32_e32 v93, v85, v93
	v_div_scale_f32 v85, vcc, 0.5, v92, 0.5
	v_mul_f32_e32 v155, v85, v93
	v_fma_f32 v86, -v84, v155, v85
	v_fmac_f32_e32 v155, v86, v93
	v_fma_f32 v156, -v84, v155, v85
	ds_read_b128 v[84:87], v81
	v_div_fmas_f32 v93, v156, v93, v155
	v_div_fixup_f32 v155, v93, v92, 0.5
	v_mul_f32_e32 v88, v155, v88
	v_lshl_add_u64 v[92:93], v[72:73], 0, s[0:1]
	s_waitcnt lgkmcnt(0)
	v_fma_f32 v2, v84, v88, v2
	v_mul_f32_e32 v84, v155, v89
	v_fma_f32 v3, v85, v84, v3
	v_mul_f32_e32 v84, v155, v90
	v_fma_f32 v4, v86, v84, v4
	v_mul_f32_e32 v84, v155, v91
	v_fmac_f32_e32 v5, v87, v84
	v_cvt_pk_bf16_f32 v88, v2, v3
	v_cvt_pk_bf16_f32 v89, v4, v5
	ds_read_b128 v[84:87], v81 offset:1024
	global_store_dwordx2 v[92:93], v[88:89], off
	v_mul_f32_e32 v88, v155, v94
	s_waitcnt vmcnt(15) lgkmcnt(0)
	v_fma_f32 v84, v84, v88, v62
	v_mul_f32_e32 v62, v155, v95
	v_fma_f32 v63, v85, v62, v63
	v_mul_f32_e32 v62, v155, v96
	v_fma_f32 v62, v86, v62, v64
	v_mul_f32_e32 v64, v155, v97
	v_fmac_f32_e32 v65, v87, v64
	v_cvt_pk_bf16_f32 v90, v84, v63
	v_cvt_pk_bf16_f32 v91, v62, v65
	ds_read_b128 v[86:89], v81 offset:2048
	v_mul_f32_e32 v64, v155, v98
	global_store_dwordx2 v[92:93], v[90:91], off offset:512
	s_waitcnt vmcnt(15) lgkmcnt(0)
	v_fma_f32 v54, v64, v86, v54
	v_mul_f32_e32 v64, v155, v99
	v_fma_f32 v55, v64, v87, v55
	v_mul_f32_e32 v64, v155, v100
	v_fma_f32 v56, v64, v88, v56
	v_mul_f32_e32 v64, v155, v101
	v_fmac_f32_e32 v57, v64, v89
	v_cvt_pk_bf16_f32 v90, v54, v55
	v_cvt_pk_bf16_f32 v91, v56, v57
	ds_read_b128 v[86:89], v81 offset:3072
	v_mul_f32_e32 v64, v155, v102
	global_store_dwordx2 v[92:93], v[90:91], off offset:1024
	s_waitcnt vmcnt(15) lgkmcnt(0)
	v_fma_f32 v64, v64, v86, v50
	v_mul_f32_e32 v50, v155, v103
	v_fma_f32 v85, v50, v87, v51
	v_mul_f32_e32 v50, v155, v104
	v_fma_f32 v86, v50, v88, v52
	v_mul_f32_e32 v50, v155, v105
	v_fmac_f32_e32 v53, v50, v89
	v_cvt_pk_bf16_f32 v50, v64, v85
	v_cvt_pk_bf16_f32 v51, v86, v53
	global_store_dwordx2 v[92:93], v[50:51], off offset:1536
	ds_read_b128 v[88:91], v81 offset:4096
	v_mul_f32_e32 v50, v155, v106
	v_mul_f32_e32 v51, v155, v107
	v_mul_f32_e32 v52, v155, v108
	s_waitcnt vmcnt(5) lgkmcnt(0)
	v_fma_f32 v50, v50, v88, v58
	v_mul_f32_e32 v58, v155, v109
	v_fma_f32 v51, v51, v89, v59
	v_fma_f32 v52, v52, v90, v60
	v_fmac_f32_e32 v61, v58, v91
	v_cvt_pk_bf16_f32 v58, v50, v51
	v_cvt_pk_bf16_f32 v59, v52, v61
	ds_read_b128 v[88:91], v81 offset:5120
	global_store_dwordx2 v[92:93], v[58:59], off offset:2048
	v_mul_f32_e32 v58, v155, v110
	s_waitcnt lgkmcnt(0)
	v_fma_f32 v58, v58, v88, v46
	v_mul_f32_e32 v46, v155, v111
	v_fma_f32 v47, v46, v89, v47
	v_mul_f32_e32 v46, v155, v112
	v_fma_f32 v46, v46, v90, v48
	v_mul_f32_e32 v48, v155, v113
	v_fmac_f32_e32 v49, v48, v91
	v_cvt_pk_bf16_f32 v94, v58, v47
	v_cvt_pk_bf16_f32 v95, v46, v49
	ds_read_b128 v[88:91], v81 offset:6144
	v_mul_f32_e32 v48, v155, v114
	global_store_dwordx2 v[92:93], v[94:95], off offset:2560
	s_waitcnt lgkmcnt(0)
	v_fma_f32 v38, v48, v88, v38
	v_mul_f32_e32 v48, v155, v115
	v_fma_f32 v39, v48, v89, v39
	v_mul_f32_e32 v48, v155, v116
	v_fma_f32 v40, v48, v90, v40
	v_mul_f32_e32 v48, v155, v117
	v_fmac_f32_e32 v41, v48, v91
	v_cvt_pk_bf16_f32 v94, v38, v39
	v_cvt_pk_bf16_f32 v95, v40, v41
	ds_read_b128 v[88:91], v81 offset:7168
	v_mul_f32_e32 v48, v155, v118
	global_store_dwordx2 v[92:93], v[94:95], off offset:3072
	s_waitcnt lgkmcnt(0)
	v_fma_f32 v42, v48, v88, v42
	v_mul_f32_e32 v48, v155, v119
	v_fma_f32 v43, v48, v89, v43
	v_mul_f32_e32 v48, v155, v120
	v_fma_f32 v44, v48, v90, v44
	v_mul_f32_e32 v48, v155, v121
	v_fmac_f32_e32 v45, v48, v91
	v_cvt_pk_bf16_f32 v88, v42, v43
	v_cvt_pk_bf16_f32 v89, v44, v45
	global_store_dwordx2 v[92:93], v[88:89], off offset:3584
	ds_read_b128 v[88:91], v81 offset:8192
	v_mul_f32_e32 v48, v155, v122
	v_mul_f32_e32 v59, v155, v123
	v_mul_f32_e32 v60, v155, v124
	v_add_co_u32_e32 v92, vcc, s47, v92
	s_waitcnt lgkmcnt(0)
	v_fma_f32 v34, v48, v88, v34
	v_mul_f32_e32 v48, v155, v125
	v_fma_f32 v35, v59, v89, v35
	v_fma_f32 v36, v60, v90, v36
	v_fmac_f32_e32 v37, v48, v91
	v_cvt_pk_bf16_f32 v94, v34, v35
	v_cvt_pk_bf16_f32 v95, v36, v37
	ds_read_b128 v[88:91], v81 offset:9216
	v_mul_f32_e32 v48, v155, v126
	v_addc_co_u32_e32 v93, vcc, 0, v93, vcc
	global_store_dwordx2 v[92:93], v[94:95], off
	s_waitcnt lgkmcnt(0)
	v_fma_f32 v48, v48, v88, v30
	v_mul_f32_e32 v30, v155, v127
	v_fma_f32 v31, v30, v89, v31
	v_mul_f32_e32 v30, v155, v128
	v_fma_f32 v30, v30, v90, v32
	v_mul_f32_e32 v32, v155, v129
	v_fmac_f32_e32 v33, v32, v91
	v_cvt_pk_bf16_f32 v94, v48, v31
	v_cvt_pk_bf16_f32 v95, v30, v33
	ds_read_b128 v[88:91], v81 offset:10240
	v_mul_f32_e32 v32, v155, v130
	global_store_dwordx2 v[92:93], v[94:95], off offset:512
	s_waitcnt lgkmcnt(0)
	v_fma_f32 v26, v32, v88, v26
	v_mul_f32_e32 v32, v155, v131
	v_fma_f32 v27, v32, v89, v27
	v_mul_f32_e32 v32, v155, v132
	v_fma_f32 v28, v32, v90, v28
	v_mul_f32_e32 v32, v155, v133
	v_fmac_f32_e32 v29, v32, v91
	v_cvt_pk_bf16_f32 v94, v26, v27
	v_cvt_pk_bf16_f32 v95, v28, v29
	ds_read_b128 v[88:91], v81 offset:11264
	v_mul_f32_e32 v32, v155, v134
	global_store_dwordx2 v[92:93], v[94:95], off offset:1024
	s_waitcnt lgkmcnt(0)
	v_fma_f32 v22, v32, v88, v22
	v_mul_f32_e32 v32, v155, v135
	v_fma_f32 v23, v32, v89, v23
	v_mul_f32_e32 v32, v155, v136
	v_fma_f32 v24, v32, v90, v24
	v_mul_f32_e32 v32, v155, v137
	v_fmac_f32_e32 v25, v32, v91
	v_cvt_pk_bf16_f32 v88, v22, v23
	v_cvt_pk_bf16_f32 v89, v24, v25
	global_store_dwordx2 v[92:93], v[88:89], off offset:1536
	ds_read_b128 v[88:91], v81 offset:12288
	v_mul_f32_e32 v32, v155, v138
	v_mul_f32_e32 v59, v155, v139
	v_mul_f32_e32 v60, v155, v140
	s_waitcnt lgkmcnt(0)
	v_fma_f32 v18, v32, v88, v18
	v_mul_f32_e32 v32, v155, v141
	v_fma_f32 v19, v59, v89, v19
	v_fma_f32 v20, v60, v90, v20
	v_fmac_f32_e32 v21, v32, v91
	v_cvt_pk_bf16_f32 v94, v18, v19
	v_cvt_pk_bf16_f32 v95, v20, v21
	ds_read_b128 v[88:91], v81 offset:13312
	v_mul_f32_e32 v32, v155, v142
	global_store_dwordx2 v[92:93], v[94:95], off offset:2048
	s_waitcnt lgkmcnt(0)
	v_fma_f32 v32, v32, v88, v14
	v_mul_f32_e32 v14, v155, v143
	v_fma_f32 v15, v14, v89, v15
	v_mul_f32_e32 v14, v155, v144
	v_fma_f32 v14, v14, v90, v16
	v_mul_f32_e32 v16, v155, v145
	v_fmac_f32_e32 v17, v16, v91
	v_cvt_pk_bf16_f32 v94, v32, v15
	v_cvt_pk_bf16_f32 v95, v14, v17
	ds_read_b128 v[88:91], v81 offset:14336
	v_mul_f32_e32 v16, v155, v147
	global_store_dwordx2 v[92:93], v[94:95], off offset:2560
	s_waitcnt lgkmcnt(0)
	v_fma_f32 v10, v16, v88, v10
	v_mul_f32_e32 v16, v155, v148
	v_fma_f32 v11, v16, v89, v11
	v_mul_f32_e32 v16, v155, v149
	v_fma_f32 v12, v16, v90, v12
	v_mul_f32_e32 v16, v155, v150
	v_fmac_f32_e32 v13, v16, v91
	v_cvt_pk_bf16_f32 v94, v10, v11
	v_cvt_pk_bf16_f32 v95, v12, v13
	ds_read_b128 v[88:91], v81 offset:15360
	v_mul_f32_e32 v16, v155, v151
	global_store_dwordx2 v[92:93], v[94:95], off offset:3072
	s_waitcnt vmcnt(15) lgkmcnt(0)
	v_fma_f32 v6, v16, v88, v6
	v_mul_f32_e32 v16, v155, v152
	v_fma_f32 v7, v16, v89, v7
	v_mul_f32_e32 v16, v155, v153
	v_fma_f32 v8, v16, v90, v8
	v_mul_f32_e32 v16, v155, v154
	v_fmac_f32_e32 v9, v16, v91
	v_cvt_pk_bf16_f32 v88, v6, v7
	v_cvt_pk_bf16_f32 v89, v8, v9
	global_store_dwordx2 v[92:93], v[88:89], off offset:3584
	v_mul_f32_e32 v16, v3, v3
	v_mul_f32_e32 v59, v5, v5
	v_fmac_f32_e32 v16, v2, v2
	v_fmac_f32_e32 v59, v4, v4
	v_add_f32_e32 v16, v16, v59
	v_mul_f32_e32 v59, v63, v63
	v_mul_f32_e32 v60, v65, v65
	v_fmac_f32_e32 v59, v84, v84
	v_fmac_f32_e32 v60, v62, v62
	v_add_f32_e32 v59, v59, v60
	v_add_f32_e32 v16, v16, v59
	v_mul_f32_e32 v59, v55, v55
	v_mul_f32_e32 v60, v57, v57
	v_fmac_f32_e32 v59, v54, v54
	v_fmac_f32_e32 v60, v56, v56
	v_add_f32_e32 v59, v59, v60
	v_add_f32_e32 v16, v16, v59
	v_mul_f32_e32 v59, v85, v85
	v_mul_f32_e32 v60, v53, v53
	v_fmac_f32_e32 v59, v64, v64
	v_fmac_f32_e32 v60, v86, v86
	v_add_f32_e32 v59, v59, v60
	v_add_f32_e32 v16, v16, v59
	v_mul_f32_e32 v59, v51, v51
	v_mul_f32_e32 v60, v61, v61
	v_fmac_f32_e32 v59, v50, v50
	v_fmac_f32_e32 v60, v52, v52
	v_add_f32_e32 v59, v59, v60
	v_add_f32_e32 v16, v16, v59
	v_mul_f32_e32 v59, v47, v47
	v_mul_f32_e32 v60, v49, v49
	v_fmac_f32_e32 v59, v58, v58
	v_fmac_f32_e32 v60, v46, v46
	v_add_f32_e32 v59, v59, v60
	v_add_f32_e32 v16, v16, v59
	v_mul_f32_e32 v59, v39, v39
	v_mul_f32_e32 v60, v41, v41
	v_fmac_f32_e32 v59, v38, v38
	v_fmac_f32_e32 v60, v40, v40
	v_add_f32_e32 v59, v59, v60
	v_add_f32_e32 v16, v16, v59
	v_mul_f32_e32 v59, v43, v43
	v_mul_f32_e32 v60, v45, v45
	v_fmac_f32_e32 v59, v42, v42
	v_fmac_f32_e32 v60, v44, v44
	v_add_f32_e32 v59, v59, v60
	v_add_f32_e32 v16, v16, v59
	v_mul_f32_e32 v59, v35, v35
	v_mul_f32_e32 v60, v37, v37
	v_fmac_f32_e32 v59, v34, v34
	v_fmac_f32_e32 v60, v36, v36
	v_add_f32_e32 v59, v59, v60
	v_add_f32_e32 v16, v16, v59
	v_mul_f32_e32 v59, v31, v31
	v_mul_f32_e32 v60, v33, v33
	v_fmac_f32_e32 v59, v48, v48
	v_fmac_f32_e32 v60, v30, v30
	v_add_f32_e32 v59, v59, v60
	v_add_f32_e32 v16, v16, v59
	v_mul_f32_e32 v59, v27, v27
	v_mul_f32_e32 v60, v29, v29
	v_fmac_f32_e32 v59, v26, v26
	v_fmac_f32_e32 v60, v28, v28
	v_add_f32_e32 v59, v59, v60
	v_add_f32_e32 v16, v16, v59
	v_mul_f32_e32 v59, v23, v23
	v_mul_f32_e32 v60, v25, v25
	v_fmac_f32_e32 v59, v22, v22
	v_fmac_f32_e32 v60, v24, v24
	v_add_f32_e32 v59, v59, v60
	v_add_f32_e32 v16, v16, v59
	v_mul_f32_e32 v59, v19, v19
	v_mul_f32_e32 v60, v21, v21
	v_fmac_f32_e32 v59, v18, v18
	v_fmac_f32_e32 v60, v20, v20
	v_add_f32_e32 v59, v59, v60
	v_add_f32_e32 v16, v16, v59
	v_mul_f32_e32 v59, v15, v15
	v_mul_f32_e32 v60, v17, v17
	v_fmac_f32_e32 v59, v32, v32
	v_fmac_f32_e32 v60, v14, v14
	v_add_f32_e32 v59, v59, v60
	v_add_f32_e32 v16, v16, v59
	v_mul_f32_e32 v59, v11, v11
	v_mul_f32_e32 v60, v13, v13
	v_fmac_f32_e32 v59, v10, v10
	v_fmac_f32_e32 v60, v12, v12
	v_add_f32_e32 v59, v59, v60
	v_add_f32_e32 v16, v16, v59
	v_mul_f32_e32 v59, v7, v7
	v_mul_f32_e32 v60, v9, v9
	v_fmac_f32_e32 v59, v6, v6
	v_fmac_f32_e32 v60, v8, v8
	v_add_f32_e32 v59, v59, v60
	v_add_f32_e32 v16, v16, v59
	ds_bpermute_b32 v59, v1, v16
	s_waitcnt lgkmcnt(0)
	v_add_f32_e32 v16, v16, v59
	ds_bpermute_b32 v59, v76, v16
	s_waitcnt lgkmcnt(0)
	v_add_f32_e32 v16, v16, v59
	ds_bpermute_b32 v59, v77, v16
	s_waitcnt lgkmcnt(0)
	v_add_f32_e32 v16, v16, v59
	ds_bpermute_b32 v59, v78, v16
	s_waitcnt lgkmcnt(0)
	v_add_f32_e32 v16, v16, v59
	ds_bpermute_b32 v59, v79, v16
	s_waitcnt lgkmcnt(0)
	v_add_f32_e32 v16, v16, v59
	ds_bpermute_b32 v59, v80, v16
	s_waitcnt lgkmcnt(0)
	v_add_f32_e32 v16, v16, v59
	v_fmamk_f32 v16, v16, 0x39800000, v66
	v_mul_f32_e32 v59, 0x4f800000, v16
	v_cmp_gt_f32_e32 vcc, s50, v16
	s_nop 1
	v_cndmask_b32_e32 v16, v16, v59, vcc
	v_sqrt_f32_e32 v59, v16
	s_nop 0
	v_add_u32_e32 v60, -1, v59
	v_fma_f32 v87, -v60, v59, v16
	v_cmp_ge_f32_e64 s[8:9], 0, v87
	v_add_u32_e32 v87, 1, v59
	s_nop 0
	v_cndmask_b32_e64 v60, v59, v60, s[8:9]
	v_fma_f32 v59, -v87, v59, v16
	v_cmp_lt_f32_e64 s[8:9], 0, v59
	s_nop 1
	v_cndmask_b32_e64 v59, v60, v87, s[8:9]
	v_mul_f32_e32 v60, 0x37800000, v59
	v_cndmask_b32_e32 v59, v59, v60, vcc
	v_cmp_class_f32_e32 vcc, v16, v82
	s_nop 1
	v_cndmask_b32_e32 v16, v59, v16, vcc
	v_div_scale_f32 v59, s[0:1], v16, v16, 1.0
	v_rcp_f32_e32 v60, v59
	s_nop 0
	v_fma_f32 v87, -v59, v60, 1.0
	v_fmac_f32_e32 v60, v87, v60
	v_div_scale_f32 v87, vcc, 1.0, v16, 1.0
	v_mul_f32_e32 v88, v87, v60
	v_fma_f32 v89, -v59, v88, v87
	v_fmac_f32_e32 v88, v89, v60
	v_fma_f32 v59, -v59, v88, v87
	v_div_fmas_f32 v59, v59, v60, v88
	v_div_fixup_f32 v87, v59, v16, 1.0
	s_and_saveexec_b64 s[0:1], s[6:7]
	s_cbranch_execz .LBB0_483
	s_lshl_b64 s[8:9], s[38:39], 2
	s_add_u32 s8, s10, s8
	s_addc_u32 s9, s11, s9
	global_store_dword v67, v87, s[8:9]

.LBB0_1187:
	v_mov_b32_e32 v131, v0
	s_cmp_lg_u32 s72, 0
	v_ashrrev_i32_e32 v130, 2, v131
	v_and_b32_e32 v130, 0xffffffc0, v130
	v_lshl_add_u32 v130, s48, 8, v130
	v_and_or_b32 v130, v131, 15, v130
	v_lshrrev_b32_e32 v131, 1, v131
	v_and_b32_e32 v131, 0x78, v131
	v_lshl_or_b32 v144, s49, 8, v131
	s_cselect_b64 s[48:49], -1, 0
	s_cmp_eq_u32 s72, 0
	v_ashrrev_i32_e32 v145, 31, v144
	v_ashrrev_i32_e32 v131, 31, v130
	v_mad_i64_i32 v[178:179], s[0:1], v130, s67, 0
	v_or_b32_e32 v142, 16, v130
	v_or_b32_e32 v174, 32, v130
	v_or_b32_e32 v172, 48, v130
	v_add_u32_e32 v170, 0x80, v130
	v_add_u32_e32 v168, 0x90, v130
	v_add_u32_e32 v166, 0xa0, v130
	v_add_u32_e32 v164, 0xb0, v130
	s_cbranch_scc1 .LBB0_1195
	v_lshl_add_u64 v[132:133], s[36:37], 0, v[178:179]
	v_lshlrev_b64 v[176:177], 1, v[144:145]
	v_lshl_add_u64 v[132:133], v[132:133], 0, v[176:177]
	v_add_co_u32_e32 v134, vcc, 0x7000, v132
	v_mov_b64_e32 v[180:181], s[36:37]
	s_nop 0
	v_addc_co_u32_e32 v135, vcc, 0, v133, vcc
	global_load_dwordx4 v[138:141], v[134:135], off nt
	v_lshl_add_u64 v[132:133], v[132:133], 0, s[40:41]
	global_load_dwordx4 v[182:185], v[132:133], off offset:256 nt
	v_lshlrev_b64 v[130:131], 13, v[130:131]
	v_mad_i64_i32 v[132:133], s[0:1], v142, s67, v[180:181]
	v_lshl_add_u64 v[130:131], s[38:39], 0, v[130:131]
	v_lshl_add_u64 v[132:133], v[132:133], 0, v[176:177]
	v_lshl_add_u64 v[202:203], v[130:131], 0, v[176:177]
	v_lshl_add_u64 v[130:131], v[132:133], 0, s[40:41]
	v_add_co_u32_e32 v132, vcc, 0x7000, v132
	v_mad_i64_i32 v[134:135], s[0:1], v174, s67, v[180:181]
	s_nop 0
	v_addc_co_u32_e32 v133, vcc, 0, v133, vcc
	global_load_dwordx4 v[186:189], v[132:133], off nt
	global_load_dwordx4 v[190:193], v[130:131], off offset:256 nt
	v_lshl_add_u64 v[134:135], v[134:135], 0, v[176:177]
	v_lshl_add_u64 v[198:199], v[134:135], 0, s[40:41]
	v_add_co_u32_e32 v134, vcc, 0x7000, v134
	v_mad_i64_i32 v[136:137], s[0:1], v172, s67, v[180:181]
	s_nop 0
	v_addc_co_u32_e32 v135, vcc, 0, v135, vcc
	global_load_dwordx4 v[194:197], v[134:135], off nt
	s_nop 0
	global_load_dwordx4 v[198:201], v[198:199], off offset:256 nt
	v_lshl_add_u64 v[136:137], v[136:137], 0, v[176:177]
	v_add_co_u32_e32 v130, vcc, 0x7000, v136
	v_lshl_add_u64 v[204:205], v[136:137], 0, s[40:41]
	s_nop 0
	v_addc_co_u32_e32 v131, vcc, 0, v137, vcc
	global_load_dwordx4 v[134:137], v[130:131], off nt
	s_nop 0
	global_load_dwordx4 v[130:133], v[204:205], off offset:256 nt
	v_ashrrev_i32_e32 v143, 31, v142
	v_ashrrev_i32_e32 v175, 31, v174
	v_ashrrev_i32_e32 v173, 31, v172
	s_waitcnt vmcnt(0)
	v_lshlrev_b32_e32 v165, 16, v138
	v_and_b32_e32 v138, 0xffff0000, v138
	v_lshlrev_b32_e32 v167, 16, v139
	v_and_b32_e32 v139, 0xffff0000, v139
	v_lshlrev_b32_e32 v169, 16, v140
	v_and_b32_e32 v140, 0xffff0000, v140
	v_lshlrev_b32_e32 v171, 16, v141
	v_and_b32_e32 v141, 0xffff0000, v141
	v_max_f32_e32 v138, v138, v138
	v_max_f32_e32 v139, v139, v139
	v_max_f32_e32 v165, v165, v165
	v_max_f32_e32 v167, v167, v167
	v_max_f32_e32 v140, v140, v140
	v_max_f32_e32 v141, v141, v141
	v_max_f32_e32 v138, 0x358637bd, v138
	v_max_f32_e32 v139, 0x358637bd, v139
	v_max_f32_e32 v169, v169, v169
	v_max_f32_e32 v171, v171, v171
	v_max_f32_e32 v165, 0x358637bd, v165
	v_max_f32_e32 v167, 0x358637bd, v167
	v_max_f32_e32 v140, 0x358637bd, v140
	v_max_f32_e32 v141, 0x358637bd, v141
	v_mul_f32_e32 v138, v127, v138
	v_mul_f32_e32 v139, v129, v139
	v_max_f32_e32 v169, 0x358637bd, v169
	v_max_f32_e32 v171, 0x358637bd, v171
	v_mul_f32_e32 v165, v126, v165
	v_mul_f32_e32 v167, v128, v167
	v_mul_f32_e32 v140, v123, v140
	v_mul_f32_e32 v141, v125, v141
	v_cvt_pk_bf16_f32 v138, v165, v138
	v_cvt_pk_bf16_f32 v139, v167, v139
	v_lshlrev_b32_e32 v204, 16, v182
	v_mul_f32_e32 v169, v122, v169
	v_mul_f32_e32 v171, v124, v171
	v_cvt_pk_bf16_f32 v140, v169, v140
	v_cvt_pk_bf16_f32 v141, v171, v141
	global_store_dwordx4 v[202:203], v[138:141], off
	v_max_f32_e32 v204, v204, v204
	v_and_b32_e32 v165, 0xffff0000, v185
	v_and_b32_e32 v139, 0xffff0000, v182
	v_max_f32_e32 v139, v139, v139
	v_max_f32_e32 v138, 0x358637bd, v204
	v_max_f32_e32 v139, 0x358637bd, v139
	v_mul_f32_e32 v138, v94, v138
	v_mul_f32_e32 v139, v95, v139
	v_cvt_pk_bf16_f32 v138, v138, v139
	v_lshlrev_b32_e32 v139, 16, v183
	v_and_b32_e32 v140, 0xffff0000, v183
	v_max_f32_e32 v139, v139, v139
	v_max_f32_e32 v140, v140, v140
	v_max_f32_e32 v139, 0x358637bd, v139
	v_max_f32_e32 v140, 0x358637bd, v140
	v_mul_f32_e32 v139, v96, v139
	v_mul_f32_e32 v140, v97, v140
	v_cvt_pk_bf16_f32 v139, v139, v140
	v_lshlrev_b32_e32 v140, 16, v184
	v_and_b32_e32 v141, 0xffff0000, v184
	v_max_f32_e32 v140, v140, v140
	v_max_f32_e32 v141, v141, v141
	v_max_f32_e32 v140, 0x358637bd, v140
	v_max_f32_e32 v141, 0x358637bd, v141
	v_mul_f32_e32 v140, v90, v140
	v_mul_f32_e32 v141, v91, v141
	v_cvt_pk_bf16_f32 v140, v140, v141
	v_lshlrev_b32_e32 v141, 16, v185
	v_max_f32_e32 v141, v141, v141
	v_max_f32_e32 v141, 0x358637bd, v141
	v_max_f32_e32 v165, v165, v165
	v_mul_f32_e32 v141, v92, v141
	v_max_f32_e32 v165, 0x358637bd, v165
	v_mul_f32_e32 v165, v93, v165
	v_cvt_pk_bf16_f32 v141, v141, v165
	global_store_dwordx4 v[202:203], v[138:141], off offset:256
	v_and_b32_e32 v165, 0xffff0000, v189
	v_lshlrev_b64 v[182:183], 13, v[142:143]
	v_lshlrev_b32_e32 v138, 16, v186
	v_and_b32_e32 v139, 0xffff0000, v186
	v_max_f32_e32 v138, v138, v138
	v_max_f32_e32 v139, v139, v139
	v_max_f32_e32 v138, 0x358637bd, v138
	v_max_f32_e32 v139, 0x358637bd, v139
	v_mul_f32_e32 v138, v118, v138
	v_mul_f32_e32 v139, v119, v139
	v_cvt_pk_bf16_f32 v138, v138, v139
	v_lshlrev_b32_e32 v139, 16, v187
	v_and_b32_e32 v140, 0xffff0000, v187
	v_max_f32_e32 v139, v139, v139
	v_max_f32_e32 v140, v140, v140
	v_max_f32_e32 v139, 0x358637bd, v139
	v_max_f32_e32 v140, 0x358637bd, v140
	v_mul_f32_e32 v139, v120, v139
	v_mul_f32_e32 v140, v121, v140
	v_cvt_pk_bf16_f32 v139, v139, v140
	v_lshlrev_b32_e32 v140, 16, v188
	v_and_b32_e32 v141, 0xffff0000, v188
	v_max_f32_e32 v140, v140, v140
	v_max_f32_e32 v141, v141, v141
	v_max_f32_e32 v140, 0x358637bd, v140
	v_max_f32_e32 v141, 0x358637bd, v141
	v_mul_f32_e32 v140, v114, v140
	v_mul_f32_e32 v141, v115, v141
	v_cvt_pk_bf16_f32 v140, v140, v141
	v_lshlrev_b32_e32 v141, 16, v189
	v_max_f32_e32 v141, v141, v141
	v_max_f32_e32 v141, 0x358637bd, v141
	v_max_f32_e32 v165, v165, v165
	v_lshl_add_u64 v[182:183], s[38:39], 0, v[182:183]
	v_mul_f32_e32 v141, v116, v141
	v_max_f32_e32 v165, 0x358637bd, v165
	v_lshl_add_u64 v[182:183], v[182:183], 0, v[176:177]
	v_mul_f32_e32 v165, v117, v165
	v_cvt_pk_bf16_f32 v141, v141, v165
	global_store_dwordx4 v[182:183], v[138:141], off
	v_and_b32_e32 v143, 0xffff0000, v193
	v_max_f32_e32 v143, v143, v143
	v_lshlrev_b32_e32 v138, 16, v190
	v_and_b32_e32 v139, 0xffff0000, v190
	v_max_f32_e32 v138, v138, v138
	v_max_f32_e32 v139, v139, v139
	v_max_f32_e32 v138, 0x358637bd, v138
	v_max_f32_e32 v139, 0x358637bd, v139
	v_mul_f32_e32 v138, v86, v138
	v_mul_f32_e32 v139, v87, v139
	v_cvt_pk_bf16_f32 v138, v138, v139
	v_lshlrev_b32_e32 v139, 16, v191
	v_and_b32_e32 v140, 0xffff0000, v191
	v_max_f32_e32 v139, v139, v139
	v_max_f32_e32 v140, v140, v140
	v_max_f32_e32 v139, 0x358637bd, v139
	v_max_f32_e32 v140, 0x358637bd, v140
	v_mul_f32_e32 v139, v88, v139
	v_mul_f32_e32 v140, v89, v140
	v_cvt_pk_bf16_f32 v139, v139, v140
	v_lshlrev_b32_e32 v140, 16, v192
	v_and_b32_e32 v141, 0xffff0000, v192
	v_max_f32_e32 v140, v140, v140
	v_max_f32_e32 v141, v141, v141
	v_max_f32_e32 v140, 0x358637bd, v140
	v_max_f32_e32 v141, 0x358637bd, v141
	v_mul_f32_e32 v140, v82, v140
	v_mul_f32_e32 v141, v83, v141
	v_cvt_pk_bf16_f32 v140, v140, v141
	v_lshlrev_b32_e32 v141, 16, v193
	v_max_f32_e32 v141, v141, v141
	v_max_f32_e32 v141, 0x358637bd, v141
	v_mul_f32_e32 v141, v84, v141
	v_max_f32_e32 v143, 0x358637bd, v143
	v_mul_f32_e32 v143, v85, v143
	v_cvt_pk_bf16_f32 v141, v141, v143
	global_store_dwordx4 v[182:183], v[138:141], off offset:256
	v_and_b32_e32 v143, 0xffff0000, v197
	v_lshlrev_b64 v[182:183], 13, v[174:175]
	v_lshlrev_b32_e32 v138, 16, v194
	v_and_b32_e32 v139, 0xffff0000, v194
	v_max_f32_e32 v138, v138, v138
	v_max_f32_e32 v139, v139, v139
	v_max_f32_e32 v138, 0x358637bd, v138
	v_max_f32_e32 v139, 0x358637bd, v139
	v_mul_f32_e32 v138, v110, v138
	v_mul_f32_e32 v139, v111, v139
	v_cvt_pk_bf16_f32 v138, v138, v139
	v_lshlrev_b32_e32 v139, 16, v195
	v_and_b32_e32 v140, 0xffff0000, v195
	v_max_f32_e32 v139, v139, v139
	v_max_f32_e32 v140, v140, v140
	v_max_f32_e32 v139, 0x358637bd, v139
	v_max_f32_e32 v140, 0x358637bd, v140
	v_mul_f32_e32 v139, v112, v139
	v_mul_f32_e32 v140, v113, v140
	v_cvt_pk_bf16_f32 v139, v139, v140
	v_lshlrev_b32_e32 v140, 16, v196
	v_and_b32_e32 v141, 0xffff0000, v196
	v_max_f32_e32 v140, v140, v140
	v_max_f32_e32 v141, v141, v141
	v_max_f32_e32 v140, 0x358637bd, v140
	v_max_f32_e32 v141, 0x358637bd, v141
	v_mul_f32_e32 v140, v106, v140
	v_mul_f32_e32 v141, v107, v141
	v_cvt_pk_bf16_f32 v140, v140, v141
	v_lshlrev_b32_e32 v141, 16, v197
	v_max_f32_e32 v141, v141, v141
	v_max_f32_e32 v141, 0x358637bd, v141
	v_max_f32_e32 v143, v143, v143
	v_lshl_add_u64 v[182:183], s[38:39], 0, v[182:183]
	v_mul_f32_e32 v141, v108, v141
	v_max_f32_e32 v143, 0x358637bd, v143
	v_lshl_add_u64 v[182:183], v[182:183], 0, v[176:177]
	v_mul_f32_e32 v143, v109, v143
	v_cvt_pk_bf16_f32 v141, v141, v143
	global_store_dwordx4 v[182:183], v[138:141], off
	v_and_b32_e32 v143, 0xffff0000, v201
	v_max_f32_e32 v143, v143, v143
	v_lshlrev_b32_e32 v138, 16, v198
	v_and_b32_e32 v139, 0xffff0000, v198
	v_max_f32_e32 v138, v138, v138
	v_max_f32_e32 v139, v139, v139
	v_max_f32_e32 v138, 0x358637bd, v138
	v_max_f32_e32 v139, 0x358637bd, v139
	v_mul_f32_e32 v138, v78, v138
	v_mul_f32_e32 v139, v79, v139
	v_cvt_pk_bf16_f32 v138, v138, v139
	v_lshlrev_b32_e32 v139, 16, v199
	v_and_b32_e32 v140, 0xffff0000, v199
	v_max_f32_e32 v139, v139, v139
	v_max_f32_e32 v140, v140, v140
	v_max_f32_e32 v139, 0x358637bd, v139
	v_max_f32_e32 v140, 0x358637bd, v140
	v_mul_f32_e32 v139, v80, v139
	v_mul_f32_e32 v140, v81, v140
	v_cvt_pk_bf16_f32 v139, v139, v140
	v_lshlrev_b32_e32 v140, 16, v200
	v_and_b32_e32 v141, 0xffff0000, v200
	v_max_f32_e32 v140, v140, v140
	v_max_f32_e32 v141, v141, v141
	v_max_f32_e32 v140, 0x358637bd, v140
	v_max_f32_e32 v141, 0x358637bd, v141
	v_mul_f32_e32 v140, v74, v140
	v_mul_f32_e32 v141, v75, v141
	v_cvt_pk_bf16_f32 v140, v140, v141
	v_lshlrev_b32_e32 v141, 16, v201
	v_max_f32_e32 v141, v141, v141
	v_max_f32_e32 v141, 0x358637bd, v141
	v_mul_f32_e32 v141, v76, v141
	v_max_f32_e32 v143, 0x358637bd, v143
	v_mul_f32_e32 v143, v77, v143
	v_cvt_pk_bf16_f32 v141, v141, v143
	global_store_dwordx4 v[182:183], v[138:141], off offset:256
	v_ashrrev_i32_e32 v171, 31, v170
	v_ashrrev_i32_e32 v169, 31, v168
	v_lshlrev_b32_e32 v138, 16, v134
	v_and_b32_e32 v134, 0xffff0000, v134
	v_max_f32_e32 v138, v138, v138
	v_max_f32_e32 v134, v134, v134
	v_max_f32_e32 v138, 0x358637bd, v138
	v_max_f32_e32 v134, 0x358637bd, v134
	v_mul_f32_e32 v138, v102, v138
	v_mul_f32_e32 v134, v103, v134
	v_cvt_pk_bf16_f32 v134, v138, v134
	v_lshlrev_b32_e32 v138, 16, v135
	v_and_b32_e32 v135, 0xffff0000, v135
	v_max_f32_e32 v138, v138, v138
	v_max_f32_e32 v135, v135, v135
	v_max_f32_e32 v138, 0x358637bd, v138
	v_max_f32_e32 v135, 0x358637bd, v135
	v_mul_f32_e32 v138, v104, v138
	v_mul_f32_e32 v135, v105, v135
	v_cvt_pk_bf16_f32 v135, v138, v135
	v_lshlrev_b32_e32 v138, 16, v136
	v_and_b32_e32 v136, 0xffff0000, v136
	v_max_f32_e32 v138, v138, v138
	v_max_f32_e32 v136, v136, v136
	v_max_f32_e32 v138, 0x358637bd, v138
	v_max_f32_e32 v136, 0x358637bd, v136
	v_mul_f32_e32 v138, v98, v138
	v_mul_f32_e32 v136, v99, v136
	v_cvt_pk_bf16_f32 v136, v138, v136
	v_lshlrev_b32_e32 v138, 16, v137
	v_and_b32_e32 v137, 0xffff0000, v137
	v_max_f32_e32 v138, v138, v138
	v_max_f32_e32 v137, v137, v137
	v_max_f32_e32 v138, 0x358637bd, v138
	v_max_f32_e32 v137, 0x358637bd, v137
	v_mul_f32_e32 v138, v100, v138
	v_mul_f32_e32 v137, v101, v137
	v_cvt_pk_bf16_f32 v137, v138, v137
	v_lshlrev_b64 v[138:139], 13, v[172:173]
	v_lshl_add_u64 v[138:139], s[38:39], 0, v[138:139]
	v_lshl_add_u64 v[138:139], v[138:139], 0, v[176:177]
	global_store_dwordx4 v[138:139], v[134:137], off
	v_ashrrev_i32_e32 v167, 31, v166
	v_ashrrev_i32_e32 v165, 31, v164
	v_lshlrev_b32_e32 v134, 16, v130
	v_and_b32_e32 v130, 0xffff0000, v130
	v_max_f32_e32 v134, v134, v134
	v_max_f32_e32 v130, v130, v130
	v_max_f32_e32 v134, 0x358637bd, v134
	v_max_f32_e32 v130, 0x358637bd, v130
	v_mul_f32_e32 v134, v70, v134
	v_mul_f32_e32 v130, v71, v130
	v_cvt_pk_bf16_f32 v130, v134, v130
	v_lshlrev_b32_e32 v134, 16, v131
	v_and_b32_e32 v131, 0xffff0000, v131
	v_max_f32_e32 v134, v134, v134
	v_max_f32_e32 v131, v131, v131
	v_max_f32_e32 v134, 0x358637bd, v134
	v_max_f32_e32 v131, 0x358637bd, v131
	v_mul_f32_e32 v134, v72, v134
	v_mul_f32_e32 v131, v73, v131
	v_cvt_pk_bf16_f32 v131, v134, v131
	v_lshlrev_b32_e32 v134, 16, v132
	v_and_b32_e32 v132, 0xffff0000, v132
	v_max_f32_e32 v134, v134, v134
	v_max_f32_e32 v132, v132, v132
	v_max_f32_e32 v134, 0x358637bd, v134
	v_max_f32_e32 v132, 0x358637bd, v132
	v_mul_f32_e32 v134, v66, v134
	v_mul_f32_e32 v132, v67, v132
	v_cvt_pk_bf16_f32 v132, v134, v132
	v_lshlrev_b32_e32 v134, 16, v133
	v_and_b32_e32 v133, 0xffff0000, v133
	v_max_f32_e32 v133, v133, v133
	v_max_f32_e32 v134, v134, v134
	v_max_f32_e32 v133, 0x358637bd, v133
	v_max_f32_e32 v134, 0x358637bd, v134
	v_mul_f32_e32 v133, v69, v133
	v_mul_f32_e32 v134, v68, v134
	v_cvt_pk_bf16_f32 v133, v134, v133
	global_store_dwordx4 v[138:139], v[130:133], off offset:256
	s_nop 1
	v_mad_i64_i32 v[130:131], s[0:1], v170, s67, v[180:181]
	v_lshl_add_u64 v[130:131], v[130:131], 0, v[176:177]
	v_add_co_u32_e32 v132, vcc, s68, v130
	s_nop 1
	v_addc_co_u32_e32 v133, vcc, 0, v131, vcc
	global_load_dwordx4 v[182:185], v[132:133], off nt
	v_lshl_add_u64 v[130:131], v[130:131], 0, s[40:41]
	global_load_dwordx4 v[186:189], v[130:131], off offset:256 nt
	v_mad_i64_i32 v[130:131], s[0:1], v168, s67, v[180:181]
	v_lshl_add_u64 v[130:131], v[130:131], 0, v[176:177]
	v_lshl_add_u64 v[132:133], v[130:131], 0, s[40:41]
	v_add_co_u32_e32 v130, vcc, s68, v130
	s_waitcnt vmcnt(1)
	v_lshlrev_b32_e32 v143, 16, v182
	v_addc_co_u32_e32 v131, vcc, 0, v131, vcc
	global_load_dwordx4 v[190:193], v[130:131], off nt
	global_load_dwordx4 v[194:197], v[132:133], off offset:256 nt
	v_mad_i64_i32 v[130:131], s[0:1], v166, s67, v[180:181]
	v_lshl_add_u64 v[130:131], v[130:131], 0, v[176:177]
	v_lshl_add_u64 v[132:133], v[130:131], 0, s[40:41]
	v_add_co_u32_e32 v130, vcc, s68, v130
	v_max_f32_e32 v143, v143, v143
	s_nop 0
	v_addc_co_u32_e32 v131, vcc, 0, v131, vcc
	global_load_dwordx4 v[198:201], v[130:131], off nt
	global_load_dwordx4 v[138:141], v[132:133], off offset:256 nt
	v_mad_i64_i32 v[130:131], s[0:1], v164, s67, v[180:181]
	v_lshl_add_u64 v[130:131], v[130:131], 0, v[176:177]
	v_and_b32_e32 v173, 0xffff0000, v182
	v_lshl_add_u64 v[132:133], v[130:131], 0, s[40:41]
	v_add_co_u32_e32 v130, vcc, s68, v130
	v_max_f32_e32 v143, 0x358637bd, v143
	v_max_f32_e32 v173, v173, v173
	v_addc_co_u32_e32 v131, vcc, 0, v131, vcc
	v_mul_f32_e32 v143, v62, v143
	v_max_f32_e32 v173, 0x358637bd, v173
	global_load_dwordx4 v[134:137], v[130:131], off nt
	s_nop 0
	global_load_dwordx4 v[130:133], v[132:133], off offset:256 nt
	v_mul_f32_e32 v173, v63, v173
	v_cvt_pk_bf16_f32 v180, v143, v173
	v_lshlrev_b32_e32 v143, 16, v183
	v_max_f32_e32 v143, v143, v143
	v_and_b32_e32 v173, 0xffff0000, v183
	v_max_f32_e32 v143, 0x358637bd, v143
	v_max_f32_e32 v173, v173, v173
	v_mul_f32_e32 v143, v64, v143
	v_max_f32_e32 v173, 0x358637bd, v173
	v_mul_f32_e32 v173, v65, v173
	v_cvt_pk_bf16_f32 v181, v143, v173
	v_lshlrev_b32_e32 v143, 16, v184
	v_max_f32_e32 v143, v143, v143
	v_and_b32_e32 v173, 0xffff0000, v184
	v_max_f32_e32 v143, 0x358637bd, v143
	v_max_f32_e32 v173, v173, v173
	v_mul_f32_e32 v143, v58, v143
	v_max_f32_e32 v173, 0x358637bd, v173
	v_mul_f32_e32 v173, v59, v173
	v_cvt_pk_bf16_f32 v182, v143, v173
	v_lshlrev_b32_e32 v143, 16, v185
	v_max_f32_e32 v143, v143, v143
	v_and_b32_e32 v173, 0xffff0000, v185
	v_max_f32_e32 v143, 0x358637bd, v143
	v_max_f32_e32 v173, v173, v173
	v_mul_f32_e32 v143, v60, v143
	v_max_f32_e32 v173, 0x358637bd, v173
	v_mul_f32_e32 v173, v61, v173
	v_cvt_pk_bf16_f32 v183, v143, v173
	s_waitcnt vmcnt(6)
	v_lshlrev_b32_e32 v143, 16, v186
	v_lshlrev_b64 v[184:185], 13, v[170:171]
	v_max_f32_e32 v143, v143, v143
	v_and_b32_e32 v171, 0xffff0000, v186
	v_lshl_add_u64 v[184:185], s[38:39], 0, v[184:185]
	v_max_f32_e32 v143, 0x358637bd, v143
	v_max_f32_e32 v171, v171, v171
	v_lshl_add_u64 v[184:185], v[184:185], 0, v[176:177]
	v_mul_f32_e32 v143, v30, v143
	v_max_f32_e32 v171, 0x358637bd, v171
	global_store_dwordx4 v[184:185], v[180:183], off
	v_mul_f32_e32 v171, v31, v171
	s_nop 0
	v_cvt_pk_bf16_f32 v180, v143, v171
	v_lshlrev_b32_e32 v143, 16, v187
	v_max_f32_e32 v143, v143, v143
	v_and_b32_e32 v171, 0xffff0000, v187
	v_max_f32_e32 v143, 0x358637bd, v143
	v_max_f32_e32 v171, v171, v171
	v_mul_f32_e32 v143, v32, v143
	v_max_f32_e32 v171, 0x358637bd, v171
	v_mul_f32_e32 v171, v33, v171
	v_cvt_pk_bf16_f32 v181, v143, v171
	v_lshlrev_b32_e32 v143, 16, v188
	v_max_f32_e32 v143, v143, v143
	v_and_b32_e32 v171, 0xffff0000, v188
	v_max_f32_e32 v143, 0x358637bd, v143
	v_max_f32_e32 v171, v171, v171
	v_mul_f32_e32 v143, v26, v143
	v_max_f32_e32 v171, 0x358637bd, v171
	v_mul_f32_e32 v171, v27, v171
	v_cvt_pk_bf16_f32 v182, v143, v171
	v_lshlrev_b32_e32 v143, 16, v189
	v_max_f32_e32 v143, v143, v143
	v_and_b32_e32 v171, 0xffff0000, v189
	v_max_f32_e32 v143, 0x358637bd, v143
	v_max_f32_e32 v171, v171, v171
	v_mul_f32_e32 v143, v28, v143
	v_max_f32_e32 v171, 0x358637bd, v171
	v_mul_f32_e32 v171, v29, v171
	v_cvt_pk_bf16_f32 v183, v143, v171
	s_waitcnt vmcnt(6)
	v_lshlrev_b32_e32 v143, 16, v190
	v_max_f32_e32 v143, v143, v143
	v_and_b32_e32 v171, 0xffff0000, v190
	v_max_f32_e32 v143, 0x358637bd, v143
	v_max_f32_e32 v171, v171, v171
	v_mul_f32_e32 v143, v54, v143
	v_max_f32_e32 v171, 0x358637bd, v171
	global_store_dwordx4 v[184:185], v[180:183], off offset:256
	v_mul_f32_e32 v171, v55, v171
	v_lshlrev_b64 v[184:185], 13, v[168:169]
	v_cvt_pk_bf16_f32 v180, v143, v171
	v_lshlrev_b32_e32 v143, 16, v191
	v_max_f32_e32 v143, v143, v143
	v_and_b32_e32 v171, 0xffff0000, v191
	v_max_f32_e32 v143, 0x358637bd, v143
	v_max_f32_e32 v171, v171, v171
	v_mul_f32_e32 v143, v56, v143
	v_max_f32_e32 v171, 0x358637bd, v171
	v_mul_f32_e32 v171, v57, v171
	v_cvt_pk_bf16_f32 v181, v143, v171
	v_lshlrev_b32_e32 v143, 16, v192
	v_max_f32_e32 v143, v143, v143
	v_and_b32_e32 v171, 0xffff0000, v192
	v_max_f32_e32 v143, 0x358637bd, v143
	v_max_f32_e32 v171, v171, v171
	v_mul_f32_e32 v143, v50, v143
	v_max_f32_e32 v171, 0x358637bd, v171
	v_mul_f32_e32 v171, v51, v171
	v_cvt_pk_bf16_f32 v182, v143, v171
	v_lshlrev_b32_e32 v143, 16, v193
	v_max_f32_e32 v143, v143, v143
	v_and_b32_e32 v171, 0xffff0000, v193
	v_max_f32_e32 v143, 0x358637bd, v143
	v_max_f32_e32 v171, v171, v171
	v_mul_f32_e32 v143, v52, v143
	v_max_f32_e32 v171, 0x358637bd, v171
	v_mul_f32_e32 v171, v53, v171
	v_cvt_pk_bf16_f32 v183, v143, v171
	s_waitcnt vmcnt(6)
	v_lshlrev_b32_e32 v143, 16, v194
	v_max_f32_e32 v143, v143, v143
	v_and_b32_e32 v169, 0xffff0000, v194
	v_lshl_add_u64 v[184:185], s[38:39], 0, v[184:185]
	v_max_f32_e32 v143, 0x358637bd, v143
	v_max_f32_e32 v169, v169, v169
	v_lshl_add_u64 v[184:185], v[184:185], 0, v[176:177]
	v_mul_f32_e32 v143, v22, v143
	v_max_f32_e32 v169, 0x358637bd, v169
	global_store_dwordx4 v[184:185], v[180:183], off
	v_mul_f32_e32 v169, v23, v169
	s_nop 0
	v_cvt_pk_bf16_f32 v180, v143, v169
	v_lshlrev_b32_e32 v143, 16, v195
	v_max_f32_e32 v143, v143, v143
	v_and_b32_e32 v169, 0xffff0000, v195
	v_max_f32_e32 v143, 0x358637bd, v143
	v_max_f32_e32 v169, v169, v169
	v_mul_f32_e32 v143, v24, v143
	v_max_f32_e32 v169, 0x358637bd, v169
	v_mul_f32_e32 v169, v25, v169
	v_cvt_pk_bf16_f32 v181, v143, v169
	v_lshlrev_b32_e32 v143, 16, v196
	v_max_f32_e32 v143, v143, v143
	v_and_b32_e32 v169, 0xffff0000, v196
	v_max_f32_e32 v143, 0x358637bd, v143
	v_max_f32_e32 v169, v169, v169
	v_mul_f32_e32 v143, v18, v143
	v_max_f32_e32 v169, 0x358637bd, v169
	v_mul_f32_e32 v169, v19, v169
	v_cvt_pk_bf16_f32 v182, v143, v169
	v_lshlrev_b32_e32 v143, 16, v197
	v_max_f32_e32 v143, v143, v143
	v_and_b32_e32 v169, 0xffff0000, v197
	v_max_f32_e32 v143, 0x358637bd, v143
	v_max_f32_e32 v169, v169, v169
	v_mul_f32_e32 v143, v20, v143
	v_max_f32_e32 v169, 0x358637bd, v169
	v_mul_f32_e32 v169, v21, v169
	v_cvt_pk_bf16_f32 v183, v143, v169
	s_waitcnt vmcnt(6)
	v_lshlrev_b32_e32 v143, 16, v198
	v_max_f32_e32 v143, v143, v143
	v_and_b32_e32 v169, 0xffff0000, v198
	v_max_f32_e32 v143, 0x358637bd, v143
	v_max_f32_e32 v169, v169, v169
	v_mul_f32_e32 v143, v46, v143
	v_max_f32_e32 v169, 0x358637bd, v169
	global_store_dwordx4 v[184:185], v[180:183], off offset:256
	v_mul_f32_e32 v169, v47, v169
	v_lshlrev_b64 v[184:185], 13, v[166:167]
	v_cvt_pk_bf16_f32 v180, v143, v169
	v_lshlrev_b32_e32 v143, 16, v199
	v_max_f32_e32 v143, v143, v143
	v_and_b32_e32 v169, 0xffff0000, v199
	v_max_f32_e32 v143, 0x358637bd, v143
	v_max_f32_e32 v169, v169, v169
	v_mul_f32_e32 v143, v48, v143
	v_max_f32_e32 v169, 0x358637bd, v169
	v_mul_f32_e32 v169, v49, v169
	v_cvt_pk_bf16_f32 v181, v143, v169
	v_lshlrev_b32_e32 v143, 16, v200
	v_max_f32_e32 v143, v143, v143
	v_and_b32_e32 v169, 0xffff0000, v200
	v_max_f32_e32 v143, 0x358637bd, v143
	v_max_f32_e32 v169, v169, v169
	v_mul_f32_e32 v143, v42, v143
	v_max_f32_e32 v169, 0x358637bd, v169
	v_mul_f32_e32 v169, v43, v169
	v_cvt_pk_bf16_f32 v182, v143, v169
	v_lshlrev_b32_e32 v143, 16, v201
	v_max_f32_e32 v143, v143, v143
	v_and_b32_e32 v169, 0xffff0000, v201
	v_max_f32_e32 v143, 0x358637bd, v143
	v_max_f32_e32 v169, v169, v169
	v_mul_f32_e32 v143, v44, v143
	v_max_f32_e32 v169, 0x358637bd, v169
	v_mul_f32_e32 v169, v45, v169
	v_cvt_pk_bf16_f32 v183, v143, v169
	s_waitcnt vmcnt(6)
	v_lshlrev_b32_e32 v143, 16, v138
	v_and_b32_e32 v138, 0xffff0000, v138
	v_max_f32_e32 v143, v143, v143
	v_max_f32_e32 v138, v138, v138
	v_lshl_add_u64 v[184:185], s[38:39], 0, v[184:185]
	v_max_f32_e32 v143, 0x358637bd, v143
	v_max_f32_e32 v138, 0x358637bd, v138
	v_lshl_add_u64 v[184:185], v[184:185], 0, v[176:177]
	v_mul_f32_e32 v143, v14, v143
	v_mul_f32_e32 v138, v15, v138
	global_store_dwordx4 v[184:185], v[180:183], off
	v_cvt_pk_bf16_f32 v138, v143, v138
	v_lshlrev_b32_e32 v143, 16, v139
	v_and_b32_e32 v139, 0xffff0000, v139
	v_max_f32_e32 v143, v143, v143
	v_max_f32_e32 v139, v139, v139
	v_max_f32_e32 v143, 0x358637bd, v143
	v_max_f32_e32 v139, 0x358637bd, v139
	v_mul_f32_e32 v143, v16, v143
	v_mul_f32_e32 v139, v17, v139
	v_cvt_pk_bf16_f32 v139, v143, v139
	v_lshlrev_b32_e32 v143, 16, v140
	v_and_b32_e32 v140, 0xffff0000, v140
	v_max_f32_e32 v143, v143, v143
	v_max_f32_e32 v140, v140, v140
	v_max_f32_e32 v143, 0x358637bd, v143
	v_max_f32_e32 v140, 0x358637bd, v140
	v_mul_f32_e32 v143, v10, v143
	v_mul_f32_e32 v140, v11, v140
	v_cvt_pk_bf16_f32 v140, v143, v140
	v_lshlrev_b32_e32 v143, 16, v141
	v_and_b32_e32 v141, 0xffff0000, v141
	v_max_f32_e32 v141, v141, v141
	v_max_f32_e32 v143, v143, v143
	v_max_f32_e32 v141, 0x358637bd, v141
	v_max_f32_e32 v143, 0x358637bd, v143
	v_mul_f32_e32 v141, v13, v141
	v_mul_f32_e32 v143, v12, v143
	v_cvt_pk_bf16_f32 v141, v143, v141
	global_store_dwordx4 v[184:185], v[138:141], off offset:256
	s_waitcnt vmcnt(7)
	s_nop 0
	v_lshlrev_b32_e32 v138, 16, v134
	v_and_b32_e32 v134, 0xffff0000, v134
	v_max_f32_e32 v138, v138, v138
	v_max_f32_e32 v134, v134, v134
	v_max_f32_e32 v138, 0x358637bd, v138
	v_max_f32_e32 v134, 0x358637bd, v134
	v_mul_f32_e32 v138, v38, v138
	v_mul_f32_e32 v134, v39, v134
	v_cvt_pk_bf16_f32 v134, v138, v134
	v_lshlrev_b32_e32 v138, 16, v135
	v_and_b32_e32 v135, 0xffff0000, v135
	v_max_f32_e32 v138, v138, v138
	v_max_f32_e32 v135, v135, v135
	v_max_f32_e32 v138, 0x358637bd, v138
	v_max_f32_e32 v135, 0x358637bd, v135
	v_mul_f32_e32 v138, v40, v138
	v_mul_f32_e32 v135, v41, v135
	v_cvt_pk_bf16_f32 v135, v138, v135
	v_lshlrev_b32_e32 v138, 16, v136
	v_and_b32_e32 v136, 0xffff0000, v136
	v_max_f32_e32 v138, v138, v138
	v_max_f32_e32 v136, v136, v136
	v_max_f32_e32 v138, 0x358637bd, v138
	v_max_f32_e32 v136, 0x358637bd, v136
	v_mul_f32_e32 v138, v34, v138
	v_mul_f32_e32 v136, v35, v136
	v_cvt_pk_bf16_f32 v136, v138, v136
	v_lshlrev_b32_e32 v138, 16, v137
	v_and_b32_e32 v137, 0xffff0000, v137
	v_max_f32_e32 v138, v138, v138
	v_max_f32_e32 v137, v137, v137
	v_max_f32_e32 v138, 0x358637bd, v138
	v_max_f32_e32 v137, 0x358637bd, v137
	v_mul_f32_e32 v138, v36, v138
	v_mul_f32_e32 v137, v37, v137
	v_cvt_pk_bf16_f32 v137, v138, v137
	v_lshlrev_b64 v[138:139], 13, v[164:165]
	v_lshl_add_u64 v[138:139], s[38:39], 0, v[138:139]
	v_lshl_add_u64 v[138:139], v[138:139], 0, v[176:177]
	global_store_dwordx4 v[138:139], v[134:137], off
	s_waitcnt vmcnt(7)
	s_nop 0
	v_lshlrev_b32_e32 v134, 16, v130
	v_and_b32_e32 v130, 0xffff0000, v130
	v_max_f32_e32 v134, v134, v134
	v_max_f32_e32 v130, v130, v130
	v_max_f32_e32 v134, 0x358637bd, v134
	v_max_f32_e32 v130, 0x358637bd, v130
	v_mul_f32_e32 v134, v6, v134
	v_mul_f32_e32 v130, v7, v130
	v_cvt_pk_bf16_f32 v130, v134, v130
	v_lshlrev_b32_e32 v134, 16, v131
	v_and_b32_e32 v131, 0xffff0000, v131
	v_max_f32_e32 v134, v134, v134
	v_max_f32_e32 v131, v131, v131
	v_max_f32_e32 v134, 0x358637bd, v134
	v_max_f32_e32 v131, 0x358637bd, v131
	v_mul_f32_e32 v134, v8, v134
	v_mul_f32_e32 v131, v9, v131
	v_cvt_pk_bf16_f32 v131, v134, v131
	v_lshlrev_b32_e32 v134, 16, v132
	v_and_b32_e32 v132, 0xffff0000, v132
	v_max_f32_e32 v134, v134, v134
	v_max_f32_e32 v132, v132, v132
	v_max_f32_e32 v134, 0x358637bd, v134
	v_max_f32_e32 v132, 0x358637bd, v132
	v_mul_f32_e32 v134, v2, v134
	v_mul_f32_e32 v132, v3, v132
	v_cvt_pk_bf16_f32 v132, v134, v132
	v_lshlrev_b32_e32 v134, 16, v133
	v_and_b32_e32 v133, 0xffff0000, v133
	v_max_f32_e32 v133, v133, v133
	v_max_f32_e32 v134, v134, v134
	v_max_f32_e32 v133, 0x358637bd, v133
	v_max_f32_e32 v134, 0x358637bd, v134
	v_mul_f32_e32 v133, v5, v133
	v_mul_f32_e32 v134, v4, v134
	v_cvt_pk_bf16_f32 v133, v134, v133
	global_store_dwordx4 v[138:139], v[130:133], off offset:256
	s_cbranch_execnz .LBB0_1190
.LBB0_1189:
	v_lshl_add_u64 v[176:177], v[144:145], 1, s[36:37]
	v_lshl_add_u64 v[130:131], v[176:177], 0, v[178:179]
	v_add_co_u32_e32 v132, vcc, 0x5000, v130
	s_nop 1
	v_addc_co_u32_e32 v133, vcc, 0, v131, vcc
	v_add_co_u32_e32 v130, vcc, 0x7000, v130
	global_load_dwordx4 v[178:181], v[132:133], off nt
	global_load_dwordx4 v[182:185], v[132:133], off offset:256 nt
	v_addc_co_u32_e32 v131, vcc, 0, v131, vcc
	global_load_dwordx4 v[186:189], v[130:131], off nt
	global_load_dwordx4 v[190:193], v[130:131], off offset:256 nt
	v_mad_i64_i32 v[130:131], s[0:1], v142, s67, v[176:177]
	v_add_co_u32_e32 v132, vcc, 0x5000, v130
	s_waitcnt vmcnt(0)
	v_lshlrev_b32_e32 v194, 16, v178
	v_addc_co_u32_e32 v133, vcc, 0, v131, vcc
	v_add_co_u32_e32 v134, vcc, s68, v130
	v_lshlrev_b32_e32 v169, 16, v187
	s_nop 0
	v_addc_co_u32_e32 v135, vcc, 0, v131, vcc
	global_load_dwordx4 v[138:141], v[132:133], off nt
	s_nop 0
	global_load_dwordx4 v[130:133], v[132:133], off offset:256 nt
	s_nop 0
	global_load_dwordx4 v[142:145], v[134:135], off nt
	s_nop 0
	global_load_dwordx4 v[134:137], v[134:135], off offset:256 nt
	v_and_b32_e32 v171, 0xffff0000, v187
	v_lshlrev_b32_e32 v198, 16, v182
	v_and_b32_e32 v199, 0xffff0000, v182
	v_lshlrev_b32_e32 v165, 16, v186
	v_and_b32_e32 v167, 0xffff0000, v186
	v_lshlrev_b32_e32 v173, 16, v188
	v_and_b32_e32 v175, 0xffff0000, v188
	v_lshlrev_b32_e32 v182, 16, v189
	v_and_b32_e32 v186, 0xffff0000, v189
	v_and_b32_e32 v188, 0xffff0000, v190
	v_lshlrev_b32_e32 v189, 16, v191
	v_max_f32_e32 v169, v169, v169
	v_max_f32_e32 v171, v171, v171
	v_max_f32_e32 v188, v188, v188
	v_max_f32_e32 v189, v189, v189
	v_max_f32_e32 v169, 0x358637bd, v169
	v_max_f32_e32 v171, 0x358637bd, v171
	v_max_f32_e32 v165, v165, v165
	v_max_f32_e32 v205, 0x358637bd, v188
	v_max_f32_e32 v206, 0x358637bd, v189
	v_rcp_f32_e32 v188, v169
	v_rcp_f32_e32 v189, v171
	v_max_f32_e32 v182, v182, v182
	v_max_f32_e32 v186, v186, v186
	v_max_f32_e32 v165, 0x358637bd, v165
	v_lshlrev_b32_e32 v187, 16, v190
	v_max_f32_e32 v182, 0x358637bd, v182
	v_max_f32_e32 v190, 0x358637bd, v186
	v_rcp_f32_e32 v186, v165
	v_and_b32_e32 v165, 0xffff0000, v191
	v_and_b32_e32 v195, 0xffff0000, v178
	v_lshlrev_b32_e32 v178, 16, v179
	v_and_b32_e32 v179, 0xffff0000, v179
	v_rcp_f32_e32 v202, v182
	v_rcp_f32_e32 v203, v190
	v_max_f32_e32 v165, v165, v165
	v_pk_mul_f32 v[178:179], v[188:189], v[178:179]
	v_max_f32_e32 v165, 0x358637bd, v165
	v_pk_mul_f32 v[128:129], v[128:129], v[178:179]
	v_rcp_f32_e32 v178, v206
	v_rcp_f32_e32 v179, v165
	v_lshlrev_b32_e32 v196, 16, v180
	v_and_b32_e32 v197, 0xffff0000, v180
	v_lshlrev_b32_e32 v180, 16, v181
	v_and_b32_e32 v181, 0xffff0000, v181
	v_lshlrev_b32_e32 v165, 16, v192
	v_pk_mul_f32 v[180:181], v[202:203], v[180:181]
	v_max_f32_e32 v165, v165, v165
	v_pk_mul_f32 v[124:125], v[124:125], v[180:181]
	v_lshlrev_b32_e32 v180, 16, v183
	v_and_b32_e32 v181, 0xffff0000, v183
	v_max_f32_e32 v165, 0x358637bd, v165
	v_pk_mul_f32 v[178:179], v[178:179], v[180:181]
	v_rcp_f32_e32 v180, v165
	v_and_b32_e32 v165, 0xffff0000, v192
	v_max_f32_e32 v165, v165, v165
	v_max_f32_e32 v165, 0x358637bd, v165
	v_rcp_f32_e32 v181, v165
	v_lshlrev_b32_e32 v165, 16, v193
	v_max_f32_e32 v165, v165, v165
	v_pk_mul_f32 v[96:97], v[96:97], v[178:179]
	v_lshlrev_b32_e32 v178, 16, v184
	v_and_b32_e32 v179, 0xffff0000, v184
	v_max_f32_e32 v165, 0x358637bd, v165
	v_pk_mul_f32 v[178:179], v[180:181], v[178:179]
	v_rcp_f32_e32 v180, v165
	v_and_b32_e32 v165, 0xffff0000, v193
	v_max_f32_e32 v165, v165, v165
	v_max_f32_e32 v165, 0x358637bd, v165
	v_rcp_f32_e32 v181, v165
	v_pk_mul_f32 v[90:91], v[90:91], v[178:179]
	v_lshlrev_b32_e32 v178, 16, v185
	v_and_b32_e32 v179, 0xffff0000, v185
	v_pk_mul_f32 v[178:179], v[180:181], v[178:179]
	v_max_f32_e32 v175, v175, v175
	v_pk_mul_f32 v[92:93], v[92:93], v[178:179]
	s_waitcnt vmcnt(3)
	v_lshlrev_b32_e32 v178, 16, v138
	v_and_b32_e32 v179, 0xffff0000, v138
	s_waitcnt vmcnt(1)
	v_lshlrev_b32_e32 v165, 16, v142
	v_and_b32_e32 v142, 0xffff0000, v142
	v_lshlrev_b32_e32 v138, 16, v143
	v_max_f32_e32 v142, v142, v142
	v_max_f32_e32 v138, v138, v138
	v_max_f32_e32 v142, 0x358637bd, v142
	v_max_f32_e32 v138, 0x358637bd, v138
	v_rcp_f32_e32 v181, v142
	v_rcp_f32_e32 v142, v138
	v_and_b32_e32 v138, 0xffff0000, v143
	v_max_f32_e32 v138, v138, v138
	v_max_f32_e32 v138, 0x358637bd, v138
	v_rcp_f32_e32 v143, v138
	v_lshlrev_b32_e32 v138, 16, v139
	v_and_b32_e32 v139, 0xffff0000, v139
	v_max_f32_e32 v165, v165, v165
	v_pk_mul_f32 v[138:139], v[142:143], v[138:139]
	v_lshlrev_b32_e32 v142, 16, v144
	v_and_b32_e32 v143, 0xffff0000, v144
	v_max_f32_e32 v142, v142, v142
	v_max_f32_e32 v143, v143, v143
	v_max_f32_e32 v142, 0x358637bd, v142
	v_max_f32_e32 v143, 0x358637bd, v143
	v_rcp_f32_e32 v142, v142
	v_rcp_f32_e32 v143, v143
	v_max_f32_e32 v165, 0x358637bd, v165
	v_rcp_f32_e32 v180, v165
	v_pk_mul_f32 v[120:121], v[120:121], v[138:139]
	v_lshlrev_b32_e32 v138, 16, v140
	v_and_b32_e32 v139, 0xffff0000, v140
	v_pk_mul_f32 v[138:139], v[142:143], v[138:139]
	v_mad_i64_i32 v[142:143], s[0:1], v174, s67, v[176:177]
	v_max_f32_e32 v175, 0x358637bd, v175
	v_add_co_u32_e32 v174, vcc, s68, v142
	v_rcp_f32_e32 v201, v175
	v_pk_mul_f32 v[178:179], v[180:181], v[178:179]
	v_addc_co_u32_e32 v175, vcc, 0, v143, vcc
	v_pk_mul_f32 v[118:119], v[118:119], v[178:179]
	global_load_dwordx4 v[178:181], v[174:175], off nt
	v_add_co_u32_e32 v142, vcc, s69, v142
	v_lshlrev_b32_e32 v140, 16, v145
	s_nop 0
	v_addc_co_u32_e32 v143, vcc, 0, v143, vcc
	global_load_dwordx4 v[182:185], v[142:143], off nt
	global_load_dwordx4 v[190:193], v[142:143], off offset:256 nt
	v_max_f32_e32 v167, v167, v167
	v_max_f32_e32 v173, v173, v173
	v_max_f32_e32 v140, v140, v140
	v_max_f32_e32 v187, v187, v187
	v_max_f32_e32 v167, 0x358637bd, v167
	v_max_f32_e32 v173, 0x358637bd, v173
	v_max_f32_e32 v140, 0x358637bd, v140
	v_max_f32_e32 v204, 0x358637bd, v187
	v_rcp_f32_e32 v187, v167
	v_rcp_f32_e32 v200, v173
	v_rcp_f32_e32 v144, v140
	v_and_b32_e32 v140, 0xffff0000, v145
	v_max_f32_e32 v140, v140, v140
	v_max_f32_e32 v140, 0x358637bd, v140
	v_rcp_f32_e32 v145, v140
	v_pk_mul_f32 v[186:187], v[186:187], v[194:195]
	v_pk_mul_f32 v[188:189], v[200:201], v[196:197]
	v_pk_mul_f32 v[126:127], v[126:127], v[186:187]
	v_pk_mul_f32 v[122:123], v[122:123], v[188:189]
	global_load_dwordx4 v[186:189], v[174:175], off offset:256 nt
	v_pk_mul_f32 v[114:115], v[114:115], v[138:139]
	v_lshlrev_b32_e32 v138, 16, v141
	v_and_b32_e32 v139, 0xffff0000, v141
	v_pk_mul_f32 v[138:139], v[144:145], v[138:139]
	s_waitcnt vmcnt(4)
	v_lshlrev_b32_e32 v140, 16, v134
	v_and_b32_e32 v134, 0xffff0000, v134
	v_pk_mul_f32 v[116:117], v[116:117], v[138:139]
	v_lshlrev_b32_e32 v138, 16, v130
	v_and_b32_e32 v139, 0xffff0000, v130
	v_lshlrev_b32_e32 v130, 16, v135
	v_max_f32_e32 v134, v134, v134
	v_max_f32_e32 v130, v130, v130
	v_max_f32_e32 v134, 0x358637bd, v134
	v_max_f32_e32 v130, 0x358637bd, v130
	v_rcp_f32_e32 v141, v134
	v_rcp_f32_e32 v134, v130
	v_and_b32_e32 v130, 0xffff0000, v135
	v_max_f32_e32 v130, v130, v130
	v_max_f32_e32 v130, 0x358637bd, v130
	v_rcp_f32_e32 v135, v130
	v_lshlrev_b32_e32 v130, 16, v131
	v_and_b32_e32 v131, 0xffff0000, v131
	v_max_f32_e32 v140, v140, v140
	v_pk_mul_f32 v[130:131], v[134:135], v[130:131]
	v_lshlrev_b32_e32 v134, 16, v136
	v_and_b32_e32 v135, 0xffff0000, v136
	v_max_f32_e32 v134, v134, v134
	v_max_f32_e32 v135, v135, v135
	v_max_f32_e32 v134, 0x358637bd, v134
	v_max_f32_e32 v135, 0x358637bd, v135
	v_rcp_f32_e32 v134, v134
	v_rcp_f32_e32 v135, v135
	v_pk_mul_f32 v[88:89], v[88:89], v[130:131]
	v_lshlrev_b32_e32 v130, 16, v132
	v_and_b32_e32 v131, 0xffff0000, v132
	v_lshlrev_b32_e32 v132, 16, v137
	v_max_f32_e32 v132, v132, v132
	v_max_f32_e32 v132, 0x358637bd, v132
	v_pk_mul_f32 v[130:131], v[134:135], v[130:131]
	v_rcp_f32_e32 v134, v132
	v_and_b32_e32 v132, 0xffff0000, v137
	v_max_f32_e32 v132, v132, v132
	v_max_f32_e32 v132, 0x358637bd, v132
	v_rcp_f32_e32 v135, v132
	v_pk_mul_f32 v[82:83], v[82:83], v[130:131]
	v_lshlrev_b32_e32 v130, 16, v133
	v_and_b32_e32 v131, 0xffff0000, v133
	v_max_f32_e32 v140, 0x358637bd, v140
	v_pk_mul_f32 v[130:131], v[134:135], v[130:131]
	v_rcp_f32_e32 v140, v140
	v_pk_mul_f32 v[84:85], v[84:85], v[130:131]
	v_mad_i64_i32 v[130:131], s[0:1], v172, s67, v[176:177]
	s_waitcnt vmcnt(3)
	v_lshlrev_b32_e32 v136, 16, v178
	v_max_f32_e32 v136, v136, v136
	v_add_co_u32_e32 v132, vcc, s69, v130
	v_max_f32_e32 v136, 0x358637bd, v136
	s_nop 0
	v_addc_co_u32_e32 v133, vcc, 0, v131, vcc
	v_rcp_f32_e32 v172, v136
	v_and_b32_e32 v136, 0xffff0000, v178
	v_add_co_u32_e32 v134, vcc, s68, v130
	v_max_f32_e32 v136, v136, v136
	v_pk_mul_f32 v[138:139], v[140:141], v[138:139]
	v_addc_co_u32_e32 v135, vcc, 0, v131, vcc
	v_max_f32_e32 v136, 0x358637bd, v136
	v_pk_mul_f32 v[86:87], v[86:87], v[138:139]
	global_load_dwordx4 v[138:141], v[132:133], off nt
	s_nop 0
	global_load_dwordx4 v[130:133], v[132:133], off offset:256 nt
	v_rcp_f32_e32 v173, v136
	global_load_dwordx4 v[142:145], v[134:135], off nt
	s_nop 0
	global_load_dwordx4 v[134:137], v[134:135], off offset:256 nt
	v_lshlrev_b32_e32 v165, 16, v179
	v_max_f32_e32 v165, v165, v165
	s_waitcnt vmcnt(6)
	v_lshlrev_b32_e32 v174, 16, v182
	v_and_b32_e32 v175, 0xffff0000, v182
	v_max_f32_e32 v165, 0x358637bd, v165
	v_pk_mul_f32 v[172:173], v[172:173], v[174:175]
	v_rcp_f32_e32 v174, v165
	v_and_b32_e32 v165, 0xffff0000, v179
	v_max_f32_e32 v165, v165, v165
	v_max_f32_e32 v165, 0x358637bd, v165
	v_rcp_f32_e32 v175, v165
	v_lshlrev_b32_e32 v165, 16, v180
	v_max_f32_e32 v165, v165, v165
	v_pk_mul_f32 v[110:111], v[110:111], v[172:173]
	v_lshlrev_b32_e32 v172, 16, v183
	v_and_b32_e32 v173, 0xffff0000, v183
	v_max_f32_e32 v165, 0x358637bd, v165
	v_pk_mul_f32 v[172:173], v[174:175], v[172:173]
	v_rcp_f32_e32 v174, v165
	v_and_b32_e32 v165, 0xffff0000, v180
	v_max_f32_e32 v165, v165, v165
	v_max_f32_e32 v165, 0x358637bd, v165
	v_rcp_f32_e32 v175, v165
	v_lshlrev_b32_e32 v165, 16, v181
	v_max_f32_e32 v165, v165, v165
	v_pk_mul_f32 v[112:113], v[112:113], v[172:173]
	v_lshlrev_b32_e32 v172, 16, v184
	v_and_b32_e32 v173, 0xffff0000, v184
	v_max_f32_e32 v165, 0x358637bd, v165
	v_pk_mul_f32 v[172:173], v[174:175], v[172:173]
	v_rcp_f32_e32 v174, v165
	v_and_b32_e32 v165, 0xffff0000, v181
	v_max_f32_e32 v165, v165, v165
	v_max_f32_e32 v165, 0x358637bd, v165
	v_rcp_f32_e32 v175, v165
	s_waitcnt vmcnt(4)
	v_lshlrev_b32_e32 v165, 16, v186
	v_max_f32_e32 v165, v165, v165
	v_pk_mul_f32 v[106:107], v[106:107], v[172:173]
	v_lshlrev_b32_e32 v172, 16, v185
	v_and_b32_e32 v173, 0xffff0000, v185
	v_max_f32_e32 v165, 0x358637bd, v165
	v_pk_mul_f32 v[172:173], v[174:175], v[172:173]
	v_rcp_f32_e32 v174, v165
	v_and_b32_e32 v165, 0xffff0000, v186
	v_max_f32_e32 v165, v165, v165
	v_max_f32_e32 v165, 0x358637bd, v165
	v_rcp_f32_e32 v175, v165
	v_lshlrev_b32_e32 v165, 16, v187
	v_max_f32_e32 v165, v165, v165
	v_pk_mul_f32 v[108:109], v[108:109], v[172:173]
	v_lshlrev_b32_e32 v172, 16, v190
	v_and_b32_e32 v173, 0xffff0000, v190
	v_max_f32_e32 v165, 0x358637bd, v165
	v_pk_mul_f32 v[172:173], v[174:175], v[172:173]
	v_rcp_f32_e32 v174, v165
	v_and_b32_e32 v165, 0xffff0000, v187
	v_max_f32_e32 v165, v165, v165
	v_max_f32_e32 v165, 0x358637bd, v165
	v_rcp_f32_e32 v175, v165
	v_lshlrev_b32_e32 v165, 16, v188
	v_max_f32_e32 v165, v165, v165
	v_pk_mul_f32 v[78:79], v[78:79], v[172:173]
	v_lshlrev_b32_e32 v172, 16, v191
	v_and_b32_e32 v173, 0xffff0000, v191
	v_max_f32_e32 v165, 0x358637bd, v165
	v_pk_mul_f32 v[172:173], v[174:175], v[172:173]
	v_rcp_f32_e32 v174, v165
	v_and_b32_e32 v165, 0xffff0000, v188
	v_max_f32_e32 v165, v165, v165
	v_max_f32_e32 v165, 0x358637bd, v165
	v_rcp_f32_e32 v175, v165
	v_lshlrev_b32_e32 v165, 16, v189
	v_max_f32_e32 v165, v165, v165
	v_pk_mul_f32 v[80:81], v[80:81], v[172:173]
	v_lshlrev_b32_e32 v172, 16, v192
	v_and_b32_e32 v173, 0xffff0000, v192
	v_max_f32_e32 v165, 0x358637bd, v165
	v_pk_mul_f32 v[172:173], v[174:175], v[172:173]
	v_rcp_f32_e32 v174, v165
	v_and_b32_e32 v165, 0xffff0000, v189
	v_max_f32_e32 v165, v165, v165
	v_max_f32_e32 v165, 0x358637bd, v165
	v_rcp_f32_e32 v175, v165
	v_pk_mul_f32 v[74:75], v[74:75], v[172:173]
	v_lshlrev_b32_e32 v172, 16, v193
	v_and_b32_e32 v173, 0xffff0000, v193
	v_pk_mul_f32 v[172:173], v[174:175], v[172:173]
	s_waitcnt vmcnt(1)
	v_lshlrev_b32_e32 v165, 16, v142
	v_and_b32_e32 v142, 0xffff0000, v142
	v_pk_mul_f32 v[76:77], v[76:77], v[172:173]
	v_lshlrev_b32_e32 v172, 16, v138
	v_and_b32_e32 v173, 0xffff0000, v138
	v_lshlrev_b32_e32 v138, 16, v143
	v_max_f32_e32 v142, v142, v142
	v_max_f32_e32 v138, v138, v138
	v_max_f32_e32 v142, 0x358637bd, v142
	v_max_f32_e32 v138, 0x358637bd, v138
	v_rcp_f32_e32 v175, v142
	v_rcp_f32_e32 v142, v138
	v_and_b32_e32 v138, 0xffff0000, v143
	v_max_f32_e32 v138, v138, v138
	v_max_f32_e32 v138, 0x358637bd, v138
	v_rcp_f32_e32 v143, v138
	v_lshlrev_b32_e32 v138, 16, v139
	v_and_b32_e32 v139, 0xffff0000, v139
	v_max_f32_e32 v165, v165, v165
	v_pk_mul_f32 v[138:139], v[142:143], v[138:139]
	v_lshlrev_b32_e32 v142, 16, v144
	v_and_b32_e32 v143, 0xffff0000, v144
	v_max_f32_e32 v142, v142, v142
	v_max_f32_e32 v143, v143, v143
	v_max_f32_e32 v142, 0x358637bd, v142
	v_max_f32_e32 v143, 0x358637bd, v143
	v_max_f32_e32 v165, 0x358637bd, v165
	v_rcp_f32_e32 v142, v142
	v_rcp_f32_e32 v143, v143
	v_rcp_f32_e32 v174, v165
	v_pk_mul_f32 v[104:105], v[104:105], v[138:139]
	v_lshlrev_b32_e32 v138, 16, v140
	v_and_b32_e32 v139, 0xffff0000, v140
	v_pk_mul_f32 v[138:139], v[142:143], v[138:139]
	v_mad_i64_i32 v[142:143], s[0:1], v170, s67, v[176:177]
	v_pk_mul_f32 v[172:173], v[174:175], v[172:173]
	v_add_co_u32_e32 v174, vcc, s68, v142
	v_pk_mul_f32 v[102:103], v[102:103], v[172:173]
	s_nop 0
	v_addc_co_u32_e32 v175, vcc, 0, v143, vcc
	global_load_dwordx4 v[170:173], v[174:175], off nt
	global_load_dwordx4 v[182:185], v[174:175], off offset:256 nt
	v_add_co_u32_e32 v142, vcc, s69, v142
	v_lshlrev_b32_e32 v140, 16, v145
	s_nop 0
	v_addc_co_u32_e32 v143, vcc, 0, v143, vcc
	global_load_dwordx4 v[178:181], v[142:143], off nt
	global_load_dwordx4 v[186:189], v[142:143], off offset:256 nt
	v_max_f32_e32 v140, v140, v140
	v_max_f32_e32 v140, 0x358637bd, v140
	v_rcp_f32_e32 v144, v140
	v_and_b32_e32 v140, 0xffff0000, v145
	v_max_f32_e32 v140, v140, v140
	v_max_f32_e32 v140, 0x358637bd, v140
	v_rcp_f32_e32 v145, v140
	v_pk_mul_f32 v[98:99], v[98:99], v[138:139]
	v_lshlrev_b32_e32 v138, 16, v141
	v_and_b32_e32 v139, 0xffff0000, v141
	v_pk_mul_f32 v[138:139], v[144:145], v[138:139]
	s_waitcnt vmcnt(4)
	v_lshlrev_b32_e32 v140, 16, v134
	v_and_b32_e32 v134, 0xffff0000, v134
	v_pk_mul_f32 v[100:101], v[100:101], v[138:139]
	v_lshlrev_b32_e32 v138, 16, v130
	v_and_b32_e32 v139, 0xffff0000, v130
	v_lshlrev_b32_e32 v130, 16, v135
	v_max_f32_e32 v134, v134, v134
	v_max_f32_e32 v130, v130, v130
	v_max_f32_e32 v134, 0x358637bd, v134
	v_max_f32_e32 v130, 0x358637bd, v130
	v_rcp_f32_e32 v141, v134
	v_rcp_f32_e32 v134, v130
	v_and_b32_e32 v130, 0xffff0000, v135
	v_max_f32_e32 v130, v130, v130
	v_max_f32_e32 v130, 0x358637bd, v130
	v_rcp_f32_e32 v135, v130
	v_lshlrev_b32_e32 v130, 16, v131
	v_and_b32_e32 v131, 0xffff0000, v131
	v_max_f32_e32 v140, v140, v140
	v_pk_mul_f32 v[130:131], v[134:135], v[130:131]
	v_lshlrev_b32_e32 v134, 16, v136
	v_and_b32_e32 v135, 0xffff0000, v136
	v_max_f32_e32 v134, v134, v134
	v_max_f32_e32 v135, v135, v135
	v_max_f32_e32 v134, 0x358637bd, v134
	v_max_f32_e32 v135, 0x358637bd, v135
	v_rcp_f32_e32 v134, v134
	v_rcp_f32_e32 v135, v135
	v_pk_mul_f32 v[72:73], v[72:73], v[130:131]
	v_lshlrev_b32_e32 v130, 16, v132
	v_and_b32_e32 v131, 0xffff0000, v132
	v_lshlrev_b32_e32 v132, 16, v137
	v_max_f32_e32 v132, v132, v132
	v_max_f32_e32 v132, 0x358637bd, v132
	v_pk_mul_f32 v[130:131], v[134:135], v[130:131]
	v_rcp_f32_e32 v134, v132
	v_and_b32_e32 v132, 0xffff0000, v137
	v_max_f32_e32 v132, v132, v132
	v_max_f32_e32 v132, 0x358637bd, v132
	v_rcp_f32_e32 v135, v132
	v_pk_mul_f32 v[66:67], v[66:67], v[130:131]
	v_lshlrev_b32_e32 v130, 16, v133
	v_and_b32_e32 v131, 0xffff0000, v133
	v_max_f32_e32 v140, 0x358637bd, v140
	v_pk_mul_f32 v[130:131], v[134:135], v[130:131]
	v_rcp_f32_e32 v140, v140
	v_pk_mul_f32 v[68:69], v[68:69], v[130:131]
	v_mad_i64_i32 v[130:131], s[0:1], v168, s67, v[176:177]
	v_add_co_u32_e32 v132, vcc, s69, v130
	v_pk_mul_f32 v[138:139], v[140:141], v[138:139]
	s_nop 0
	v_addc_co_u32_e32 v133, vcc, 0, v131, vcc
	v_add_co_u32_e32 v134, vcc, s68, v130
	v_pk_mul_f32 v[70:71], v[70:71], v[138:139]
	s_nop 0
	v_addc_co_u32_e32 v135, vcc, 0, v131, vcc
	global_load_dwordx4 v[138:141], v[132:133], off nt
	s_nop 0
	global_load_dwordx4 v[130:133], v[132:133], off offset:256 nt
	s_waitcnt vmcnt(5)
	v_lshlrev_b32_e32 v136, 16, v170
	v_max_f32_e32 v136, v136, v136
	v_max_f32_e32 v136, 0x358637bd, v136
	v_rcp_f32_e32 v168, v136
	v_and_b32_e32 v136, 0xffff0000, v170
	v_max_f32_e32 v136, v136, v136
	v_max_f32_e32 v136, 0x358637bd, v136
	v_rcp_f32_e32 v169, v136
	global_load_dwordx4 v[142:145], v[134:135], off nt
	s_nop 0
	global_load_dwordx4 v[134:137], v[134:135], off offset:256 nt
	v_lshlrev_b32_e32 v165, 16, v171
	v_max_f32_e32 v165, v165, v165
	v_max_f32_e32 v165, 0x358637bd, v165
	v_rcp_f32_e32 v170, v165
	v_and_b32_e32 v165, 0xffff0000, v171
	v_max_f32_e32 v165, v165, v165
	v_max_f32_e32 v165, 0x358637bd, v165
	v_rcp_f32_e32 v171, v165
	s_waitcnt vmcnt(5)
	v_lshlrev_b32_e32 v174, 16, v178
	v_and_b32_e32 v175, 0xffff0000, v178
	v_lshlrev_b32_e32 v165, 16, v172
	v_pk_mul_f32 v[168:169], v[168:169], v[174:175]
	v_max_f32_e32 v165, v165, v165
	v_pk_mul_f32 v[62:63], v[62:63], v[168:169]
	v_lshlrev_b32_e32 v168, 16, v179
	v_and_b32_e32 v169, 0xffff0000, v179
	v_max_f32_e32 v165, 0x358637bd, v165
	v_pk_mul_f32 v[168:169], v[170:171], v[168:169]
	v_rcp_f32_e32 v170, v165
	v_and_b32_e32 v165, 0xffff0000, v172
	v_max_f32_e32 v165, v165, v165
	v_max_f32_e32 v165, 0x358637bd, v165
	v_rcp_f32_e32 v171, v165
	v_lshlrev_b32_e32 v165, 16, v173
	v_max_f32_e32 v165, v165, v165
	v_pk_mul_f32 v[64:65], v[64:65], v[168:169]
	v_lshlrev_b32_e32 v168, 16, v180
	v_and_b32_e32 v169, 0xffff0000, v180
	v_max_f32_e32 v165, 0x358637bd, v165
	v_pk_mul_f32 v[168:169], v[170:171], v[168:169]
	v_rcp_f32_e32 v170, v165
	v_and_b32_e32 v165, 0xffff0000, v173
	v_max_f32_e32 v165, v165, v165
	v_max_f32_e32 v165, 0x358637bd, v165
	v_rcp_f32_e32 v171, v165
	v_lshlrev_b32_e32 v165, 16, v182
	v_max_f32_e32 v165, v165, v165
	v_pk_mul_f32 v[58:59], v[58:59], v[168:169]
	v_lshlrev_b32_e32 v168, 16, v181
	v_and_b32_e32 v169, 0xffff0000, v181
	v_max_f32_e32 v165, 0x358637bd, v165
	v_pk_mul_f32 v[168:169], v[170:171], v[168:169]
	v_rcp_f32_e32 v170, v165
	v_and_b32_e32 v165, 0xffff0000, v182
	v_max_f32_e32 v165, v165, v165
	v_max_f32_e32 v165, 0x358637bd, v165
	v_rcp_f32_e32 v171, v165
	v_lshlrev_b32_e32 v165, 16, v183
	v_max_f32_e32 v165, v165, v165
	v_pk_mul_f32 v[60:61], v[60:61], v[168:169]
	s_waitcnt vmcnt(4)
	v_lshlrev_b32_e32 v168, 16, v186
	v_and_b32_e32 v169, 0xffff0000, v186
	v_max_f32_e32 v165, 0x358637bd, v165
	v_pk_mul_f32 v[168:169], v[170:171], v[168:169]
	v_rcp_f32_e32 v170, v165
	v_and_b32_e32 v165, 0xffff0000, v183
	v_max_f32_e32 v165, v165, v165
	v_max_f32_e32 v165, 0x358637bd, v165
	v_rcp_f32_e32 v171, v165
	v_lshlrev_b32_e32 v165, 16, v184
	v_max_f32_e32 v165, v165, v165
	v_pk_mul_f32 v[30:31], v[30:31], v[168:169]
	v_lshlrev_b32_e32 v168, 16, v187
	v_and_b32_e32 v169, 0xffff0000, v187
	v_max_f32_e32 v165, 0x358637bd, v165
	v_pk_mul_f32 v[168:169], v[170:171], v[168:169]
	v_rcp_f32_e32 v170, v165
	v_and_b32_e32 v165, 0xffff0000, v184
	v_max_f32_e32 v165, v165, v165
	v_max_f32_e32 v165, 0x358637bd, v165
	v_rcp_f32_e32 v171, v165
	v_lshlrev_b32_e32 v165, 16, v185
	v_max_f32_e32 v165, v165, v165
	v_pk_mul_f32 v[32:33], v[32:33], v[168:169]
	v_lshlrev_b32_e32 v168, 16, v188
	v_and_b32_e32 v169, 0xffff0000, v188
	v_max_f32_e32 v165, 0x358637bd, v165
	v_pk_mul_f32 v[168:169], v[170:171], v[168:169]
	v_rcp_f32_e32 v170, v165
	v_and_b32_e32 v165, 0xffff0000, v185
	v_max_f32_e32 v165, v165, v165
	v_max_f32_e32 v165, 0x358637bd, v165
	v_rcp_f32_e32 v171, v165
	v_pk_mul_f32 v[26:27], v[26:27], v[168:169]
	v_lshlrev_b32_e32 v168, 16, v189
	v_and_b32_e32 v169, 0xffff0000, v189
	v_pk_mul_f32 v[168:169], v[170:171], v[168:169]
	s_waitcnt vmcnt(1)
	v_lshlrev_b32_e32 v165, 16, v142
	v_and_b32_e32 v142, 0xffff0000, v142
	v_pk_mul_f32 v[28:29], v[28:29], v[168:169]
	v_lshlrev_b32_e32 v168, 16, v138
	v_and_b32_e32 v169, 0xffff0000, v138
	v_lshlrev_b32_e32 v138, 16, v143
	v_max_f32_e32 v142, v142, v142
	v_max_f32_e32 v138, v138, v138
	v_max_f32_e32 v142, 0x358637bd, v142
	v_max_f32_e32 v138, 0x358637bd, v138
	v_rcp_f32_e32 v171, v142
	v_rcp_f32_e32 v142, v138
	v_and_b32_e32 v138, 0xffff0000, v143
	v_max_f32_e32 v138, v138, v138
	v_max_f32_e32 v138, 0x358637bd, v138
	v_rcp_f32_e32 v143, v138
	v_lshlrev_b32_e32 v138, 16, v139
	v_and_b32_e32 v139, 0xffff0000, v139
	v_max_f32_e32 v165, v165, v165
	v_pk_mul_f32 v[138:139], v[142:143], v[138:139]
	v_lshlrev_b32_e32 v142, 16, v144
	v_and_b32_e32 v143, 0xffff0000, v144
	v_max_f32_e32 v142, v142, v142
	v_max_f32_e32 v143, v143, v143
	v_max_f32_e32 v142, 0x358637bd, v142
	v_max_f32_e32 v143, 0x358637bd, v143
	v_max_f32_e32 v165, 0x358637bd, v165
	v_rcp_f32_e32 v142, v142
	v_rcp_f32_e32 v143, v143
	v_rcp_f32_e32 v170, v165
	v_pk_mul_f32 v[56:57], v[56:57], v[138:139]
	v_lshlrev_b32_e32 v138, 16, v140
	v_and_b32_e32 v139, 0xffff0000, v140
	v_pk_mul_f32 v[138:139], v[142:143], v[138:139]
	v_mad_i64_i32 v[142:143], s[0:1], v166, s67, v[176:177]
	v_pk_mul_f32 v[168:169], v[170:171], v[168:169]
	v_add_co_u32_e32 v170, vcc, s68, v142
	v_pk_mul_f32 v[54:55], v[54:55], v[168:169]
	s_nop 0
	v_addc_co_u32_e32 v171, vcc, 0, v143, vcc
	global_load_dwordx4 v[166:169], v[170:171], off nt
	v_lshlrev_b32_e32 v140, 16, v145
	v_max_f32_e32 v140, v140, v140
	v_add_co_u32_e32 v174, vcc, s69, v142
	v_max_f32_e32 v140, 0x358637bd, v140
	s_nop 0
	v_addc_co_u32_e32 v175, vcc, 0, v143, vcc
	v_rcp_f32_e32 v172, v140
	v_and_b32_e32 v140, 0xffff0000, v145
	global_load_dwordx4 v[142:145], v[174:175], off nt
	v_max_f32_e32 v140, v140, v140
	v_max_f32_e32 v140, 0x358637bd, v140
	v_rcp_f32_e32 v173, v140
	v_pk_mul_f32 v[50:51], v[50:51], v[138:139]
	v_lshlrev_b32_e32 v138, 16, v141
	v_and_b32_e32 v139, 0xffff0000, v141
	v_pk_mul_f32 v[138:139], v[172:173], v[138:139]
	s_waitcnt vmcnt(2)
	v_lshlrev_b32_e32 v140, 16, v134
	v_and_b32_e32 v134, 0xffff0000, v134
	v_pk_mul_f32 v[52:53], v[52:53], v[138:139]
	v_lshlrev_b32_e32 v138, 16, v130
	v_and_b32_e32 v139, 0xffff0000, v130
	v_lshlrev_b32_e32 v130, 16, v135
	v_max_f32_e32 v134, v134, v134
	v_max_f32_e32 v130, v130, v130
	v_max_f32_e32 v140, v140, v140
	v_max_f32_e32 v134, 0x358637bd, v134
	v_max_f32_e32 v130, 0x358637bd, v130
	v_max_f32_e32 v140, 0x358637bd, v140
	v_rcp_f32_e32 v141, v134
	v_rcp_f32_e32 v134, v130
	v_and_b32_e32 v130, 0xffff0000, v135
	v_rcp_f32_e32 v140, v140
	v_max_f32_e32 v130, v130, v130
	v_max_f32_e32 v130, 0x358637bd, v130
	v_rcp_f32_e32 v135, v130
	v_pk_mul_f32 v[138:139], v[140:141], v[138:139]
	v_lshlrev_b32_e32 v130, 16, v131
	v_pk_mul_f32 v[22:23], v[22:23], v[138:139]
	v_and_b32_e32 v131, 0xffff0000, v131
	global_load_dwordx4 v[138:141], v[170:171], off offset:256 nt
	v_pk_mul_f32 v[130:131], v[134:135], v[130:131]
	v_lshlrev_b32_e32 v134, 16, v136
	v_and_b32_e32 v135, 0xffff0000, v136
	v_max_f32_e32 v134, v134, v134
	v_max_f32_e32 v135, v135, v135
	v_max_f32_e32 v134, 0x358637bd, v134
	v_max_f32_e32 v135, 0x358637bd, v135
	v_rcp_f32_e32 v134, v134
	v_rcp_f32_e32 v135, v135
	v_pk_mul_f32 v[24:25], v[24:25], v[130:131]
	v_lshlrev_b32_e32 v130, 16, v132
	v_and_b32_e32 v131, 0xffff0000, v132
	v_lshlrev_b32_e32 v132, 16, v137
	v_max_f32_e32 v132, v132, v132
	v_max_f32_e32 v132, 0x358637bd, v132
	global_load_dwordx4 v[170:173], v[174:175], off offset:256 nt
	v_pk_mul_f32 v[130:131], v[134:135], v[130:131]
	v_rcp_f32_e32 v134, v132
	v_and_b32_e32 v132, 0xffff0000, v137
	v_max_f32_e32 v132, v132, v132
	v_max_f32_e32 v132, 0x358637bd, v132
	v_rcp_f32_e32 v135, v132
	v_pk_mul_f32 v[18:19], v[18:19], v[130:131]
	v_lshlrev_b32_e32 v130, 16, v133
	v_and_b32_e32 v131, 0xffff0000, v133
	v_pk_mul_f32 v[130:131], v[134:135], v[130:131]
	v_rcp_f32_e32 v204, v204
	v_pk_mul_f32 v[20:21], v[20:21], v[130:131]
	v_mad_i64_i32 v[130:131], s[0:1], v164, s67, v[176:177]
	v_add_co_u32_e32 v132, vcc, s69, v130
	v_rcp_f32_e32 v205, v205
	s_nop 0
	v_addc_co_u32_e32 v133, vcc, 0, v131, vcc
	v_add_co_u32_e32 v134, vcc, s68, v130
	v_pk_mul_f32 v[194:195], v[204:205], v[198:199]
	s_waitcnt vmcnt(3)
	v_lshlrev_b32_e32 v136, 16, v166
	v_max_f32_e32 v136, v136, v136
	v_max_f32_e32 v136, 0x358637bd, v136
	v_rcp_f32_e32 v164, v136
	v_and_b32_e32 v136, 0xffff0000, v166
	v_max_f32_e32 v136, v136, v136
	v_addc_co_u32_e32 v135, vcc, 0, v131, vcc
	v_max_f32_e32 v136, 0x358637bd, v136
	global_load_dwordx4 v[174:177], v[132:133], off nt
	s_nop 0
	global_load_dwordx4 v[130:133], v[132:133], off offset:256 nt
	v_rcp_f32_e32 v165, v136
	global_load_dwordx4 v[178:181], v[134:135], off nt
	s_nop 0
	global_load_dwordx4 v[134:137], v[134:135], off offset:256 nt
	s_waitcnt vmcnt(6)
	v_lshlrev_b32_e32 v182, 16, v142
	v_and_b32_e32 v183, 0xffff0000, v142
	v_lshlrev_b32_e32 v142, 16, v167
	v_max_f32_e32 v142, v142, v142
	v_max_f32_e32 v142, 0x358637bd, v142
	v_rcp_f32_e32 v166, v142
	v_and_b32_e32 v142, 0xffff0000, v167
	v_max_f32_e32 v142, v142, v142
	v_max_f32_e32 v142, 0x358637bd, v142
	v_pk_mul_f32 v[164:165], v[164:165], v[182:183]
	v_rcp_f32_e32 v167, v142
	v_pk_mul_f32 v[46:47], v[46:47], v[164:165]
	v_lshlrev_b32_e32 v164, 16, v168
	v_and_b32_e32 v165, 0xffff0000, v168
	v_max_f32_e32 v164, v164, v164
	v_max_f32_e32 v165, v165, v165
	v_lshlrev_b32_e32 v142, 16, v143
	v_and_b32_e32 v143, 0xffff0000, v143
	v_max_f32_e32 v164, 0x358637bd, v164
	v_max_f32_e32 v165, 0x358637bd, v165
	v_pk_mul_f32 v[142:143], v[166:167], v[142:143]
	v_rcp_f32_e32 v164, v164
	v_rcp_f32_e32 v165, v165
	v_pk_mul_f32 v[48:49], v[48:49], v[142:143]
	v_lshlrev_b32_e32 v142, 16, v144
	v_and_b32_e32 v143, 0xffff0000, v144
	v_lshlrev_b32_e32 v144, 16, v169
	v_max_f32_e32 v144, v144, v144
	v_max_f32_e32 v144, 0x358637bd, v144
	v_pk_mul_f32 v[142:143], v[164:165], v[142:143]
	v_rcp_f32_e32 v164, v144
	v_and_b32_e32 v144, 0xffff0000, v169
	v_max_f32_e32 v144, v144, v144
	v_max_f32_e32 v144, 0x358637bd, v144
	v_rcp_f32_e32 v165, v144
	s_waitcnt vmcnt(5)
	v_lshlrev_b32_e32 v144, 16, v138
	v_and_b32_e32 v138, 0xffff0000, v138
	v_max_f32_e32 v138, v138, v138
	v_max_f32_e32 v144, v144, v144
	v_max_f32_e32 v138, 0x358637bd, v138
	v_pk_mul_f32 v[42:43], v[42:43], v[142:143]
	v_lshlrev_b32_e32 v142, 16, v145
	v_and_b32_e32 v143, 0xffff0000, v145
	v_max_f32_e32 v144, 0x358637bd, v144
	v_rcp_f32_e32 v145, v138
	v_lshlrev_b32_e32 v138, 16, v139
	v_and_b32_e32 v139, 0xffff0000, v139
	v_rcp_f32_e32 v144, v144
	v_max_f32_e32 v138, v138, v138
	v_max_f32_e32 v139, v139, v139
	v_max_f32_e32 v138, 0x358637bd, v138
	v_max_f32_e32 v139, 0x358637bd, v139
	v_pk_mul_f32 v[142:143], v[164:165], v[142:143]
	v_rcp_f32_e32 v138, v138
	v_rcp_f32_e32 v139, v139
	v_pk_mul_f32 v[44:45], v[44:45], v[142:143]
	s_waitcnt vmcnt(4)
	v_lshlrev_b32_e32 v142, 16, v170
	v_and_b32_e32 v143, 0xffff0000, v170
	v_pk_mul_f32 v[142:143], v[144:145], v[142:143]
	v_pk_mul_f32 v[94:95], v[94:95], v[194:195]
	v_pk_mul_f32 v[14:15], v[14:15], v[142:143]
	v_lshlrev_b32_e32 v142, 16, v171
	v_and_b32_e32 v143, 0xffff0000, v171
	v_pk_mul_f32 v[138:139], v[138:139], v[142:143]
	v_lshlrev_b32_e32 v142, 16, v140
	v_and_b32_e32 v140, 0xffff0000, v140
	v_max_f32_e32 v140, v140, v140
	v_max_f32_e32 v142, v142, v142
	v_max_f32_e32 v140, 0x358637bd, v140
	v_max_f32_e32 v142, 0x358637bd, v142
	v_rcp_f32_e32 v143, v140
	v_lshlrev_b32_e32 v140, 16, v141
	v_and_b32_e32 v141, 0xffff0000, v141
	v_rcp_f32_e32 v142, v142
	v_max_f32_e32 v140, v140, v140
	v_max_f32_e32 v141, v141, v141
	v_max_f32_e32 v140, 0x358637bd, v140
	v_max_f32_e32 v141, 0x358637bd, v141
	v_rcp_f32_e32 v140, v140
	v_rcp_f32_e32 v141, v141
	v_pk_mul_f32 v[16:17], v[16:17], v[138:139]
	v_lshlrev_b32_e32 v138, 16, v172
	v_and_b32_e32 v139, 0xffff0000, v172
	v_pk_mul_f32 v[138:139], v[142:143], v[138:139]
	s_nop 0
	v_pk_mul_f32 v[10:11], v[10:11], v[138:139]
	v_lshlrev_b32_e32 v138, 16, v173
	v_and_b32_e32 v139, 0xffff0000, v173
	v_pk_mul_f32 v[138:139], v[140:141], v[138:139]
	s_waitcnt vmcnt(1)
	v_lshlrev_b32_e32 v140, 16, v178
	v_and_b32_e32 v141, 0xffff0000, v178
	v_max_f32_e32 v140, v140, v140
	v_max_f32_e32 v141, v141, v141
	v_max_f32_e32 v140, 0x358637bd, v140
	v_max_f32_e32 v141, 0x358637bd, v141
	v_rcp_f32_e32 v140, v140
	v_rcp_f32_e32 v141, v141
	v_pk_mul_f32 v[12:13], v[12:13], v[138:139]
	v_lshlrev_b32_e32 v138, 16, v174
	v_and_b32_e32 v139, 0xffff0000, v174
	v_pk_mul_f32 v[138:139], v[140:141], v[138:139]
	v_lshlrev_b32_e32 v140, 16, v179
	v_and_b32_e32 v141, 0xffff0000, v179
	v_max_f32_e32 v140, v140, v140
	v_max_f32_e32 v141, v141, v141
	v_max_f32_e32 v140, 0x358637bd, v140
	v_max_f32_e32 v141, 0x358637bd, v141
	v_rcp_f32_e32 v140, v140
	v_rcp_f32_e32 v141, v141
	v_pk_mul_f32 v[38:39], v[38:39], v[138:139]
	v_lshlrev_b32_e32 v138, 16, v175
	v_and_b32_e32 v139, 0xffff0000, v175
	v_pk_mul_f32 v[138:139], v[140:141], v[138:139]
	v_lshlrev_b32_e32 v140, 16, v180
	v_and_b32_e32 v141, 0xffff0000, v180
	v_max_f32_e32 v140, v140, v140
	v_max_f32_e32 v141, v141, v141
	v_max_f32_e32 v140, 0x358637bd, v140
	v_max_f32_e32 v141, 0x358637bd, v141
	v_rcp_f32_e32 v140, v140
	v_rcp_f32_e32 v141, v141
	v_pk_mul_f32 v[40:41], v[40:41], v[138:139]
	v_lshlrev_b32_e32 v138, 16, v176
	v_and_b32_e32 v139, 0xffff0000, v176
	v_pk_mul_f32 v[138:139], v[140:141], v[138:139]
	v_lshlrev_b32_e32 v140, 16, v181
	v_and_b32_e32 v141, 0xffff0000, v181
	v_max_f32_e32 v140, v140, v140
	v_max_f32_e32 v141, v141, v141
	v_max_f32_e32 v140, 0x358637bd, v140
	v_max_f32_e32 v141, 0x358637bd, v141
	v_rcp_f32_e32 v140, v140
	v_rcp_f32_e32 v141, v141
	v_pk_mul_f32 v[34:35], v[34:35], v[138:139]
	v_lshlrev_b32_e32 v138, 16, v177
	v_and_b32_e32 v139, 0xffff0000, v177
	v_pk_mul_f32 v[138:139], v[140:141], v[138:139]
	s_waitcnt vmcnt(0)
	v_lshlrev_b32_e32 v140, 16, v134
	v_and_b32_e32 v134, 0xffff0000, v134
	v_pk_mul_f32 v[36:37], v[36:37], v[138:139]
	v_lshlrev_b32_e32 v138, 16, v130
	v_and_b32_e32 v139, 0xffff0000, v130
	v_lshlrev_b32_e32 v130, 16, v135
	v_max_f32_e32 v134, v134, v134
	v_max_f32_e32 v130, v130, v130
	v_max_f32_e32 v134, 0x358637bd, v134
	v_max_f32_e32 v130, 0x358637bd, v130
	v_rcp_f32_e32 v141, v134
	v_rcp_f32_e32 v134, v130
	v_and_b32_e32 v130, 0xffff0000, v135
	v_max_f32_e32 v130, v130, v130
	v_max_f32_e32 v130, 0x358637bd, v130
	v_rcp_f32_e32 v135, v130
	v_lshlrev_b32_e32 v130, 16, v131
	v_and_b32_e32 v131, 0xffff0000, v131
	v_max_f32_e32 v140, v140, v140
	v_pk_mul_f32 v[130:131], v[134:135], v[130:131]
	v_lshlrev_b32_e32 v134, 16, v136
	v_and_b32_e32 v135, 0xffff0000, v136
	v_max_f32_e32 v134, v134, v134
	v_max_f32_e32 v135, v135, v135
	v_max_f32_e32 v134, 0x358637bd, v134
	v_max_f32_e32 v135, 0x358637bd, v135
	v_rcp_f32_e32 v134, v134
	v_rcp_f32_e32 v135, v135
	v_pk_mul_f32 v[8:9], v[8:9], v[130:131]
	v_lshlrev_b32_e32 v130, 16, v132
	v_and_b32_e32 v131, 0xffff0000, v132
	v_lshlrev_b32_e32 v132, 16, v137
	v_max_f32_e32 v132, v132, v132
	v_max_f32_e32 v132, 0x358637bd, v132
	v_pk_mul_f32 v[130:131], v[134:135], v[130:131]
	v_rcp_f32_e32 v134, v132
	v_and_b32_e32 v132, 0xffff0000, v137
	v_max_f32_e32 v132, v132, v132
	v_max_f32_e32 v140, 0x358637bd, v140
	v_max_f32_e32 v132, 0x358637bd, v132
	v_rcp_f32_e32 v140, v140
	v_rcp_f32_e32 v135, v132
	v_pk_mul_f32 v[2:3], v[2:3], v[130:131]
	v_lshlrev_b32_e32 v130, 16, v133
	v_and_b32_e32 v131, 0xffff0000, v133
	v_pk_mul_f32 v[138:139], v[140:141], v[138:139]
	v_pk_mul_f32 v[130:131], v[134:135], v[130:131]
	v_pk_mul_f32 v[6:7], v[6:7], v[138:139]
	v_pk_mul_f32 v[4:5], v[4:5], v[130:131]

.LBB0_1343:
	s_or_b64 exec, exec, s[0:1]
	s_ashr_i32 s25, s24, 31
	s_lshl_b64 s[0:1], s[24:25], 13
	v_lshl_add_u64 v[12:13], v[6:7], 0, s[0:1]
	global_load_dwordx2 v[38:39], v[12:13], off nt
	global_load_dwordx2 v[40:41], v[12:13], off offset:512 nt
	global_load_dwordx2 v[42:43], v[12:13], off offset:1024 nt
	global_load_dwordx2 v[44:45], v[12:13], off offset:1536 nt
	global_load_dwordx2 v[46:47], v[12:13], off offset:2048 nt
	global_load_dwordx2 v[68:69], v[12:13], off offset:2560 nt
	global_load_dwordx2 v[70:71], v[12:13], off offset:3072 nt
	v_lshl_add_u64 v[14:15], v[4:5], 0, s[0:1]
	global_load_dwordx2 v[22:23], v[12:13], off offset:3584 nt
	global_load_dwordx2 v[72:73], v[14:15], off
	global_load_dwordx2 v[74:75], v[14:15], off offset:512
	global_load_dwordx2 v[76:77], v[14:15], off offset:1024
	global_load_dwordx2 v[78:79], v[14:15], off offset:1536
	global_load_dwordx2 v[80:81], v[14:15], off offset:2048
	global_load_dwordx2 v[82:83], v[14:15], off offset:2560
	global_load_dwordx2 v[84:85], v[14:15], off offset:3072
	global_load_dwordx2 v[86:87], v[14:15], off offset:3584
	v_add_co_u32_e64 v12, s[8:9], s45, v12
	v_add_co_u32_e32 v48, vcc, 0x1000, v14
	s_nop 0
	v_addc_co_u32_e64 v13, s[8:9], 0, v13, s[8:9]
	v_addc_co_u32_e32 v49, vcc, 0, v15, vcc
	global_load_dwordx2 v[28:29], v[12:13], off nt
	global_load_dwordx2 v[26:27], v[12:13], off offset:512 nt
	global_load_dwordx2 v[24:25], v[12:13], off offset:1024 nt
	global_load_dwordx2 v[20:21], v[12:13], off offset:1536 nt
	global_load_dwordx2 v[18:19], v[12:13], off offset:2048 nt
	global_load_dwordx2 v[16:17], v[12:13], off offset:2560 nt
	global_load_dwordx2 v[14:15], v[12:13], off offset:3072 nt
	s_nop 0
	global_load_dwordx2 v[12:13], v[12:13], off offset:3584 nt
	s_nop 0
	global_load_dwordx2 v[88:89], v[48:49], off
	global_load_dwordx2 v[90:91], v[48:49], off offset:512
	global_load_dwordx2 v[92:93], v[48:49], off offset:1024
	global_load_dwordx2 v[94:95], v[48:49], off offset:1536
	global_load_dwordx2 v[96:97], v[48:49], off offset:2048
	global_load_dwordx2 v[98:99], v[48:49], off offset:2560
	global_load_dwordx2 v[100:101], v[48:49], off offset:3072
	global_load_dwordx2 v[102:103], v[48:49], off offset:3584
	s_waitcnt vmcnt(31)
	v_lshlrev_b32_e32 v66, 16, v38
	s_waitcnt vmcnt(23)
	v_and_b32_e32 v105, 0xffff0000, v72
	v_and_b32_e32 v107, 0xffff0000, v73
	v_lshlrev_b32_e32 v52, 16, v45
	v_and_b32_e32 v51, 0xffff0000, v45
	v_lshlrev_b32_e32 v48, 16, v46
	v_and_b32_e32 v49, 0xffff0000, v46
	v_lshlrev_b32_e32 v46, 16, v68
	v_and_b32_e32 v45, 0xffff0000, v68
	v_lshlrev_b32_e32 v104, 16, v72
	v_lshlrev_b32_e32 v106, 16, v73
	v_mul_f32_e32 v67, v105, v105
	v_mul_f32_e32 v68, v107, v107
	s_waitcnt vmcnt(22)
	v_and_b32_e32 v109, 0xffff0000, v74
	v_and_b32_e32 v111, 0xffff0000, v75
	v_fmac_f32_e32 v67, v104, v104
	v_fmac_f32_e32 v68, v106, v106
	v_lshlrev_b32_e32 v56, 16, v43
	v_and_b32_e32 v55, 0xffff0000, v43
	v_lshlrev_b32_e32 v54, 16, v44
	v_and_b32_e32 v53, 0xffff0000, v44
	v_lshlrev_b32_e32 v44, 16, v69
	v_and_b32_e32 v43, 0xffff0000, v69
	v_lshlrev_b32_e32 v108, 16, v74
	v_lshlrev_b32_e32 v110, 16, v75
	v_add_f32_e32 v67, v67, v68
	v_mul_f32_e32 v68, v109, v109
	v_mul_f32_e32 v69, v111, v111
	v_fmac_f32_e32 v68, v108, v108
	v_fmac_f32_e32 v69, v110, v110
	v_add_f32_e32 v68, v68, v69
	s_waitcnt vmcnt(21)
	v_and_b32_e32 v113, 0xffff0000, v76
	v_and_b32_e32 v115, 0xffff0000, v77
	v_add_f32_e32 v67, v67, v68
	v_lshlrev_b32_e32 v112, 16, v76
	v_lshlrev_b32_e32 v114, 16, v77
	v_mul_f32_e32 v68, v113, v113
	v_mul_f32_e32 v69, v115, v115
	v_fmac_f32_e32 v68, v112, v112
	v_fmac_f32_e32 v69, v114, v114
	v_add_f32_e32 v68, v68, v69
	s_waitcnt vmcnt(20)
	v_and_b32_e32 v117, 0xffff0000, v78
	v_and_b32_e32 v119, 0xffff0000, v79
	v_add_f32_e32 v67, v67, v68
	v_lshlrev_b32_e32 v116, 16, v78
	v_lshlrev_b32_e32 v118, 16, v79
	v_mul_f32_e32 v68, v117, v117
	v_mul_f32_e32 v69, v119, v119
	v_fmac_f32_e32 v68, v116, v116
	v_fmac_f32_e32 v69, v118, v118
	v_add_f32_e32 v68, v68, v69
	s_waitcnt vmcnt(19)
	v_and_b32_e32 v121, 0xffff0000, v80
	v_and_b32_e32 v123, 0xffff0000, v81
	v_add_f32_e32 v67, v67, v68
	v_lshlrev_b32_e32 v120, 16, v80
	v_lshlrev_b32_e32 v122, 16, v81
	v_mul_f32_e32 v68, v121, v121
	v_mul_f32_e32 v69, v123, v123
	v_fmac_f32_e32 v68, v120, v120
	v_fmac_f32_e32 v69, v122, v122
	v_add_f32_e32 v68, v68, v69
	s_waitcnt vmcnt(18)
	v_and_b32_e32 v125, 0xffff0000, v82
	v_and_b32_e32 v127, 0xffff0000, v83
	v_add_f32_e32 v67, v67, v68
	v_lshlrev_b32_e32 v124, 16, v82
	v_lshlrev_b32_e32 v126, 16, v83
	v_mul_f32_e32 v68, v125, v125
	v_mul_f32_e32 v69, v127, v127
	v_fmac_f32_e32 v68, v124, v124
	v_fmac_f32_e32 v69, v126, v126
	v_add_f32_e32 v68, v68, v69
	s_waitcnt vmcnt(17)
	v_and_b32_e32 v129, 0xffff0000, v84
	v_and_b32_e32 v131, 0xffff0000, v85
	v_add_f32_e32 v67, v67, v68
	v_lshlrev_b32_e32 v128, 16, v84
	v_lshlrev_b32_e32 v130, 16, v85
	v_mul_f32_e32 v68, v129, v129
	v_mul_f32_e32 v69, v131, v131
	v_fmac_f32_e32 v68, v128, v128
	v_fmac_f32_e32 v69, v130, v130
	v_add_f32_e32 v68, v68, v69
	s_waitcnt vmcnt(16)
	v_and_b32_e32 v133, 0xffff0000, v86
	v_and_b32_e32 v135, 0xffff0000, v87
	v_add_f32_e32 v67, v67, v68
	v_lshlrev_b32_e32 v132, 16, v86
	v_lshlrev_b32_e32 v134, 16, v87
	v_mul_f32_e32 v68, v133, v133
	v_mul_f32_e32 v69, v135, v135
	v_fmac_f32_e32 v68, v132, v132
	v_fmac_f32_e32 v69, v134, v134
	v_add_f32_e32 v68, v68, v69
	s_waitcnt vmcnt(7)
	v_and_b32_e32 v137, 0xffff0000, v88
	v_and_b32_e32 v139, 0xffff0000, v89
	v_add_f32_e32 v67, v67, v68
	v_lshlrev_b32_e32 v136, 16, v88
	v_lshlrev_b32_e32 v138, 16, v89
	v_mul_f32_e32 v68, v137, v137
	v_mul_f32_e32 v69, v139, v139
	v_fmac_f32_e32 v68, v136, v136
	v_fmac_f32_e32 v69, v138, v138
	v_add_f32_e32 v68, v68, v69
	s_waitcnt vmcnt(6)
	v_and_b32_e32 v141, 0xffff0000, v90
	v_and_b32_e32 v143, 0xffff0000, v91
	v_add_f32_e32 v67, v67, v68
	v_lshlrev_b32_e32 v140, 16, v90
	v_lshlrev_b32_e32 v142, 16, v91
	v_mul_f32_e32 v68, v141, v141
	v_mul_f32_e32 v69, v143, v143
	v_fmac_f32_e32 v68, v140, v140
	v_fmac_f32_e32 v69, v142, v142
	v_add_f32_e32 v68, v68, v69
	s_waitcnt vmcnt(5)
	v_lshlrev_b32_e32 v144, 16, v92
	v_and_b32_e32 v92, 0xffff0000, v92
	v_lshlrev_b32_e32 v145, 16, v93
	v_and_b32_e32 v93, 0xffff0000, v93
	v_add_f32_e32 v67, v67, v68
	v_mul_f32_e32 v68, v92, v92
	v_mul_f32_e32 v69, v93, v93
	v_fmac_f32_e32 v68, v144, v144
	v_fmac_f32_e32 v69, v145, v145
	v_add_f32_e32 v68, v68, v69
	s_waitcnt vmcnt(4)
	v_lshlrev_b32_e32 v147, 16, v94
	v_and_b32_e32 v94, 0xffff0000, v94
	v_lshlrev_b32_e32 v148, 16, v95
	v_and_b32_e32 v95, 0xffff0000, v95
	v_add_f32_e32 v67, v67, v68
	v_mul_f32_e32 v68, v94, v94
	v_mul_f32_e32 v69, v95, v95
	v_fmac_f32_e32 v68, v147, v147
	v_fmac_f32_e32 v69, v148, v148
	v_add_f32_e32 v68, v68, v69
	s_waitcnt vmcnt(3)
	v_lshlrev_b32_e32 v149, 16, v96
	v_and_b32_e32 v96, 0xffff0000, v96
	v_lshlrev_b32_e32 v150, 16, v97
	v_and_b32_e32 v97, 0xffff0000, v97
	v_add_f32_e32 v67, v67, v68
	v_mul_f32_e32 v68, v96, v96
	v_mul_f32_e32 v69, v97, v97
	v_fmac_f32_e32 v68, v149, v149
	v_fmac_f32_e32 v69, v150, v150
	v_add_f32_e32 v68, v68, v69
	s_waitcnt vmcnt(2)
	v_lshlrev_b32_e32 v151, 16, v98
	v_and_b32_e32 v98, 0xffff0000, v98
	v_lshlrev_b32_e32 v152, 16, v99
	v_and_b32_e32 v99, 0xffff0000, v99
	v_add_f32_e32 v67, v67, v68
	v_mul_f32_e32 v68, v98, v98
	v_mul_f32_e32 v69, v99, v99
	v_fmac_f32_e32 v68, v151, v151
	v_fmac_f32_e32 v69, v152, v152
	v_add_f32_e32 v68, v68, v69
	s_waitcnt vmcnt(1)
	v_lshlrev_b32_e32 v153, 16, v100
	v_and_b32_e32 v100, 0xffff0000, v100
	v_lshlrev_b32_e32 v154, 16, v101
	v_and_b32_e32 v101, 0xffff0000, v101
	v_add_f32_e32 v67, v67, v68
	v_mul_f32_e32 v68, v100, v100
	v_mul_f32_e32 v69, v101, v101
	v_fmac_f32_e32 v68, v153, v153
	v_fmac_f32_e32 v69, v154, v154
	v_add_f32_e32 v68, v68, v69
	s_waitcnt vmcnt(0)
	v_lshlrev_b32_e32 v155, 16, v102
	v_and_b32_e32 v102, 0xffff0000, v102
	v_lshlrev_b32_e32 v156, 16, v103
	v_and_b32_e32 v103, 0xffff0000, v103
	v_add_f32_e32 v67, v67, v68
	v_mul_f32_e32 v68, v102, v102
	v_mul_f32_e32 v69, v103, v103
	v_fmac_f32_e32 v68, v155, v155
	v_fmac_f32_e32 v69, v156, v156
	v_add_f32_e32 v68, v68, v69
	v_add_f32_e32 v67, v67, v68
	ds_bpermute_b32 v68, v1, v67
	v_and_b32_e32 v65, 0xffff0000, v38
	v_lshlrev_b32_e32 v38, 16, v22
	v_and_b32_e32 v81, 0xffff0000, v22
	v_lshlrev_b32_e32 v80, 16, v23
	s_waitcnt lgkmcnt(0)
	v_add_f32_e32 v22, v67, v68
	v_and_b32_e32 v79, 0xffff0000, v23
	ds_bpermute_b32 v23, v30, v22
	v_lshlrev_b32_e32 v73, 16, v28
	v_and_b32_e32 v77, 0xffff0000, v28
	v_lshlrev_b32_e32 v74, 16, v26
	v_and_b32_e32 v76, 0xffff0000, v26
	s_waitcnt lgkmcnt(0)
	v_add_f32_e32 v22, v22, v23
	ds_bpermute_b32 v23, v31, v22
	v_lshlrev_b32_e32 v28, 16, v21
	v_and_b32_e32 v26, 0xffff0000, v21
	v_lshlrev_b32_e32 v60, 16, v41
	v_and_b32_e32 v59, 0xffff0000, v41
	s_waitcnt lgkmcnt(0)
	v_add_f32_e32 v22, v22, v23
	ds_bpermute_b32 v23, v32, v22
	v_lshlrev_b32_e32 v58, 16, v42
	v_and_b32_e32 v57, 0xffff0000, v42
	v_lshlrev_b32_e32 v42, 16, v70
	v_and_b32_e32 v41, 0xffff0000, v70
	s_waitcnt lgkmcnt(0)
	v_add_f32_e32 v22, v22, v23
	ds_bpermute_b32 v23, v33, v22
	v_lshlrev_b32_e32 v68, 16, v24
	v_and_b32_e32 v70, 0xffff0000, v24
	v_lshlrev_b32_e32 v64, 16, v39
	v_and_b32_e32 v63, 0xffff0000, v39
	s_waitcnt lgkmcnt(0)
	v_add_f32_e32 v21, v22, v23
	ds_bpermute_b32 v24, v34, v21
	v_lshlrev_b32_e32 v62, 16, v40
	v_and_b32_e32 v61, 0xffff0000, v40
	v_lshlrev_b32_e32 v40, 16, v71
	v_and_b32_e32 v39, 0xffff0000, v71
	s_waitcnt lgkmcnt(0)
	v_add_f32_e32 v21, v21, v24
	v_fmamk_f32 v21, v21, 0x39800000, v2
	v_mul_f32_e32 v24, 0x4f800000, v21
	v_cmp_gt_f32_e32 vcc, s46, v21
	v_lshlrev_b32_e32 v78, 16, v29
	v_and_b32_e32 v75, 0xffff0000, v29
	v_cndmask_b32_e32 v24, v21, v24, vcc
	v_sqrt_f32_e32 v82, v24
	v_lshlrev_b32_e32 v72, 16, v27
	v_and_b32_e32 v71, 0xffff0000, v27
	v_lshlrev_b32_e32 v69, 16, v25
	v_and_b32_e32 v29, 0xffff0000, v25
	v_lshlrev_b32_e32 v27, 16, v20
	v_and_b32_e32 v67, 0xffff0000, v20
	v_lshlrev_b32_e32 v20, 16, v18
	v_and_b32_e32 v22, 0xffff0000, v18
	v_lshlrev_b32_e32 v18, 16, v16
	v_and_b32_e32 v25, 0xffff0000, v16
	v_lshlrev_b32_e32 v21, 16, v17
	v_and_b32_e32 v16, 0xffff0000, v17
	v_add_u32_e32 v17, -1, v82
	v_fma_f32 v83, -v17, v82, v24
	v_cmp_ge_f32_e64 s[8:9], 0, v83
	v_add_u32_e32 v83, 1, v82
	v_lshlrev_b32_e32 v50, 16, v47
	v_cndmask_b32_e64 v17, v82, v17, s[8:9]
	v_fma_f32 v82, -v83, v82, v24
	v_cmp_lt_f32_e64 s[8:9], 0, v82
	v_and_b32_e32 v47, 0xffff0000, v47
	v_lshlrev_b32_e32 v23, 16, v19
	v_cndmask_b32_e64 v17, v17, v83, s[8:9]
	v_mul_f32_e32 v82, 0x37800000, v17
	v_cndmask_b32_e32 v17, v17, v82, vcc
	v_cmp_class_f32_e32 vcc, v24, v36
	v_and_b32_e32 v19, 0xffff0000, v19
	s_nop 0
	v_cndmask_b32_e32 v86, v17, v24, vcc
	v_div_scale_f32 v82, s[8:9], v86, v86, 1.0
	v_rcp_f32_e32 v87, v82
	v_lshlrev_b32_e32 v24, 16, v14
	v_and_b32_e32 v17, 0xffff0000, v14
	v_lshlrev_b32_e32 v14, 16, v15
	v_fma_f32 v83, -v82, v87, 1.0
	v_fmac_f32_e32 v87, v83, v87
	v_div_scale_f32 v83, vcc, 1.0, v86, 1.0
	v_mul_f32_e32 v88, v83, v87
	v_fma_f32 v84, -v82, v88, v83
	v_fmac_f32_e32 v88, v84, v87
	v_fma_f32 v89, -v82, v88, v83
	ds_read_b128 v[82:85], v35
	v_div_fmas_f32 v87, v89, v87, v88
	v_div_fixup_f32 v157, v87, v86, 1.0
	v_mul_f32_e32 v86, v157, v104
	v_lshl_add_u64 v[88:89], v[8:9], 0, s[0:1]
	s_waitcnt lgkmcnt(0)
	v_fmac_f32_e32 v66, v82, v86
	v_mul_f32_e32 v82, v157, v105
	v_fmac_f32_e32 v65, v83, v82
	v_mul_f32_e32 v82, v157, v106
	v_fmac_f32_e32 v64, v84, v82
	v_mul_f32_e32 v82, v157, v107
	v_fmac_f32_e32 v63, v85, v82
	v_cvt_pk_bf16_f32 v86, v66, v65
	v_cvt_pk_bf16_f32 v87, v64, v63
	ds_read_b128 v[82:85], v35 offset:1024
	global_store_dwordx2 v[88:89], v[86:87], off
	v_mul_f32_e32 v86, v157, v108
	v_and_b32_e32 v15, 0xffff0000, v15
	s_waitcnt lgkmcnt(0)
	v_fmac_f32_e32 v62, v82, v86
	v_mul_f32_e32 v82, v157, v109
	v_fmac_f32_e32 v61, v83, v82
	v_mul_f32_e32 v82, v157, v110
	v_fmac_f32_e32 v60, v84, v82
	v_mul_f32_e32 v82, v157, v111
	v_fmac_f32_e32 v59, v85, v82
	v_cvt_pk_bf16_f32 v90, v62, v61
	v_cvt_pk_bf16_f32 v91, v60, v59
	ds_read_b128 v[84:87], v35 offset:2048
	v_mul_f32_e32 v83, v157, v112
	global_store_dwordx2 v[88:89], v[90:91], off offset:512
	v_lshlrev_b32_e32 v82, 16, v12
	v_and_b32_e32 v12, 0xffff0000, v12
	s_waitcnt lgkmcnt(0)
	v_fmac_f32_e32 v58, v83, v84
	v_mul_f32_e32 v83, v157, v113
	v_fmac_f32_e32 v57, v83, v85
	v_mul_f32_e32 v83, v157, v114
	v_fmac_f32_e32 v56, v83, v86
	v_mul_f32_e32 v83, v157, v115
	v_fmac_f32_e32 v55, v83, v87
	v_cvt_pk_bf16_f32 v90, v58, v57
	v_cvt_pk_bf16_f32 v91, v56, v55
	ds_read_b128 v[84:87], v35 offset:3072
	global_store_dwordx2 v[88:89], v[90:91], off offset:1024
	v_mul_f32_e32 v90, v157, v116
	v_lshlrev_b32_e32 v83, 16, v13
	v_and_b32_e32 v13, 0xffff0000, v13
	s_waitcnt lgkmcnt(0)
	v_fmac_f32_e32 v54, v90, v84
	v_mul_f32_e32 v84, v157, v117
	v_fmac_f32_e32 v53, v84, v85
	v_mul_f32_e32 v84, v157, v118
	v_fmac_f32_e32 v52, v84, v86
	v_mul_f32_e32 v84, v157, v119
	v_fmac_f32_e32 v51, v84, v87
	v_cvt_pk_bf16_f32 v84, v54, v53
	v_cvt_pk_bf16_f32 v85, v52, v51
	global_store_dwordx2 v[88:89], v[84:85], off offset:1536
	ds_read_b128 v[84:87], v35 offset:4096
	v_mul_f32_e32 v90, v157, v120
	v_mul_f32_e32 v91, v157, v121
	v_mul_f32_e32 v104, v157, v122
	s_waitcnt lgkmcnt(0)
	v_fmac_f32_e32 v48, v90, v84
	v_mul_f32_e32 v84, v157, v123
	v_fmac_f32_e32 v49, v91, v85
	v_fmac_f32_e32 v50, v104, v86
	v_fmac_f32_e32 v47, v84, v87
	v_cvt_pk_bf16_f32 v90, v48, v49
	v_cvt_pk_bf16_f32 v91, v50, v47
	ds_read_b128 v[84:87], v35 offset:5120
	global_store_dwordx2 v[88:89], v[90:91], off offset:2048
	v_mul_f32_e32 v90, v157, v124
	s_waitcnt lgkmcnt(0)
	v_fmac_f32_e32 v46, v90, v84
	v_mul_f32_e32 v84, v157, v125
	v_fmac_f32_e32 v45, v84, v85
	v_mul_f32_e32 v84, v157, v126
	v_fmac_f32_e32 v44, v84, v86
	v_mul_f32_e32 v84, v157, v127
	v_fmac_f32_e32 v43, v84, v87
	v_cvt_pk_bf16_f32 v90, v46, v45
	v_cvt_pk_bf16_f32 v91, v44, v43
	ds_read_b128 v[84:87], v35 offset:6144
	global_store_dwordx2 v[88:89], v[90:91], off offset:2560
	v_mul_f32_e32 v90, v157, v128
	s_waitcnt lgkmcnt(0)
	v_fmac_f32_e32 v42, v90, v84
	v_mul_f32_e32 v84, v157, v129
	v_fmac_f32_e32 v41, v84, v85
	v_mul_f32_e32 v84, v157, v130
	v_fmac_f32_e32 v40, v84, v86
	v_mul_f32_e32 v84, v157, v131
	v_fmac_f32_e32 v39, v84, v87
	v_cvt_pk_bf16_f32 v90, v42, v41
	v_cvt_pk_bf16_f32 v91, v40, v39
	ds_read_b128 v[84:87], v35 offset:7168
	global_store_dwordx2 v[88:89], v[90:91], off offset:3072
	v_mul_f32_e32 v90, v157, v132
	s_waitcnt lgkmcnt(0)
	v_fmac_f32_e32 v38, v90, v84
	v_mul_f32_e32 v84, v157, v133
	v_fmac_f32_e32 v81, v84, v85
	v_mul_f32_e32 v84, v157, v134
	v_fmac_f32_e32 v80, v84, v86
	v_mul_f32_e32 v84, v157, v135
	v_fmac_f32_e32 v79, v84, v87
	v_cvt_pk_bf16_f32 v84, v38, v81
	v_cvt_pk_bf16_f32 v85, v80, v79
	global_store_dwordx2 v[88:89], v[84:85], off offset:3584
	ds_read_b128 v[84:87], v35 offset:8192
	v_mul_f32_e32 v90, v157, v136
	v_mul_f32_e32 v91, v157, v137
	v_mul_f32_e32 v104, v157, v138
	v_add_co_u32_e32 v88, vcc, s45, v88
	s_waitcnt lgkmcnt(0)
	v_fmac_f32_e32 v73, v90, v84
	v_mul_f32_e32 v84, v157, v139
	v_fmac_f32_e32 v77, v91, v85
	v_fmac_f32_e32 v78, v104, v86
	v_fmac_f32_e32 v75, v84, v87
	v_cvt_pk_bf16_f32 v90, v73, v77
	v_cvt_pk_bf16_f32 v91, v78, v75
	ds_read_b128 v[84:87], v35 offset:9216
	v_addc_co_u32_e32 v89, vcc, 0, v89, vcc
	global_store_dwordx2 v[88:89], v[90:91], off
	v_mul_f32_e32 v90, v157, v140
	s_waitcnt lgkmcnt(0)
	v_fmac_f32_e32 v74, v90, v84
	v_mul_f32_e32 v84, v157, v141
	v_fmac_f32_e32 v76, v84, v85
	v_mul_f32_e32 v84, v157, v142
	v_fmac_f32_e32 v72, v84, v86
	v_mul_f32_e32 v84, v157, v143
	v_fmac_f32_e32 v71, v84, v87
	v_cvt_pk_bf16_f32 v90, v74, v76
	v_cvt_pk_bf16_f32 v91, v72, v71
	ds_read_b128 v[84:87], v35 offset:10240
	global_store_dwordx2 v[88:89], v[90:91], off offset:512
	v_mul_f32_e32 v90, v157, v144
	s_waitcnt lgkmcnt(0)
	v_fmac_f32_e32 v68, v90, v84
	v_mul_f32_e32 v84, v157, v92
	v_fmac_f32_e32 v70, v84, v85
	v_mul_f32_e32 v84, v157, v145
	v_fmac_f32_e32 v69, v84, v86
	v_mul_f32_e32 v84, v157, v93
	v_fmac_f32_e32 v29, v84, v87
	v_cvt_pk_bf16_f32 v90, v68, v70
	v_cvt_pk_bf16_f32 v91, v69, v29
	ds_read_b128 v[84:87], v35 offset:11264
	global_store_dwordx2 v[88:89], v[90:91], off offset:1024
	v_mul_f32_e32 v90, v157, v147
	s_waitcnt lgkmcnt(0)
	v_fmac_f32_e32 v27, v90, v84
	v_mul_f32_e32 v84, v157, v94
	v_fmac_f32_e32 v67, v84, v85
	v_mul_f32_e32 v84, v157, v148
	v_fmac_f32_e32 v28, v84, v86
	v_mul_f32_e32 v84, v157, v95
	v_fmac_f32_e32 v26, v84, v87
	v_cvt_pk_bf16_f32 v84, v27, v67
	v_cvt_pk_bf16_f32 v85, v28, v26
	global_store_dwordx2 v[88:89], v[84:85], off offset:1536
	ds_read_b128 v[84:87], v35 offset:12288
	v_mul_f32_e32 v90, v157, v149
	v_mul_f32_e32 v91, v157, v96
	v_mul_f32_e32 v92, v157, v150
	s_waitcnt lgkmcnt(0)
	v_fmac_f32_e32 v20, v90, v84
	v_mul_f32_e32 v84, v157, v97
	v_fmac_f32_e32 v22, v91, v85
	v_fmac_f32_e32 v23, v92, v86
	v_fmac_f32_e32 v19, v84, v87
	v_cvt_pk_bf16_f32 v90, v20, v22
	v_cvt_pk_bf16_f32 v91, v23, v19
	ds_read_b128 v[84:87], v35 offset:13312
	global_store_dwordx2 v[88:89], v[90:91], off offset:2048
	v_mul_f32_e32 v90, v157, v151
	s_waitcnt lgkmcnt(0)
	v_fmac_f32_e32 v18, v90, v84
	v_mul_f32_e32 v84, v157, v98
	v_fmac_f32_e32 v25, v84, v85
	v_mul_f32_e32 v84, v157, v152
	v_fmac_f32_e32 v21, v84, v86
	v_mul_f32_e32 v84, v157, v99
	v_fmac_f32_e32 v16, v84, v87
	v_cvt_pk_bf16_f32 v90, v18, v25
	v_cvt_pk_bf16_f32 v91, v21, v16
	ds_read_b128 v[84:87], v35 offset:14336
	global_store_dwordx2 v[88:89], v[90:91], off offset:2560
	v_mul_f32_e32 v90, v157, v153
	s_waitcnt lgkmcnt(0)
	v_fmac_f32_e32 v24, v90, v84
	v_mul_f32_e32 v84, v157, v100
	v_fmac_f32_e32 v17, v84, v85
	v_mul_f32_e32 v84, v157, v154
	v_fmac_f32_e32 v14, v84, v86
	v_mul_f32_e32 v84, v157, v101
	v_fmac_f32_e32 v15, v84, v87
	v_cvt_pk_bf16_f32 v90, v24, v17
	v_cvt_pk_bf16_f32 v91, v14, v15
	ds_read_b128 v[84:87], v35 offset:15360
	global_store_dwordx2 v[88:89], v[90:91], off offset:3072
	v_mul_f32_e32 v90, v157, v155
	s_waitcnt lgkmcnt(0)
	v_fmac_f32_e32 v82, v90, v84
	v_mul_f32_e32 v84, v157, v102
	v_fmac_f32_e32 v12, v84, v85
	v_mul_f32_e32 v84, v157, v156
	v_fmac_f32_e32 v83, v84, v86
	v_mul_f32_e32 v84, v157, v103
	v_fmac_f32_e32 v13, v84, v87
	v_cvt_pk_bf16_f32 v84, v82, v12
	v_cvt_pk_bf16_f32 v85, v83, v13
	global_store_dwordx2 v[88:89], v[84:85], off offset:3584
	v_mul_f32_e32 v84, v65, v65
	v_mul_f32_e32 v85, v63, v63
	v_fmac_f32_e32 v84, v66, v66
	v_fmac_f32_e32 v85, v64, v64
	v_add_f32_e32 v84, v84, v85
	v_mul_f32_e32 v85, v61, v61
	v_mul_f32_e32 v86, v59, v59
	v_fmac_f32_e32 v85, v62, v62
	v_fmac_f32_e32 v86, v60, v60
	v_add_f32_e32 v85, v85, v86
	v_add_f32_e32 v84, v84, v85
	v_mul_f32_e32 v85, v57, v57
	v_mul_f32_e32 v86, v55, v55
	v_fmac_f32_e32 v85, v58, v58
	v_fmac_f32_e32 v86, v56, v56
	v_add_f32_e32 v85, v85, v86
	v_add_f32_e32 v84, v84, v85
	v_mul_f32_e32 v85, v53, v53
	v_mul_f32_e32 v86, v51, v51
	v_fmac_f32_e32 v85, v54, v54
	v_fmac_f32_e32 v86, v52, v52
	v_add_f32_e32 v85, v85, v86
	v_add_f32_e32 v84, v84, v85
	v_mul_f32_e32 v85, v49, v49
	v_mul_f32_e32 v86, v47, v47
	v_fmac_f32_e32 v85, v48, v48
	v_fmac_f32_e32 v86, v50, v50
	v_add_f32_e32 v85, v85, v86
	v_add_f32_e32 v84, v84, v85
	v_mul_f32_e32 v85, v45, v45
	v_mul_f32_e32 v86, v43, v43
	v_fmac_f32_e32 v85, v46, v46
	v_fmac_f32_e32 v86, v44, v44
	v_add_f32_e32 v85, v85, v86
	v_add_f32_e32 v84, v84, v85
	v_mul_f32_e32 v85, v41, v41
	v_mul_f32_e32 v86, v39, v39
	v_fmac_f32_e32 v85, v42, v42
	v_fmac_f32_e32 v86, v40, v40
	v_add_f32_e32 v85, v85, v86
	v_add_f32_e32 v84, v84, v85
	v_mul_f32_e32 v85, v81, v81
	v_mul_f32_e32 v86, v79, v79
	v_fmac_f32_e32 v85, v38, v38
	v_fmac_f32_e32 v86, v80, v80
	v_add_f32_e32 v85, v85, v86
	v_add_f32_e32 v84, v84, v85
	v_mul_f32_e32 v85, v77, v77
	v_mul_f32_e32 v86, v75, v75
	v_fmac_f32_e32 v85, v73, v73
	v_fmac_f32_e32 v86, v78, v78
	v_add_f32_e32 v85, v85, v86
	v_add_f32_e32 v84, v84, v85
	v_mul_f32_e32 v85, v76, v76
	v_mul_f32_e32 v86, v71, v71
	v_fmac_f32_e32 v85, v74, v74
	v_fmac_f32_e32 v86, v72, v72
	v_add_f32_e32 v85, v85, v86
	v_add_f32_e32 v84, v84, v85
	v_mul_f32_e32 v85, v70, v70
	v_mul_f32_e32 v86, v29, v29
	v_fmac_f32_e32 v85, v68, v68
	v_fmac_f32_e32 v86, v69, v69
	v_add_f32_e32 v85, v85, v86
	v_add_f32_e32 v84, v84, v85
	v_mul_f32_e32 v85, v67, v67
	v_mul_f32_e32 v86, v26, v26
	v_fmac_f32_e32 v85, v27, v27
	v_fmac_f32_e32 v86, v28, v28
	v_add_f32_e32 v85, v85, v86
	v_add_f32_e32 v84, v84, v85
	v_mul_f32_e32 v85, v22, v22
	v_mul_f32_e32 v86, v19, v19
	v_fmac_f32_e32 v85, v20, v20
	v_fmac_f32_e32 v86, v23, v23
	v_add_f32_e32 v85, v85, v86
	v_add_f32_e32 v84, v84, v85
	v_mul_f32_e32 v85, v25, v25
	v_mul_f32_e32 v86, v16, v16
	v_fmac_f32_e32 v85, v18, v18
	v_fmac_f32_e32 v86, v21, v21
	v_add_f32_e32 v85, v85, v86
	v_add_f32_e32 v84, v84, v85
	v_mul_f32_e32 v85, v17, v17
	v_mul_f32_e32 v86, v15, v15
	v_fmac_f32_e32 v85, v24, v24
	v_fmac_f32_e32 v86, v14, v14
	v_add_f32_e32 v85, v85, v86
	v_add_f32_e32 v84, v84, v85
	v_mul_f32_e32 v85, v12, v12
	v_mul_f32_e32 v86, v13, v13
	v_fmac_f32_e32 v85, v82, v82
	v_fmac_f32_e32 v86, v83, v83
	v_add_f32_e32 v85, v85, v86
	v_add_f32_e32 v84, v84, v85
	ds_bpermute_b32 v85, v1, v84
	s_waitcnt lgkmcnt(0)
	v_add_f32_e32 v84, v84, v85
	ds_bpermute_b32 v85, v30, v84
	s_waitcnt lgkmcnt(0)
	v_add_f32_e32 v84, v84, v85
	ds_bpermute_b32 v85, v31, v84
	s_waitcnt lgkmcnt(0)
	v_add_f32_e32 v84, v84, v85
	ds_bpermute_b32 v85, v32, v84
	s_waitcnt lgkmcnt(0)
	v_add_f32_e32 v84, v84, v85
	ds_bpermute_b32 v85, v33, v84
	s_waitcnt lgkmcnt(0)
	v_add_f32_e32 v84, v84, v85
	ds_bpermute_b32 v85, v34, v84
	s_waitcnt lgkmcnt(0)
	v_add_f32_e32 v84, v84, v85
	v_fmamk_f32 v84, v84, 0x39800000, v2
	v_mul_f32_e32 v85, 0x4f800000, v84
	v_cmp_gt_f32_e32 vcc, s46, v84
	s_nop 1
	v_cndmask_b32_e32 v84, v84, v85, vcc
	v_sqrt_f32_e32 v85, v84
	s_nop 0
	v_add_u32_e32 v86, -1, v85
	v_fma_f32 v87, -v86, v85, v84
	v_cmp_ge_f32_e64 s[8:9], 0, v87
	v_add_u32_e32 v87, 1, v85
	s_nop 0
	v_cndmask_b32_e64 v86, v85, v86, s[8:9]
	v_fma_f32 v85, -v87, v85, v84
	v_cmp_lt_f32_e64 s[8:9], 0, v85
	s_nop 1
	v_cndmask_b32_e64 v85, v86, v87, s[8:9]
	v_mul_f32_e32 v86, 0x37800000, v85
	v_cndmask_b32_e32 v85, v85, v86, vcc
	v_cmp_class_f32_e32 vcc, v84, v36
	s_nop 1
	v_cndmask_b32_e32 v88, v85, v84, vcc
	v_div_scale_f32 v84, s[0:1], v88, v88, 1.0
	v_rcp_f32_e32 v89, v84
	s_nop 0
	v_fma_f32 v85, -v84, v89, 1.0
	v_fmac_f32_e32 v89, v85, v89
	v_div_scale_f32 v85, vcc, 1.0, v88, 1.0
	v_mul_f32_e32 v90, v85, v89
	v_fma_f32 v86, -v84, v90, v85
	v_fmac_f32_e32 v90, v86, v89
	v_fma_f32 v91, -v84, v90, v85
	ds_read_b128 v[84:87], v35 offset:16384
	v_div_fmas_f32 v89, v91, v89, v90
	v_div_fixup_f32 v94, v89, v88, 1.0
	ds_read_b128 v[88:91], v35 offset:17408
	s_waitcnt lgkmcnt(1)
	v_mul_f32_e32 v84, v84, v94
	v_mul_f32_e32 v66, v66, v84
	v_mul_f32_e32 v84, v85, v94
	v_mul_f32_e32 v65, v65, v84
	v_mul_f32_e32 v84, v86, v94
	v_mul_f32_e32 v64, v64, v84
	v_mul_f32_e32 v84, v87, v94
	v_mul_f32_e32 v63, v63, v84
	s_waitcnt lgkmcnt(0)
	v_mul_f32_e32 v84, v88, v94
	v_mul_f32_e32 v62, v62, v84
	v_mul_f32_e32 v84, v89, v94
	v_mul_f32_e32 v61, v61, v84
	ds_read_b128 v[84:87], v35 offset:18432
	v_mul_f32_e32 v88, v90, v94
	v_mul_f32_e32 v60, v60, v88
	v_mul_f32_e32 v88, v91, v94
	v_mul_f32_e32 v59, v59, v88
	ds_read_b128 v[88:91], v35 offset:19456
	s_waitcnt lgkmcnt(1)
	v_mul_f32_e32 v84, v84, v94
	v_mul_f32_e32 v58, v58, v84
	v_mul_f32_e32 v84, v85, v94
	v_mul_f32_e32 v57, v57, v84
	v_mul_f32_e32 v84, v86, v94
	v_mul_f32_e32 v56, v56, v84
	v_mul_f32_e32 v84, v87, v94
	v_mul_f32_e32 v55, v55, v84
	s_waitcnt lgkmcnt(0)
	v_mul_f32_e32 v84, v88, v94
	v_mul_f32_e32 v54, v54, v84
	v_mul_f32_e32 v84, v89, v94
	v_mul_f32_e32 v53, v53, v84
	v_mul_f32_e32 v84, v90, v94
	v_mul_f32_e32 v52, v52, v84
	v_mul_f32_e32 v84, v91, v94
	v_mul_f32_e32 v51, v51, v84
	ds_read_b128 v[84:87], v35 offset:20480
	ds_read_b128 v[88:91], v35 offset:21504
	s_waitcnt lgkmcnt(1)
	v_mul_f32_e32 v84, v94, v84
	v_mul_f32_e32 v86, v94, v86
	v_mul_f32_e32 v84, v48, v84
	v_mul_f32_e32 v48, v50, v86
	v_mul_f32_e32 v50, v94, v87
	v_mul_f32_e32 v47, v47, v50
	s_waitcnt lgkmcnt(0)
	v_mul_f32_e32 v50, v94, v88
	v_mul_f32_e32 v46, v46, v50
	v_mul_f32_e32 v50, v94, v89
	ds_read_b128 v[86:89], v35 offset:22528
	v_mul_f32_e32 v45, v45, v50
	v_mul_f32_e32 v50, v94, v90
	v_mul_f32_e32 v44, v44, v50
	v_mul_f32_e32 v50, v94, v91
	ds_read_b128 v[90:93], v35 offset:23552
	v_mul_f32_e32 v43, v43, v50
	s_waitcnt lgkmcnt(1)
	v_mul_f32_e32 v50, v94, v86
	v_mul_f32_e32 v42, v42, v50
	v_mul_f32_e32 v50, v94, v87
	v_mul_f32_e32 v41, v41, v50
	v_mul_f32_e32 v50, v94, v88
	v_mul_f32_e32 v85, v94, v85
	v_mul_f32_e32 v40, v40, v50
	v_mul_f32_e32 v50, v94, v89
	v_mul_f32_e32 v49, v49, v85
	v_mul_f32_e32 v85, v39, v50
	s_waitcnt lgkmcnt(0)
	v_mul_f32_e32 v39, v94, v90
	v_mul_f32_e32 v38, v38, v39
	v_mul_f32_e32 v39, v94, v91
	v_mul_f32_e32 v50, v81, v39
	v_mul_f32_e32 v39, v94, v92
	v_mul_f32_e32 v39, v80, v39
	v_mul_f32_e32 v80, v94, v93
	v_mul_f32_e32 v79, v79, v80
	ds_read_b128 v[86:89], v35 offset:24576
	ds_read_b128 v[90:93], v35 offset:25600
	s_waitcnt lgkmcnt(1)
	v_mul_f32_e32 v80, v94, v86
	v_mul_f32_e32 v81, v94, v87
	v_mul_f32_e32 v86, v94, v88
	v_mul_f32_e32 v80, v73, v80
	v_mul_f32_e32 v81, v77, v81
	v_mul_f32_e32 v77, v78, v86
	v_mul_f32_e32 v73, v94, v89
	ds_read_b128 v[86:89], v35 offset:26624
	v_mul_f32_e32 v75, v75, v73
	s_waitcnt lgkmcnt(1)
	v_mul_f32_e32 v73, v94, v90
	v_mul_f32_e32 v73, v74, v73
	v_mul_f32_e32 v74, v94, v91
	v_mul_f32_e32 v74, v76, v74
	v_mul_f32_e32 v76, v94, v92
	v_mul_f32_e32 v72, v72, v76
	v_mul_f32_e32 v76, v94, v93
	ds_read_b128 v[90:93], v35 offset:27648
	v_mul_f32_e32 v71, v71, v76
	s_waitcnt lgkmcnt(1)
	v_mul_f32_e32 v76, v94, v86
	v_mul_f32_e32 v68, v68, v76
	v_mul_f32_e32 v76, v94, v87
	v_mul_f32_e32 v70, v70, v76
	v_mul_f32_e32 v76, v94, v88
	v_mul_f32_e32 v69, v69, v76
	v_mul_f32_e32 v76, v94, v89
	v_mul_f32_e32 v76, v29, v76
	s_waitcnt lgkmcnt(0)
	v_mul_f32_e32 v29, v94, v90
	v_mul_f32_e32 v27, v27, v29
	v_mul_f32_e32 v29, v94, v91
	v_mul_f32_e32 v29, v67, v29
	v_mul_f32_e32 v67, v94, v92
	v_mul_f32_e32 v28, v28, v67
	v_mul_f32_e32 v67, v94, v93
	v_mul_f32_e32 v26, v26, v67
	ds_read_b128 v[86:89], v35 offset:28672
	ds_read_b128 v[90:93], v35 offset:29696
	s_waitcnt lgkmcnt(1)
	v_mul_f32_e32 v67, v94, v86
	v_mul_f32_e32 v86, v94, v88
	v_mul_f32_e32 v78, v94, v87
	v_mul_f32_e32 v67, v20, v67
	v_mul_f32_e32 v20, v23, v86
	v_mul_f32_e32 v23, v94, v89
	ds_read_b128 v[86:89], v35 offset:30720
	v_mul_f32_e32 v23, v19, v23
	s_waitcnt lgkmcnt(1)
	v_mul_f32_e32 v19, v94, v90
	v_mul_f32_e32 v18, v18, v19
	v_mul_f32_e32 v19, v94, v91
	v_mul_f32_e32 v19, v25, v19
	v_mul_f32_e32 v25, v94, v92
	v_mul_f32_e32 v21, v21, v25
	v_mul_f32_e32 v25, v94, v93
	ds_read_b128 v[90:93], v35 offset:31744
	v_mul_f32_e32 v16, v16, v25
	s_waitcnt lgkmcnt(1)
	v_mul_f32_e32 v25, v94, v86
	v_mul_f32_e32 v24, v24, v25
	v_mul_f32_e32 v25, v94, v87
	v_mul_f32_e32 v25, v17, v25
	v_mul_f32_e32 v17, v94, v88
	v_mul_f32_e32 v17, v14, v17
	v_mul_f32_e32 v14, v94, v89
	v_mul_f32_e32 v22, v22, v78
	v_mul_f32_e32 v78, v15, v14
	s_waitcnt lgkmcnt(0)
	v_mul_f32_e32 v14, v94, v90
	v_mul_f32_e32 v15, v94, v91
	v_mul_f32_e32 v14, v82, v14
	v_mul_f32_e32 v15, v12, v15
	v_mul_f32_e32 v12, v94, v92
	v_mul_f32_e32 v82, v94, v93
	v_mul_f32_e32 v12, v83, v12
	v_mul_f32_e32 v13, v13, v82
	v_max_f32_e64 v82, |v66|, |v65|
	v_max_f32_e64 v83, |v64|, |v63|
	v_max3_f32 v82, v82, 0, v83
	v_max_f32_e64 v83, |v62|, |v61|
	v_max_f32_e64 v86, |v60|, |v59|
	v_max3_f32 v82, v82, v83, v86
	v_max_f32_e64 v83, |v58|, |v57|
	v_max_f32_e64 v86, |v56|, |v55|
	v_max3_f32 v82, v82, v83, v86
	v_max_f32_e64 v83, |v54|, |v53|
	v_max_f32_e64 v86, |v52|, |v51|
	v_max3_f32 v82, v82, v83, v86
	v_max_f32_e64 v83, |v84|, |v49|
	v_max_f32_e64 v86, |v48|, |v47|
	v_max3_f32 v82, v82, v83, v86
	v_max_f32_e64 v83, |v46|, |v45|
	v_max_f32_e64 v86, |v44|, |v43|
	v_max3_f32 v82, v82, v83, v86
	v_max_f32_e64 v83, |v42|, |v41|
	v_max_f32_e64 v86, |v40|, |v85|
	v_max3_f32 v82, v82, v83, v86
	v_max_f32_e64 v83, |v38|, |v50|
	v_max_f32_e64 v86, |v39|, |v79|
	v_max3_f32 v82, v82, v83, v86
	v_max_f32_e64 v83, |v80|, |v81|
	v_max_f32_e64 v86, |v77|, |v75|
	v_max3_f32 v82, v82, v83, v86
	v_max_f32_e64 v83, |v73|, |v74|
	v_max_f32_e64 v86, |v72|, |v71|
	v_max3_f32 v82, v82, v83, v86
	v_max_f32_e64 v83, |v68|, |v70|
	v_max_f32_e64 v86, |v69|, |v76|
	v_max3_f32 v82, v82, v83, v86
	v_max_f32_e64 v83, |v27|, |v29|
	v_max_f32_e64 v86, |v28|, |v26|
	v_max3_f32 v82, v82, v83, v86
	v_max_f32_e64 v83, |v67|, |v22|
	v_max_f32_e64 v86, |v20|, |v23|
	v_max3_f32 v82, v82, v83, v86
	v_max_f32_e64 v83, |v18|, |v19|
	v_max_f32_e64 v86, |v21|, |v16|
	v_max3_f32 v82, v82, v83, v86
	v_max_f32_e64 v83, |v24|, |v25|
	v_max_f32_e64 v86, |v17|, |v78|
	v_max3_f32 v82, v82, v83, v86
	v_max_f32_e64 v83, |v14|, |v15|
	v_max_f32_e64 v86, |v12|, |v13|
	v_max3_f32 v82, v82, v83, v86
	ds_bpermute_b32 v83, v1, v82
	s_waitcnt lgkmcnt(0)
	v_max_f32_e32 v83, v83, v83
	v_max_f32_e32 v82, v82, v83
	ds_bpermute_b32 v83, v30, v82
	s_waitcnt lgkmcnt(0)
	v_max_f32_e32 v83, v83, v83
	v_max_f32_e32 v82, v82, v83
	ds_bpermute_b32 v83, v31, v82
	s_waitcnt lgkmcnt(0)
	v_max_f32_e32 v83, v83, v83
	v_max_f32_e32 v82, v82, v83
	ds_bpermute_b32 v83, v32, v82
	s_waitcnt lgkmcnt(0)
	v_max_f32_e32 v83, v83, v83
	v_max_f32_e32 v82, v82, v83
	ds_bpermute_b32 v83, v33, v82
	s_waitcnt lgkmcnt(0)
	v_max_f32_e32 v83, v83, v83
	v_max_f32_e32 v82, v82, v83
	ds_bpermute_b32 v83, v34, v82
	s_waitcnt lgkmcnt(0)
	v_max3_f32 v82, v82, v83, s47
	s_and_saveexec_b64 s[0:1], s[6:7]
	s_cbranch_execz .LBB0_1345
	s_lshl_b64 s[8:9], s[24:25], 2
	s_add_u32 s8, s26, s8
	v_mul_f32_e32 v83, 0x3c010204, v82
	s_addc_u32 s9, s27, s9
	global_store_dword v3, v83, s[8:9]

.LBB0_1517:
	s_or_b64 exec, exec, s[0:1]
	s_mul_hi_i32 s37, s26, 0x2b00
	s_mul_i32 s36, s26, 0x2b00
	v_lshl_add_u64 v[94:95], s[36:37], 1, v[90:91]
	v_add_co_u32_e32 v2, vcc, 0x1000, v94
	global_load_dwordx4 v[86:89], v[94:95], off nt
	global_load_dwordx4 v[82:85], v[94:95], off offset:1024 nt
	global_load_dwordx4 v[78:81], v[94:95], off offset:2048 nt
	global_load_dwordx4 v[74:77], v[94:95], off offset:3072 nt
	v_addc_co_u32_e32 v3, vcc, 0, v95, vcc
	global_load_dwordx4 v[70:73], v[2:3], off nt
	global_load_dwordx4 v[66:69], v[2:3], off offset:1024 nt
	global_load_dwordx4 v[62:65], v[2:3], off offset:2048 nt
	global_load_dwordx4 v[58:61], v[2:3], off offset:3072 nt
	v_add_co_u32_e32 v2, vcc, 0x2000, v94
	v_mov_b32_e32 v4, 0
	s_nop 0
	v_addc_co_u32_e32 v3, vcc, 0, v95, vcc
	global_load_dwordx4 v[54:57], v[2:3], off nt
	global_load_dwordx4 v[50:53], v[2:3], off offset:1024 nt
	global_load_dwordx4 v[46:49], v[2:3], off offset:2048 nt
	global_load_dwordx4 v[42:45], v[2:3], off offset:3072 nt
	v_add_co_u32_e32 v2, vcc, 0x3000, v94
	v_mov_b32_e32 v5, 0
	s_nop 0
	v_addc_co_u32_e32 v3, vcc, 0, v95, vcc
	global_load_dwordx4 v[38:41], v[2:3], off nt
	global_load_dwordx4 v[34:37], v[2:3], off offset:1024 nt
	global_load_dwordx4 v[30:33], v[2:3], off offset:2048 nt
	global_load_dwordx4 v[26:29], v[2:3], off offset:3072 nt
	v_add_co_u32_e32 v2, vcc, 0x4000, v94
	s_nop 1
	v_addc_co_u32_e32 v3, vcc, 0, v95, vcc
	global_load_dwordx4 v[22:25], v[2:3], off nt
	global_load_dwordx4 v[18:21], v[2:3], off offset:1024 nt
	global_load_dwordx4 v[14:17], v[2:3], off offset:2048 nt
	global_load_dwordx4 v[10:13], v[2:3], off offset:3072 nt
	v_add_co_u32_e32 v2, vcc, 0x5000, v94
	s_nop 1
	v_addc_co_u32_e32 v3, vcc, 0, v95, vcc
	global_load_dwordx4 v[6:9], v[2:3], off nt
	v_mov_b32_e32 v2, 0
	v_mov_b32_e32 v3, 0
	s_and_saveexec_b64 s[0:1], s[6:7]
	s_cbranch_execz .LBB0_1519
	v_add_co_u32_e32 v2, vcc, 0x5000, v94
	s_nop 1
	v_addc_co_u32_e32 v3, vcc, 0, v95, vcc
	global_load_dwordx4 v[2:5], v[2:3], off offset:1024 nt

.LBB0_1672:
	s_or_b64 exec, exec, s[2:3]
	s_ashr_i32 s13, s12, 31
	s_lshl_b64 s[2:3], s[12:13], 13
	v_lshl_add_u64 v[0:1], v[18:19], 0, s[2:3]
	v_add_co_u32_e32 v12, vcc, 0x1000, v0
	global_load_dwordx2 v[2:3], v[0:1], off offset:512
	global_load_dwordx2 v[4:5], v[0:1], off offset:1024
	global_load_dwordx2 v[6:7], v[0:1], off offset:2048
	global_load_dwordx2 v[8:9], v[0:1], off offset:2560
	global_load_dwordx2 v[10:11], v[0:1], off offset:3072
	v_addc_co_u32_e32 v13, vcc, 0, v1, vcc
	global_load_dwordx2 v[14:15], v[12:13], off
	global_load_dwordx2 v[24:25], v[12:13], off offset:512
	v_lshl_add_u64 v[26:27], v[20:21], 0, s[2:3]
	global_load_dwordx2 v[28:29], v[12:13], off offset:1024
	global_load_dwordx2 v[78:79], v[0:1], off
	global_load_dwordx2 v[106:107], v[0:1], off offset:1536
	global_load_dwordx2 v[112:113], v[0:1], off offset:3584
	global_load_dwordx2 v[76:77], v[26:27], off nt
	global_load_dwordx2 v[86:87], v[26:27], off offset:512 nt
	global_load_dwordx2 v[94:95], v[26:27], off offset:1024 nt
	global_load_dwordx2 v[108:109], v[26:27], off offset:1536 nt
	global_load_dwordx2 v[30:31], v[12:13], off offset:2048
	global_load_dwordx2 v[102:103], v[26:27], off offset:2048 nt
	global_load_dwordx2 v[92:93], v[26:27], off offset:2560 nt
	global_load_dwordx2 v[100:101], v[26:27], off offset:3072 nt
	global_load_dwordx2 v[120:121], v[26:27], off offset:3584 nt
	global_load_dwordx2 v[38:39], v[12:13], off offset:2560
	v_add_co_u32_e32 v0, vcc, s22, v26
	s_lshl_b64 s[2:3], s[12:13], 14
	s_nop 0
	v_addc_co_u32_e32 v1, vcc, 0, v27, vcc
	global_load_dwordx2 v[114:115], v[0:1], off nt
	global_load_dwordx2 v[98:99], v[0:1], off offset:512 nt
	global_load_dwordx2 v[66:67], v[0:1], off offset:1024 nt
	global_load_dwordx2 v[64:65], v[0:1], off offset:1536 nt
	global_load_dwordx2 v[70:71], v[12:13], off offset:3072
	global_load_dwordx2 v[62:63], v[0:1], off offset:2048 nt
	global_load_dwordx2 v[60:61], v[0:1], off offset:2560 nt
	global_load_dwordx2 v[58:59], v[0:1], off offset:3072 nt
	global_load_dwordx2 v[56:57], v[0:1], off offset:3584 nt
	global_load_dwordx2 v[72:73], v[12:13], off offset:1536
	global_load_dwordx2 v[68:69], v[12:13], off offset:3584
	s_waitcnt vmcnt(24)
	v_and_b32_e32 v35, 0xffff0000, v28
	v_lshlrev_b32_e32 v34, 16, v28
	v_and_b32_e32 v33, 0xffff0000, v29
	v_lshlrev_b32_e32 v32, 16, v29
	v_and_b32_e32 v51, 0xffff0000, v3
	v_and_b32_e32 v50, 0xffff0000, v2
	v_lshlrev_b32_e32 v13, 16, v3
	v_lshlrev_b32_e32 v12, 16, v2
	v_pk_mul_f32 v[0:1], v[50:51], v[50:51]
	s_waitcnt vmcnt(16)
	v_lshlrev_b32_e32 v85, 16, v31
	v_pk_fma_f32 v[0:1], v[12:13], v[12:13], v[0:1]
	v_and_b32_e32 v43, 0xffff0000, v15
	v_and_b32_e32 v42, 0xffff0000, v14
	v_lshlrev_b32_e32 v137, 16, v15
	v_lshlrev_b32_e32 v136, 16, v14
	v_pk_add_f32 v[126:127], v[0:1], v[0:1] op_sel:[0,1] op_sel_hi:[1,0]
	v_pk_mul_f32 v[0:1], v[42:43], v[42:43]
	v_and_b32_e32 v41, 0xffff0000, v25
	v_pk_fma_f32 v[0:1], v[136:137], v[136:137], v[0:1]
	v_and_b32_e32 v40, 0xffff0000, v24
	v_pk_add_f32 v[140:141], v[0:1], v[0:1] op_sel:[0,1] op_sel_hi:[1,0]
	v_lshlrev_b32_e32 v169, 16, v25
	v_lshlrev_b32_e32 v168, 16, v24
	v_pk_mul_f32 v[0:1], v[40:41], v[40:41]
	v_lshlrev_b32_e32 v84, 16, v30
	v_pk_fma_f32 v[0:1], v[168:169], v[168:169], v[0:1]
	v_and_b32_e32 v31, 0xffff0000, v31
	v_pk_add_f32 v[156:157], v[0:1], v[0:1] op_sel:[0,1] op_sel_hi:[1,0]
	v_mul_f32_e32 v0, v35, v35
	v_pk_fma_f32 v[152:153], v[34:35], v[34:35], v[0:1] op_sel_hi:[1,1,0]
	v_mul_f32_e32 v0, v33, v33
	v_and_b32_e32 v30, 0xffff0000, v30
	v_pk_fma_f32 v[154:155], v[32:33], v[32:33], v[0:1] op_sel_hi:[1,1,0]
	v_pk_mul_f32 v[0:1], v[30:31], v[30:31]
	v_and_b32_e32 v37, 0xffff0000, v11
	v_pk_fma_f32 v[0:1], v[84:85], v[84:85], v[0:1]
	s_waitcnt vmcnt(11)
	v_and_b32_e32 v29, 0xffff0000, v39
	v_and_b32_e32 v28, 0xffff0000, v38
	v_lshlrev_b32_e32 v36, 16, v11
	v_mul_f32_e32 v26, v37, v37
	v_pk_add_f32 v[146:147], v[0:1], v[0:1] op_sel:[0,1] op_sel_hi:[1,0]
	v_lshlrev_b32_e32 v83, 16, v39
	v_lshlrev_b32_e32 v82, 16, v38
	v_pk_mul_f32 v[0:1], v[28:29], v[28:29]
	v_pk_fma_f32 v[130:131], v[36:37], v[36:37], v[26:27] op_sel_hi:[1,1,0]
	v_pk_fma_f32 v[0:1], v[82:83], v[82:83], v[0:1]
	s_waitcnt vmcnt(6)
	v_and_b32_e32 v27, 0xffff0000, v70
	v_pk_add_f32 v[150:151], v[0:1], v[0:1] op_sel:[0,1] op_sel_hi:[1,0]
	v_lshlrev_b32_e32 v26, 16, v70
	v_mul_f32_e32 v0, v27, v27
	v_and_b32_e32 v25, 0xffff0000, v71
	v_pk_fma_f32 v[144:145], v[26:27], v[26:27], v[0:1] op_sel_hi:[1,1,0]
	v_lshlrev_b32_e32 v24, 16, v71
	v_mul_f32_e32 v0, v25, v25
	v_and_b32_e32 v75, 0xffff0000, v78
	v_pk_fma_f32 v[148:149], v[24:25], v[24:25], v[0:1] op_sel_hi:[1,1,0]
	v_lshlrev_b32_e32 v74, 16, v78
	v_mul_f32_e32 v0, v75, v75
	v_lshlrev_b32_e32 v78, 16, v79
	v_and_b32_e32 v79, 0xffff0000, v79
	v_pk_fma_f32 v[128:129], v[74:75], v[74:75], v[0:1] op_sel_hi:[1,1,0]
	v_mul_f32_e32 v0, v79, v79
	v_and_b32_e32 v53, 0xffff0000, v4
	v_and_b32_e32 v55, 0xffff0000, v5
	v_pk_fma_f32 v[134:135], v[78:79], v[78:79], v[0:1] op_sel_hi:[1,1,0]
	v_lshlrev_b32_e32 v52, 16, v4
	v_lshlrev_b32_e32 v54, 16, v5
	v_mul_f32_e32 v2, v53, v53
	v_mul_f32_e32 v4, v55, v55
	v_and_b32_e32 v143, 0xffff0000, v106
	v_and_b32_e32 v142, s0, v106
	v_pk_add_f32 v[128:129], v[128:129], v[134:135]
	v_lshlrev_b32_e32 v134, 16, v107
	v_and_b32_e32 v135, 0xffff0000, v107
	v_pk_fma_f32 v[110:111], v[52:53], v[52:53], v[2:3] op_sel_hi:[1,1,0]
	v_pk_fma_f32 v[118:119], v[54:55], v[54:55], v[4:5] op_sel_hi:[1,1,0]
	v_lshlrev_b32_e32 v104, 16, v106
	v_mov_b32_e32 v105, v143
	v_pk_mul_f32 v[142:143], v[142:143], v[142:143]
	v_pk_mul_f32 v[106:107], v[134:135], v[134:135]
	v_and_b32_e32 v49, 0xffff0000, v7
	v_and_b32_e32 v48, 0xffff0000, v6
	v_mul_f32_e32 v129, v104, v104
	v_mov_b32_e32 v127, v143
	v_mov_b32_e32 v111, v106
	v_mov_b32_e32 v119, v107
	v_lshlrev_b32_e32 v117, 16, v7
	v_lshlrev_b32_e32 v116, 16, v6
	v_and_b32_e32 v47, 0xffff0000, v9
	v_and_b32_e32 v46, 0xffff0000, v8
	v_pk_mul_f32 v[6:7], v[48:49], v[48:49]
	v_pk_add_f32 v[126:127], v[128:129], v[126:127]
	v_pk_add_f32 v[106:107], v[110:111], v[118:119]
	v_lshlrev_b32_e32 v123, 16, v9
	v_lshlrev_b32_e32 v122, 16, v8
	v_pk_mul_f32 v[8:9], v[46:47], v[46:47]
	v_pk_fma_f32 v[2:3], v[116:117], v[116:117], v[6:7]
	v_pk_add_f32 v[106:107], v[126:127], v[106:107]
	v_pk_fma_f32 v[4:5], v[122:123], v[122:123], v[8:9]
	v_pk_add_f32 v[132:133], v[2:3], v[2:3] op_sel:[0,1] op_sel_hi:[1,0]
	v_pk_add_f32 v[170:171], v[106:107], v[106:107] op_sel:[0,1] op_sel_hi:[1,0]
	v_lshlrev_b32_e32 v106, 16, v112
	v_and_b32_e32 v107, 0xffff0000, v112
	v_pk_add_f32 v[138:139], v[4:5], v[4:5] op_sel:[0,1] op_sel_hi:[1,0]
	v_mov_b32_e32 v126, v122
	v_mov_b32_e32 v127, v46
	v_mov_b32_e32 v46, v123
	v_pk_mul_f32 v[122:123], v[106:107], v[106:107]
	v_pk_add_f32 v[132:133], v[170:171], v[132:133]
	v_and_b32_e32 v45, 0xffff0000, v10
	v_mov_b32_e32 v139, v123
	v_mov_b32_e32 v133, v122
	v_lshlrev_b32_e32 v44, 16, v10
	v_mul_f32_e32 v10, v45, v45
	v_pk_add_f32 v[138:139], v[132:133], v[138:139]
	v_lshlrev_b32_e32 v132, 16, v113
	v_and_b32_e32 v133, 0xffff0000, v113
	v_pk_fma_f32 v[124:125], v[44:45], v[44:45], v[10:11] op_sel_hi:[1,1,0]
	v_pk_mul_f32 v[112:113], v[132:133], v[132:133]
	v_lshl_add_u64 v[38:39], v[22:23], 0, s[2:3]
	v_mov_b32_e32 v125, v112
	v_mov_b32_e32 v131, v113
	v_pk_add_f32 v[112:113], v[124:125], v[130:131]
	v_lshlrev_b32_e32 v124, 16, v115
	v_pk_add_f32 v[112:113], v[138:139], v[112:113]
	v_and_b32_e32 v125, 0xffff0000, v115
	v_pk_add_f32 v[170:171], v[112:113], v[112:113] op_sel:[0,1] op_sel_hi:[1,0]
	v_lshlrev_b32_e32 v112, 16, v114
	v_and_b32_e32 v113, 0xffff0000, v114
	s_waitcnt vmcnt(1)
	v_lshlrev_b32_e32 v114, 16, v72
	v_and_b32_e32 v115, 0xffff0000, v72
	v_mov_b32_e32 v138, v136
	v_mov_b32_e32 v139, v42
	v_mov_b32_e32 v42, v137
	v_mov_b32_e32 v136, v168
	v_mov_b32_e32 v137, v40
	v_mov_b32_e32 v40, v169
	v_pk_mul_f32 v[168:169], v[114:115], v[114:115]
	v_pk_add_f32 v[140:141], v[170:171], v[140:141]
	v_mov_b32_e32 v157, v169
	v_mov_b32_e32 v141, v168
	v_pk_add_f32 v[156:157], v[140:141], v[156:157]
	v_lshlrev_b32_e32 v140, 16, v73
	v_and_b32_e32 v141, 0xffff0000, v73
	v_pk_mul_f32 v[72:73], v[140:141], v[140:141]
	ds_read_b128 v[4:7], v16
	ds_read_b128 v[0:3], v16 offset:1024
	v_mov_b32_e32 v153, v72
	v_mov_b32_e32 v155, v73
	v_pk_add_f32 v[72:73], v[152:153], v[154:155]
	s_waitcnt vmcnt(0)
	v_and_b32_e32 v155, 0xffff0000, v68
	v_pk_add_f32 v[72:73], v[156:157], v[72:73]
	v_and_b32_e32 v154, s0, v68
	v_pk_add_f32 v[152:153], v[72:73], v[72:73] op_sel:[0,1] op_sel_hi:[1,0]
	v_lshlrev_b32_e32 v72, 16, v68
	v_pk_mul_f32 v[156:157], v[154:155], v[154:155]
	v_pk_add_f32 v[146:147], v[152:153], v[146:147]
	v_mov_b32_e32 v151, v157
	v_mul_f32_e32 v147, v72, v72
	v_lshlrev_b32_e32 v68, 16, v69
	v_and_b32_e32 v69, 0xffff0000, v69
	v_pk_add_f32 v[146:147], v[146:147], v[150:151]
	v_pk_mul_f32 v[150:151], v[68:69], v[68:69]
	v_lshlrev_b32_e32 v70, 16, v76
	v_mov_b32_e32 v145, v150
	v_mov_b32_e32 v149, v151
	v_pk_add_f32 v[144:145], v[144:145], v[148:149]
	v_mov_b32_e32 v148, v84
	v_pk_add_f32 v[144:145], v[146:147], v[144:145]
	v_mov_b32_e32 v149, v30
	v_add_f32_e32 v73, v144, v145
	ds_bpermute_b32 v145, v158, v73
	v_mov_b32_e32 v30, v85
	v_lshlrev_b32_e32 v84, 16, v60
	v_and_b32_e32 v85, 0xffff0000, v60
	v_mov_b32_e32 v151, v28
	s_waitcnt lgkmcnt(0)
	v_add_f32_e32 v73, v73, v145
	ds_bpermute_b32 v147, v159, v73
	v_mov_b32_e32 v28, v83
	v_and_b32_e32 v83, 0xffff0000, v56
	v_and_b32_e32 v71, 0xffff0000, v76
	v_lshlrev_b32_e32 v76, 16, v77
	s_waitcnt lgkmcnt(0)
	v_add_f32_e32 v73, v73, v147
	ds_bpermute_b32 v150, v160, v73
	v_and_b32_e32 v77, 0xffff0000, v77
	v_mov_b32_e32 v88, v12
	v_mov_b32_e32 v89, v50
	v_lshlrev_b32_e32 v80, 16, v86
	s_waitcnt lgkmcnt(0)
	v_add_f32_e32 v73, v73, v150
	ds_bpermute_b32 v150, v161, v73
	v_and_b32_e32 v81, 0xffff0000, v86
	v_mov_b32_e32 v50, v13
	ds_read_b128 v[12:15], v16 offset:2048
	ds_read_b128 v[8:11], v16 offset:3072
	v_lshlrev_b32_e32 v86, 16, v87
	s_waitcnt lgkmcnt(2)
	v_add_f32_e32 v60, v73, v150
	ds_bpermute_b32 v73, v162, v60
	v_mov_b32_e32 v150, v82
	v_and_b32_e32 v87, 0xffff0000, v87
	v_lshlrev_b32_e32 v90, 16, v94
	v_and_b32_e32 v91, 0xffff0000, v94
	s_waitcnt lgkmcnt(0)
	v_add_f32_e32 v73, v60, v73
	ds_bpermute_b32 v82, v163, v73
	v_lshlrev_b32_e32 v94, 16, v95
	v_and_b32_e32 v95, 0xffff0000, v95
	v_lshlrev_b32_e32 v96, 16, v108
	v_and_b32_e32 v97, 0xffff0000, v108
	s_waitcnt lgkmcnt(0)
	v_add_f32_e32 v73, v73, v82
	v_fmamk_f32 v73, v73, 0x39800000, v164
	v_mul_f32_e32 v82, 0x4f800000, v73
	v_cmp_gt_f32_e32 vcc, s23, v73
	v_lshlrev_b32_e32 v128, 16, v109
	v_and_b32_e32 v129, 0xffff0000, v109
	v_cndmask_b32_e32 v73, v73, v82, vcc
	v_sqrt_f32_e32 v154, v73
	v_lshlrev_b32_e32 v82, 16, v56
	v_lshlrev_b32_e32 v110, 16, v102
	v_and_b32_e32 v111, 0xffff0000, v102
	v_add_u32_e32 v56, -1, v154
	v_fma_f32 v156, -v56, v154, v73
	v_cmp_ge_f32_e64 s[2:3], 0, v156
	v_add_u32_e32 v156, 1, v154
	v_mov_b32_e32 v142, v116
	v_cndmask_b32_e64 v56, v154, v56, s[2:3]
	v_fma_f32 v154, -v156, v154, v73
	v_cmp_lt_f32_e64 s[2:3], 0, v154
	v_mov_b32_e32 v143, v48
	v_lshlrev_b32_e32 v118, 16, v103
	v_cndmask_b32_e64 v56, v56, v156, s[2:3]
	v_mul_f32_e32 v154, 0x37800000, v56
	v_cndmask_b32_e32 v56, v56, v154, vcc
	v_cmp_class_f32_e32 vcc, v73, v165
	v_and_b32_e32 v119, 0xffff0000, v103
	v_mov_b32_e32 v48, v117
	v_cndmask_b32_e32 v154, v56, v73, vcc
	v_div_scale_f32 v156, s[2:3], v154, v154, 0.5
	v_rcp_f32_e32 v157, v156
	v_mov_b32_e32 v73, v155
	v_lshlrev_b32_e32 v116, 16, v92
	v_and_b32_e32 v117, 0xffff0000, v92
	v_fma_f32 v155, -v156, v157, 1.0
	v_fmac_f32_e32 v157, v155, v157
	v_div_scale_f32 v155, vcc, 0.5, v154, 0.5
	v_mul_f32_e32 v167, v155, v157
	v_fma_f32 v168, -v156, v167, v155
	v_fmac_f32_e32 v167, v168, v157
	v_fma_f32 v155, -v156, v167, v155
	v_div_fmas_f32 v155, v155, v157, v167
	v_div_fixup_f32 v154, v155, v154, 0.5
	v_pk_mul_f32 v[74:75], v[154:155], v[74:75] op_sel_hi:[0,1]
	v_pk_fma_f32 v[4:5], v[4:5], v[74:75], v[70:71]
	v_pk_mul_f32 v[70:71], v[154:155], v[78:79] op_sel_hi:[0,1]
	v_pk_fma_f32 v[6:7], v[6:7], v[70:71], v[76:77]
	global_store_dwordx4 v[38:39], v[4:7], off nt
	v_lshlrev_b32_e32 v108, 16, v93
	v_and_b32_e32 v109, 0xffff0000, v93
	v_pk_mul_f32 v[4:5], v[154:155], v[88:89] op_sel_hi:[0,1]
	v_pk_fma_f32 v[0:1], v[0:1], v[4:5], v[80:81]
	v_pk_mul_f32 v[4:5], v[154:155], v[50:51] op_sel_hi:[0,1]
	v_pk_fma_f32 v[2:3], v[2:3], v[4:5], v[86:87]
	global_store_dwordx4 v[38:39], v[0:3], off offset:1024 nt
	v_lshlrev_b32_e32 v92, 16, v100
	v_and_b32_e32 v93, 0xffff0000, v100
	v_pk_mul_f32 v[0:1], v[154:155], v[52:53] op_sel_hi:[0,1]
	v_pk_mul_f32 v[2:3], v[154:155], v[54:55] op_sel_hi:[0,1]
	v_pk_fma_f32 v[0:1], v[12:13], v[0:1], v[90:91]
	v_pk_fma_f32 v[2:3], v[14:15], v[2:3], v[94:95]
	global_store_dwordx4 v[38:39], v[0:3], off offset:2048 nt
	v_lshlrev_b32_e32 v100, 16, v101
	v_and_b32_e32 v101, 0xffff0000, v101
	v_pk_mul_f32 v[0:1], v[154:155], v[104:105] op_sel_hi:[0,1]
	v_pk_mul_f32 v[2:3], v[154:155], v[134:135] op_sel_hi:[0,1]
	v_pk_fma_f32 v[0:1], v[0:1], v[8:9], v[96:97]
	v_pk_fma_f32 v[2:3], v[2:3], v[10:11], v[128:129]
	v_lshlrev_b32_e32 v102, 16, v120
	v_and_b32_e32 v103, 0xffff0000, v120
	v_lshlrev_b32_e32 v122, 16, v121
	v_and_b32_e32 v123, 0xffff0000, v121
	v_lshlrev_b32_e32 v130, 16, v98
	v_and_b32_e32 v131, 0xffff0000, v98
	v_lshlrev_b32_e32 v120, 16, v99
	v_and_b32_e32 v121, 0xffff0000, v99
	v_lshlrev_b32_e32 v98, 16, v66
	v_and_b32_e32 v99, 0xffff0000, v66
	v_lshlrev_b32_e32 v66, 16, v67
	v_and_b32_e32 v67, 0xffff0000, v67
	v_lshlrev_b32_e32 v144, 16, v64
	v_and_b32_e32 v145, 0xffff0000, v64
	v_lshlrev_b32_e32 v64, 16, v65
	v_and_b32_e32 v65, 0xffff0000, v65
	v_lshlrev_b32_e32 v146, 16, v62
	v_and_b32_e32 v147, 0xffff0000, v62
	v_lshlrev_b32_e32 v62, 16, v63
	v_and_b32_e32 v63, 0xffff0000, v63
	v_lshlrev_b32_e32 v152, 16, v61
	v_and_b32_e32 v153, 0xffff0000, v61
	v_lshlrev_b32_e32 v60, 16, v58
	v_and_b32_e32 v61, 0xffff0000, v58
	v_lshlrev_b32_e32 v58, 16, v59
	v_and_b32_e32 v59, 0xffff0000, v59
	v_lshlrev_b32_e32 v56, 16, v57
	v_and_b32_e32 v57, 0xffff0000, v57
	global_store_dwordx4 v[38:39], v[0:3], off offset:3072 nt
	ds_read_b128 v[0:3], v16 offset:4096
	ds_read_b128 v[4:7], v16 offset:5120
	v_add_co_u32_e32 v12, vcc, s22, v38
	v_pk_mul_f32 v[8:9], v[154:155], v[142:143] op_sel_hi:[0,1]
	s_nop 0
	v_addc_co_u32_e32 v13, vcc, 0, v39, vcc
	v_pk_mul_f32 v[10:11], v[154:155], v[48:49] op_sel_hi:[0,1]
	v_add_co_u32_e32 v14, vcc, s24, v38
	s_waitcnt lgkmcnt(1)
	v_pk_fma_f32 v[0:1], v[8:9], v[0:1], v[110:111]
	v_pk_fma_f32 v[2:3], v[10:11], v[2:3], v[118:119]
	v_addc_co_u32_e32 v15, vcc, 0, v39, vcc
	global_store_dwordx4 v[14:15], v[0:3], off offset:-4096 nt
	ds_read_b128 v[8:11], v16 offset:6144
	s_nop 0
	v_pk_mul_f32 v[0:1], v[154:155], v[126:127] op_sel_hi:[0,1]
	v_pk_mul_f32 v[2:3], v[154:155], v[46:47] op_sel_hi:[0,1]
	s_waitcnt lgkmcnt(1)
	v_pk_fma_f32 v[0:1], v[0:1], v[4:5], v[116:117]
	v_pk_fma_f32 v[2:3], v[2:3], v[6:7], v[108:109]
	global_store_dwordx4 v[12:13], v[0:3], off offset:1024 nt
	ds_read_b128 v[0:3], v16 offset:7168
	v_pk_mul_f32 v[4:5], v[154:155], v[44:45] op_sel_hi:[0,1]
	v_pk_mul_f32 v[6:7], v[154:155], v[36:37] op_sel_hi:[0,1]
	s_waitcnt lgkmcnt(1)
	v_pk_fma_f32 v[4:5], v[4:5], v[8:9], v[92:93]
	v_pk_fma_f32 v[6:7], v[6:7], v[10:11], v[100:101]
	global_store_dwordx4 v[12:13], v[4:7], off offset:2048 nt
	s_nop 1
	v_pk_mul_f32 v[4:5], v[154:155], v[106:107] op_sel_hi:[0,1]
	s_waitcnt lgkmcnt(0)
	v_pk_fma_f32 v[0:1], v[4:5], v[0:1], v[102:103]
	v_pk_mul_f32 v[4:5], v[154:155], v[132:133] op_sel_hi:[0,1]
	v_pk_fma_f32 v[2:3], v[4:5], v[2:3], v[122:123]
	global_store_dwordx4 v[12:13], v[0:3], off offset:3072 nt
	ds_read_b128 v[0:3], v16 offset:8192
	ds_read_b128 v[4:7], v16 offset:9216
	v_pk_mul_f32 v[8:9], v[154:155], v[138:139] op_sel_hi:[0,1]
	v_pk_mul_f32 v[10:11], v[154:155], v[42:43] op_sel_hi:[0,1]
	s_waitcnt lgkmcnt(1)
	v_pk_fma_f32 v[0:1], v[8:9], v[0:1], v[112:113]
	v_pk_fma_f32 v[2:3], v[10:11], v[2:3], v[124:125]
	global_store_dwordx4 v[14:15], v[0:3], off nt
	ds_read_b128 v[8:11], v16 offset:10240
	s_nop 0
	v_pk_mul_f32 v[0:1], v[154:155], v[136:137] op_sel_hi:[0,1]
	v_pk_mul_f32 v[2:3], v[154:155], v[40:41] op_sel_hi:[0,1]
	s_waitcnt lgkmcnt(1)
	v_pk_fma_f32 v[0:1], v[0:1], v[4:5], v[130:131]
	v_pk_fma_f32 v[2:3], v[2:3], v[6:7], v[120:121]
	global_store_dwordx4 v[14:15], v[0:3], off offset:1024 nt
	ds_read_b128 v[0:3], v16 offset:11264
	v_pk_mul_f32 v[4:5], v[154:155], v[34:35] op_sel_hi:[0,1]
	v_pk_mul_f32 v[6:7], v[154:155], v[32:33] op_sel_hi:[0,1]
	s_waitcnt lgkmcnt(1)
	v_pk_fma_f32 v[4:5], v[4:5], v[8:9], v[98:99]
	v_pk_fma_f32 v[6:7], v[6:7], v[10:11], v[66:67]
	global_store_dwordx4 v[14:15], v[4:7], off offset:2048 nt
	s_nop 1
	v_pk_mul_f32 v[4:5], v[154:155], v[114:115] op_sel_hi:[0,1]
	s_waitcnt lgkmcnt(0)
	v_pk_fma_f32 v[0:1], v[4:5], v[0:1], v[144:145]
	v_pk_mul_f32 v[4:5], v[154:155], v[140:141] op_sel_hi:[0,1]
	v_pk_fma_f32 v[2:3], v[4:5], v[2:3], v[64:65]
	global_store_dwordx4 v[14:15], v[0:3], off offset:3072 nt
	ds_read_b128 v[0:3], v16 offset:12288
	ds_read_b128 v[4:7], v16 offset:13312
	v_pk_mul_f32 v[8:9], v[154:155], v[148:149] op_sel_hi:[0,1]
	v_pk_mul_f32 v[10:11], v[154:155], v[30:31] op_sel_hi:[0,1]
	v_add_co_u32_e32 v12, vcc, s25, v38
	s_waitcnt lgkmcnt(1)
	v_pk_fma_f32 v[0:1], v[8:9], v[0:1], v[146:147]
	v_pk_fma_f32 v[2:3], v[10:11], v[2:3], v[62:63]
	v_addc_co_u32_e32 v13, vcc, 0, v39, vcc
	global_store_dwordx4 v[12:13], v[0:3], off nt
	ds_read_b128 v[8:11], v16 offset:14336
	s_nop 0
	v_pk_mul_f32 v[0:1], v[154:155], v[150:151] op_sel_hi:[0,1]
	v_pk_mul_f32 v[2:3], v[154:155], v[28:29] op_sel_hi:[0,1]
	s_waitcnt lgkmcnt(1)
	v_pk_fma_f32 v[0:1], v[0:1], v[4:5], v[84:85]
	v_pk_fma_f32 v[2:3], v[2:3], v[6:7], v[152:153]
	global_store_dwordx4 v[12:13], v[0:3], off offset:1024 nt
	ds_read_b128 v[0:3], v16 offset:15360
	v_pk_mul_f32 v[4:5], v[154:155], v[26:27] op_sel_hi:[0,1]
	v_pk_mul_f32 v[6:7], v[154:155], v[24:25] op_sel_hi:[0,1]
	s_waitcnt lgkmcnt(1)
	v_pk_fma_f32 v[4:5], v[4:5], v[8:9], v[60:61]
	v_pk_fma_f32 v[6:7], v[6:7], v[10:11], v[58:59]
	global_store_dwordx4 v[12:13], v[4:7], off offset:2048 nt
	s_nop 1
	v_pk_mul_f32 v[4:5], v[154:155], v[72:73] op_sel_hi:[0,1]
	s_waitcnt lgkmcnt(0)
	v_pk_fma_f32 v[0:1], v[4:5], v[0:1], v[82:83]
	v_pk_mul_f32 v[4:5], v[154:155], v[68:69] op_sel_hi:[0,1]
	v_pk_fma_f32 v[2:3], v[4:5], v[2:3], v[56:57]
	global_store_dwordx4 v[12:13], v[0:3], off offset:3072 nt
	s_mov_b64 s[2:3], -1
	s_and_b64 vcc, exec, s[6:7]
	s_cbranch_vccz .LBB0_1676
	s_andn2_b64 vcc, exec, s[10:11]
	s_mov_b32 s13, s21
	s_cbranch_vccnz .LBB0_1675
	v_readfirstlane_b32 s2, v166
	s_lshl_b32 s2, s2, 3
	s_add_i32 s13, s20, s2
